# PEER down2/up: mid-item L2 prefetch (one dummy dword per lane) of the next item's per-wave list lines
# speedup vs baseline: 1.0017x; 1.0017x over previous
; DI void peer_down2_phase(const Params& p, unsigned char* smem, int layer, const bf16* __restrict__ x1b, u32* ctr) {
;     ...
;   for (int si = 0; si < (stat ? 1 : 8); ++si) {
;     const int slice = stat ? xi : ((xcc + si) & 7);
;     for (;;) {
;       int item;
;       if (stat) { item = it_next; it_next += it_step; }
;       else {
;         __syncthreads();
;         if (tid == 0) *slot = (int)atomicAdd(ctr + slice, 1u);
;         __syncthreads();
;         item = *slot;
;       }
;       if (item >= 256) break;
;       const int t0 = item * 64 + 16 * w;
;       const unsigned char* wbase = wd + slice * 128 + c * 16;
;       {
;         const int* src = ex + (size_t)t0 * 128;
; #pragma unroll
;         for (int i = 0; i < 32; ++i) pl[i * 64 + lane] = src[i * 64 + lane];
;       }
;       const bf16* xb0 = x1b + (size_t)t0 * 1024 + slice * 128 + c * 16;
;       float* pbase = pa + ((size_t)slice * T_TOK + t0) * 128;
;       u32x4 WA[16], WB[16];
;       u32x4 xa0, xa1, xb_0, xb_1;
;       dn2_issue(WA, pl, wbase, grp);
;       xa0 = *(const u32x4*)(xb0); xa1 = *(const u32x4*)(xb0 + 8);
;       for (int tl = 0; tl < 16; tl += 2) {
;         dn2_issue(WB, pl + (tl + 1) * 128, wbase, grp);
;         xb_0 = *(const u32x4*)(xb0 + (size_t)(tl + 1) * 1024); xb_1 = *(const u32x4*)(xb0 + (size_t)(tl + 1) * 1024 + 8);
.LBB0_691:
	v_cmp_lt_i32_e32 vcc, s51, v2
	s_mov_b64 s[28:29], -1
	s_cbranch_vccnz .LBB0_682
	v_lshl_add_u32 v2, v2, 6, v226
	v_ashrrev_i32_e32 v3, 31, v2
	v_lshlrev_b64 v[74:75], 9, v[2:3]
	v_lshl_add_u64 v[4:5], s[18:19], 0, v[74:75]
	s_mov_b32 s100, 0x200000
	s_mov_b32 s101, 0
	v_lshl_add_u64 v[252:253], v[4:5], 0, s[100:101]
	v_mov_b32_e32 v248, v161
	v_mov_b32_e32 v249, 0
	v_lshl_add_u64 v[252:253], v[248:249], 7, v[252:253]
	v_lshl_add_u64 v[6:7], v[4:5], 0, v[146:147]
	global_load_dword v36, v[6:7], off
	global_load_dword v37, v[6:7], off offset:256
	v_mov_b32_e32 v157, v147
	v_mov_b32_e32 v159, v147
	v_mov_b32_e32 v163, v147
	v_mov_b32_e32 v165, v147
	v_mov_b32_e32 v167, v147
	v_mov_b32_e32 v169, v147
	v_mov_b32_e32 v171, v147
	v_mov_b32_e32 v173, v147
	v_mov_b32_e32 v175, v147
	v_mov_b32_e32 v177, v147
	v_mov_b32_e32 v179, v147
	v_mov_b32_e32 v181, v147
	v_mov_b32_e32 v183, v147
	v_mov_b32_e32 v185, v147
	v_mov_b32_e32 v187, v147
	v_mov_b32_e32 v189, v147
	v_lshlrev_b64 v[76:77], 11, v[2:3]
	v_lshl_add_u64 v[2:3], v[4:5], 0, v[156:157]
	v_lshl_add_u64 v[8:9], v[4:5], 0, v[158:159]
	v_lshl_add_u64 v[10:11], v[4:5], 0, v[162:163]
	v_lshl_add_u64 v[12:13], v[4:5], 0, v[164:165]
	v_lshl_add_u64 v[14:15], v[4:5], 0, v[166:167]
	v_lshl_add_u64 v[16:17], v[4:5], 0, v[168:169]
	v_lshl_add_u64 v[18:19], v[4:5], 0, v[170:171]
	v_lshl_add_u64 v[20:21], v[4:5], 0, v[172:173]
	global_load_dword v78, v[6:7], off offset:512
	global_load_dword v79, v[6:7], off offset:768
	global_load_dword v80, v[6:7], off offset:1024
	global_load_dword v81, v[6:7], off offset:1280
	global_load_dword v82, v[6:7], off offset:1536
	global_load_dword v83, v[6:7], off offset:1792
	global_load_dword v84, v[6:7], off offset:2048
	global_load_dword v85, v[6:7], off offset:2304
	global_load_dword v86, v[6:7], off offset:2560
	global_load_dword v87, v[6:7], off offset:2816
	global_load_dword v88, v[6:7], off offset:3072
	global_load_dword v89, v[6:7], off offset:3328
	global_load_dword v90, v[6:7], off offset:3584
	global_load_dword v91, v[6:7], off offset:3840
	global_load_dword v92, v[2:3], off
	global_load_dword v93, v[8:9], off
	global_load_dword v94, v[10:11], off
	global_load_dword v95, v[12:13], off
	global_load_dword v96, v[14:15], off
	global_load_dword v97, v[16:17], off
	global_load_dword v98, v[18:19], off
	global_load_dword v99, v[20:21], off
	v_lshl_add_u64 v[22:23], v[4:5], 0, v[174:175]
	v_lshl_add_u64 v[24:25], v[4:5], 0, v[176:177]
	v_lshl_add_u64 v[26:27], v[4:5], 0, v[178:179]
	v_lshl_add_u64 v[28:29], v[4:5], 0, v[180:181]
	v_lshl_add_u64 v[30:31], v[4:5], 0, v[182:183]
	v_lshl_add_u64 v[32:33], v[4:5], 0, v[184:185]
	v_lshl_add_u64 v[34:35], v[4:5], 0, v[186:187]
	v_lshl_add_u64 v[4:5], v[4:5], 0, v[188:189]
	s_waitcnt vmcnt(26)
	v_lshl_add_u64 v[70:71], v[192:193], 0, v[76:77]
	v_cmp_lt_i32_e32 vcc, v221, v218
	s_mov_b32 s46, 0
	v_lshl_add_u64 v[198:199], v[194:195], 0, v[76:77]
	v_lshl_add_u64 v[200:201], v[196:197], 0, v[74:75]
	v_mov_b32_e32 v165, v229
	s_waitcnt vmcnt(22)
	ds_write2st64_b32 v228, v36, v37 offset0:1 offset1:2
	ds_read2_b32 v[2:3], v227 offset0:64 offset1:72
	global_load_dword v100, v[22:23], off
	global_load_dword v101, v[24:25], off
	global_load_dword v102, v[26:27], off
	global_load_dword v103, v[28:29], off
	global_load_dword v104, v[30:31], off
	global_load_dword v105, v[32:33], off
	global_load_dword v106, v[34:35], off
	global_load_dword v107, v[4:5], off
	ds_read2_b32 v[4:5], v227 offset0:80 offset1:88
	ds_read2_b32 v[18:19], v227 offset0:96 offset1:104
	s_waitcnt lgkmcnt(2)
	v_ashrrev_i32_e32 v7, 31, v2
	v_mov_b32_e32 v6, v2
	v_ashrrev_i32_e32 v9, 31, v3
	v_mov_b32_e32 v8, v3
	s_waitcnt lgkmcnt(1)
	v_ashrrev_i32_e32 v3, 31, v4
	v_mov_b32_e32 v2, v4
	v_ashrrev_i32_e32 v11, 31, v5
	v_mov_b32_e32 v10, v5
	v_lshlrev_b64 v[4:5], 10, v[6:7]
	v_lshlrev_b64 v[6:7], 10, v[8:9]
	v_lshlrev_b64 v[2:3], 10, v[2:3]
	v_lshlrev_b64 v[8:9], 10, v[10:11]
	v_lshl_add_u64 v[4:5], v[190:191], 0, v[4:5]
	v_lshl_add_u64 v[6:7], v[190:191], 0, v[6:7]
	v_lshl_add_u64 v[10:11], v[190:191], 0, v[2:3]
	v_lshl_add_u64 v[14:15], v[190:191], 0, v[8:9]
	global_load_dwordx4 v[2:5], v[4:5], off
	s_nop 0
	global_load_dwordx4 v[6:9], v[6:7], off
	s_nop 0
	global_load_dwordx4 v[10:13], v[10:11], off
	s_nop 0
	global_load_dwordx4 v[14:17], v[14:15], off
	ds_read2_b32 v[26:27], v227 offset0:112 offset1:120
	s_waitcnt lgkmcnt(1)
	v_ashrrev_i32_e32 v21, 31, v18
	v_mov_b32_e32 v20, v18
	v_ashrrev_i32_e32 v23, 31, v19
	v_mov_b32_e32 v22, v19
	s_waitcnt lgkmcnt(0)
	v_ashrrev_i32_e32 v29, 31, v26
	v_mov_b32_e32 v28, v26
	v_ashrrev_i32_e32 v31, 31, v27
	v_mov_b32_e32 v30, v27
	v_lshlrev_b64 v[20:21], 10, v[20:21]
	v_lshlrev_b64 v[18:19], 10, v[22:23]
	v_lshlrev_b64 v[28:29], 10, v[28:29]
	v_lshlrev_b64 v[26:27], 10, v[30:31]
	v_lshl_add_u64 v[20:21], v[190:191], 0, v[20:21]
	v_lshl_add_u64 v[22:23], v[190:191], 0, v[18:19]
	v_lshl_add_u64 v[28:29], v[190:191], 0, v[28:29]
	v_lshl_add_u64 v[30:31], v[190:191], 0, v[26:27]
	global_load_dwordx4 v[18:21], v[20:21], off
	s_nop 0
	global_load_dwordx4 v[22:25], v[22:23], off
	ds_read2_b32 v[34:35], v227 offset0:128 offset1:136
	global_load_dwordx4 v[26:29], v[28:29], off
	s_nop 0
	global_load_dwordx4 v[30:33], v[30:31], off
	ds_read2_b32 v[42:43], v227 offset0:144 offset1:152
	s_waitcnt lgkmcnt(1)
	v_ashrrev_i32_e32 v37, 31, v34
	v_mov_b32_e32 v36, v34
	v_ashrrev_i32_e32 v39, 31, v35
	v_mov_b32_e32 v38, v35
	s_waitcnt lgkmcnt(0)
; DI float bflo(u32 u) { return __uint_as_float(u << 16); }
; DI float bfhi(u32 u) { return __uint_as_float(u & 0xffff0000u); }
; DI void dn2_math(const u32x4 (&W)[16], u32x4 x0, u32x4 x1, float* __restrict__ parow, int lane) {
;   f2 xf[8];
; #pragma unroll
;   for (int q = 0; q < 4; ++q) { xf[q] = f2{bflo(x0[q]), bfhi(x0[q])}; xf[4 + q] = f2{bflo(x1[q]), bfhi(x1[q])}; }
;   float pv[16];
; #pragma unroll
;   for (int j = 0; j < 16; ++j) {
;     f2 s2 = {0.f, 0.f};
; #pragma unroll
;     for (int d = 0; d < 4; ++d) {
;       f2 lo = __builtin_amdgcn_cvt_pk_f32_fp8((int)W[j][d], false);
;       f2 hi = __builtin_amdgcn_cvt_pk_f32_fp8((int)W[j][d], true);
;       s2 = lo * xf[2 * d] + s2;
;       s2 = hi * xf[2 * d + 1] + s2;
;     }
;     pv[j] = s2.x + s2.y;
;   }
; DI void peer_down2_phase(const Params& p, unsigned char* smem, int layer, const bf16* __restrict__ x1b, u32* ctr) {
;     ...
;       {
;         const int* src = ex + (size_t)t0 * 128;
; #pragma unroll
;         for (int i = 0; i < 32; ++i) pl[i * 64 + lane] = src[i * 64 + lane];
;       }
;       const bf16* xb0 = x1b + (size_t)t0 * 1024 + slice * 128 + c * 16;
;       float* pbase = pa + ((size_t)slice * T_TOK + t0) * 128;
;       u32x4 WA[16], WB[16];
;       u32x4 xa0, xa1, xb_0, xb_1;
;       dn2_issue(WA, pl, wbase, grp);
;       xa0 = *(const u32x4*)(xb0); xa1 = *(const u32x4*)(xb0 + 8);
;       for (int tl = 0; tl < 16; tl += 2) {
;         dn2_issue(WB, pl + (tl + 1) * 128, wbase, grp);
;         xb_0 = *(const u32x4*)(xb0 + (size_t)(tl + 1) * 1024); xb_1 = *(const u32x4*)(xb0 + (size_t)(tl + 1) * 1024 + 8);
;         __builtin_amdgcn_sched_barrier(0);
;         dn2_math(WA, xa0, xa1, pbase + (size_t)tl * 128, lane);
;         __builtin_amdgcn_sched_barrier(0);
;         if (tl + 2 < 16) {
;           dn2_issue(WA, pl + (tl + 2) * 128, wbase, grp);
;           xa0 = *(const u32x4*)(xb0 + (size_t)(tl + 2) * 1024); xa1 = *(const u32x4*)(xb0 + (size_t)(tl + 2) * 1024 + 8);
;         }
;         __builtin_amdgcn_sched_barrier(0);
;         dn2_math(WB, xb_0, xb_1, pbase + (size_t)(tl + 1) * 128, lane);
	v_ashrrev_i32_e32 v45, 31, v42
	v_mov_b32_e32 v44, v42
	v_ashrrev_i32_e32 v47, 31, v43
	v_mov_b32_e32 v46, v43
	v_lshlrev_b64 v[36:37], 10, v[36:37]
	v_lshlrev_b64 v[34:35], 10, v[38:39]
	v_lshlrev_b64 v[44:45], 10, v[44:45]
	v_lshlrev_b64 v[42:43], 10, v[46:47]
	v_lshl_add_u64 v[36:37], v[190:191], 0, v[36:37]
	v_lshl_add_u64 v[38:39], v[190:191], 0, v[34:35]
	v_lshl_add_u64 v[44:45], v[190:191], 0, v[44:45]
	v_lshl_add_u64 v[46:47], v[190:191], 0, v[42:43]
	global_load_dwordx4 v[34:37], v[36:37], off
	s_nop 0
	global_load_dwordx4 v[38:41], v[38:39], off
	ds_read2_b32 v[50:51], v227 offset0:160 offset1:168
	global_load_dwordx4 v[42:45], v[44:45], off
	s_nop 0
	global_load_dwordx4 v[46:49], v[46:47], off
	ds_read2_b32 v[58:59], v227 offset0:176 offset1:184
	s_waitcnt lgkmcnt(1)
	v_ashrrev_i32_e32 v53, 31, v50
	v_mov_b32_e32 v52, v50
	v_ashrrev_i32_e32 v55, 31, v51
	v_mov_b32_e32 v54, v51
	s_waitcnt lgkmcnt(0)
	v_ashrrev_i32_e32 v61, 31, v58
	v_mov_b32_e32 v60, v58
	v_ashrrev_i32_e32 v63, 31, v59
	v_mov_b32_e32 v62, v59
	v_lshlrev_b64 v[52:53], 10, v[52:53]
	v_lshlrev_b64 v[50:51], 10, v[54:55]
	v_lshlrev_b64 v[60:61], 10, v[60:61]
	v_lshlrev_b64 v[58:59], 10, v[62:63]
	v_lshl_add_u64 v[52:53], v[190:191], 0, v[52:53]
	v_lshl_add_u64 v[54:55], v[190:191], 0, v[50:51]
	v_lshl_add_u64 v[60:61], v[190:191], 0, v[60:61]
	v_lshl_add_u64 v[62:63], v[190:191], 0, v[58:59]
	global_load_dwordx4 v[50:53], v[52:53], off
	s_nop 0
	global_load_dwordx4 v[54:57], v[54:55], off
	s_nop 0
	global_load_dwordx4 v[58:61], v[60:61], off
	s_nop 0
	global_load_dwordx4 v[62:65], v[62:63], off
	s_nop 0
	global_load_dwordx4 v[66:69], v[70:71], off offset:16
	s_nop 0
	global_load_dwordx4 v[70:73], v[70:71], off
	s_waitcnt vmcnt(46)
	ds_write2st64_b32 v228, v78, v79 offset0:3 offset1:4
	s_waitcnt vmcnt(44)
	ds_write2st64_b32 v228, v80, v81 offset0:5 offset1:6
	s_waitcnt vmcnt(42)
	ds_write2st64_b32 v228, v82, v83 offset0:7 offset1:8
	s_waitcnt vmcnt(40)
	ds_write2st64_b32 v228, v84, v85 offset0:9 offset1:10
	s_waitcnt vmcnt(38)
	ds_write2st64_b32 v228, v86, v87 offset0:11 offset1:12
	s_waitcnt vmcnt(36)
	ds_write2st64_b32 v228, v88, v89 offset0:13 offset1:14
	s_waitcnt vmcnt(34)
	ds_write2st64_b32 v228, v90, v91 offset0:15 offset1:16
	s_waitcnt vmcnt(32)
	ds_write2st64_b32 v228, v92, v93 offset0:17 offset1:18
	s_waitcnt vmcnt(30)
	ds_write2st64_b32 v228, v94, v95 offset0:19 offset1:20
	s_waitcnt vmcnt(28)
	ds_write2st64_b32 v228, v96, v97 offset0:21 offset1:22
	s_waitcnt vmcnt(26)
	ds_write2st64_b32 v228, v98, v99 offset0:23 offset1:24
	s_waitcnt vmcnt(24)
	ds_write2st64_b32 v228, v100, v101 offset0:25 offset1:26
	s_waitcnt vmcnt(22)
	ds_write2st64_b32 v228, v102, v103 offset0:27 offset1:28
	s_waitcnt vmcnt(20)
	ds_write2st64_b32 v228, v104, v105 offset0:29 offset1:30
	s_waitcnt vmcnt(18)
	ds_write2st64_b32 v228, v106, v107 offset0:31 offset1:32
	v_cndmask_b32_e32 v78, v161, v221, vcc
	v_cmp_lt_i32_e32 vcc, v220, v218
	v_lshlrev_b32_e32 v157, 2, v78
	s_nop 0
	v_cndmask_b32_e32 v78, v161, v220, vcc
	v_cmp_lt_i32_e32 vcc, v219, v218
	v_lshlrev_b32_e32 v159, 2, v78
	s_nop 0
	v_cndmask_b32_e32 v78, v161, v219, vcc
	v_lshlrev_b32_e32 v163, 2, v78
	s_branch .LBB0_694
.LBB0_693:
	s_add_i32 s46, s46, 2
	s_cmp_lg_u32 s46, 8
	s_cbranch_scc1 .Lmy_lpf_693
	global_load_dword v254, v[252:253], off
.Lmy_lpf_693:
	s_waitcnt vmcnt(19)
	v_cvt_pk_f32_fp8_e32 v[210:211], v134
	v_cvt_pk_f32_fp8_sdwa v[212:213], v134 src0_sel:WORD_1
	v_cvt_pk_f32_fp8_e32 v[214:215], v135
	s_waitcnt vmcnt(2)
	v_lshlrev_b32_e32 v204, 16, v142
	v_and_b32_e32 v205, 0xffff0000, v142
	v_cvt_pk_f32_fp8_sdwa v[134:135], v135 src0_sel:WORD_1
	v_lshlrev_b32_e32 v206, 16, v143
	v_and_b32_e32 v207, 0xffff0000, v143
	v_pk_fma_f32 v[210:211], v[210:211], v[204:205], 0 op_sel_hi:[1,1,0]
	v_lshlrev_b32_e32 v208, 16, v144
	v_and_b32_e32 v209, 0xffff0000, v144
	v_pk_fma_f32 v[210:211], v[212:213], v[206:207], v[210:211]
	v_lshlrev_b32_e32 v144, 16, v145
	v_and_b32_e32 v145, 0xffff0000, v145
	v_pk_fma_f32 v[210:211], v[214:215], v[208:209], v[210:211]
	v_cvt_pk_f32_fp8_sdwa v[212:213], v136 src0_sel:WORD_1
	v_pk_fma_f32 v[134:135], v[134:135], v[144:145], v[210:211]
	v_cvt_pk_f32_fp8_e32 v[210:211], v136
	v_cvt_pk_f32_fp8_e32 v[214:215], v137
	v_lshlrev_b32_e32 v202, 16, v138
	v_and_b32_e32 v203, 0xffff0000, v138
	v_cvt_pk_f32_fp8_sdwa v[136:137], v137 src0_sel:WORD_1
	v_lshlrev_b32_e32 v138, 16, v139
	v_and_b32_e32 v139, 0xffff0000, v139
	v_pk_fma_f32 v[134:135], v[210:211], v[202:203], v[134:135]
	v_lshlrev_b32_e32 v142, 16, v140
	v_and_b32_e32 v143, 0xffff0000, v140
	v_pk_fma_f32 v[134:135], v[212:213], v[138:139], v[134:135]
	v_lshlrev_b32_e32 v140, 16, v141
	v_and_b32_e32 v141, 0xffff0000, v141
	v_pk_fma_f32 v[134:135], v[214:215], v[142:143], v[134:135]
	v_cvt_pk_f32_fp8_e32 v[210:211], v131
	v_pk_fma_f32 v[134:135], v[136:137], v[140:141], v[134:135]
	v_cvt_pk_f32_fp8_sdwa v[136:137], v130 src0_sel:WORD_1
	v_add_f32_e32 v167, v134, v135
	v_cvt_pk_f32_fp8_e32 v[134:135], v130
	v_cvt_pk_f32_fp8_sdwa v[130:131], v131 src0_sel:WORD_1
	v_pk_fma_f32 v[134:135], v[134:135], v[204:205], 0 op_sel_hi:[1,1,0]
	s_nop 0
	v_pk_fma_f32 v[134:135], v[136:137], v[206:207], v[134:135]
	v_cvt_pk_f32_fp8_sdwa v[136:137], v132 src0_sel:WORD_1
	v_pk_fma_f32 v[134:135], v[210:211], v[208:209], v[134:135]
	v_cvt_pk_f32_fp8_e32 v[210:211], v133
	v_pk_fma_f32 v[130:131], v[130:131], v[144:145], v[134:135]
	v_cvt_pk_f32_fp8_e32 v[134:135], v132
	v_cvt_pk_f32_fp8_sdwa v[132:133], v133 src0_sel:WORD_1
	v_pk_fma_f32 v[130:131], v[134:135], v[202:203], v[130:131]
	s_nop 0
	v_pk_fma_f32 v[130:131], v[136:137], v[138:139], v[130:131]
; DI float bflo(u32 u) { return __uint_as_float(u << 16); }
; DI float bfhi(u32 u) { return __uint_as_float(u & 0xffff0000u); }
; DI void dn2_math(const u32x4 (&W)[16], u32x4 x0, u32x4 x1, float* __restrict__ parow, int lane) {
;   f2 xf[8];
; #pragma unroll
;   for (int q = 0; q < 4; ++q) { xf[q] = f2{bflo(x0[q]), bfhi(x0[q])}; xf[4 + q] = f2{bflo(x1[q]), bfhi(x1[q])}; }
;   float pv[16];
; #pragma unroll
;   for (int j = 0; j < 16; ++j) {
;     f2 s2 = {0.f, 0.f};
; #pragma unroll
;     for (int d = 0; d < 4; ++d) {
;       f2 lo = __builtin_amdgcn_cvt_pk_f32_fp8((int)W[j][d], false);
;       f2 hi = __builtin_amdgcn_cvt_pk_f32_fp8((int)W[j][d], true);
;       s2 = lo * xf[2 * d] + s2;
;       s2 = hi * xf[2 * d + 1] + s2;
;     }
;     pv[j] = s2.x + s2.y;
;   }
	v_cvt_pk_f32_fp8_e32 v[134:135], v127
	v_pk_fma_f32 v[130:131], v[210:211], v[142:143], v[130:131]
	s_nop 0
	v_pk_fma_f32 v[130:131], v[132:133], v[140:141], v[130:131]
	v_cvt_pk_f32_fp8_sdwa v[132:133], v126 src0_sel:WORD_1
	v_add_f32_e32 v136, v130, v131
	v_cvt_pk_f32_fp8_e32 v[130:131], v126
	v_cvt_pk_f32_fp8_sdwa v[126:127], v127 src0_sel:WORD_1
	v_pk_fma_f32 v[130:131], v[130:131], v[204:205], 0 op_sel_hi:[1,1,0]
	s_nop 0
	v_pk_fma_f32 v[130:131], v[132:133], v[206:207], v[130:131]
	v_cvt_pk_f32_fp8_sdwa v[132:133], v128 src0_sel:WORD_1
	v_pk_fma_f32 v[130:131], v[134:135], v[208:209], v[130:131]
	v_cvt_pk_f32_fp8_e32 v[134:135], v129
	v_pk_fma_f32 v[126:127], v[126:127], v[144:145], v[130:131]
	v_cvt_pk_f32_fp8_e32 v[130:131], v128
	v_cvt_pk_f32_fp8_sdwa v[128:129], v129 src0_sel:WORD_1
	v_pk_fma_f32 v[126:127], v[130:131], v[202:203], v[126:127]
	s_nop 0
	v_pk_fma_f32 v[126:127], v[132:133], v[138:139], v[126:127]
	v_cvt_pk_f32_fp8_e32 v[130:131], v123
	v_pk_fma_f32 v[126:127], v[134:135], v[142:143], v[126:127]
	s_nop 0
	v_pk_fma_f32 v[126:127], v[128:129], v[140:141], v[126:127]
	v_cvt_pk_f32_fp8_sdwa v[128:129], v122 src0_sel:WORD_1
	v_add_f32_e32 v132, v126, v127
	v_cvt_pk_f32_fp8_e32 v[126:127], v122
	v_cvt_pk_f32_fp8_sdwa v[122:123], v123 src0_sel:WORD_1
	v_pk_fma_f32 v[126:127], v[126:127], v[204:205], 0 op_sel_hi:[1,1,0]
	s_nop 0
	v_pk_fma_f32 v[126:127], v[128:129], v[206:207], v[126:127]
	v_cvt_pk_f32_fp8_sdwa v[128:129], v124 src0_sel:WORD_1
	v_pk_fma_f32 v[126:127], v[130:131], v[208:209], v[126:127]
	v_cvt_pk_f32_fp8_e32 v[130:131], v125
	v_pk_fma_f32 v[122:123], v[122:123], v[144:145], v[126:127]
	v_cvt_pk_f32_fp8_e32 v[126:127], v124
	v_cvt_pk_f32_fp8_sdwa v[124:125], v125 src0_sel:WORD_1
	v_pk_fma_f32 v[122:123], v[126:127], v[202:203], v[122:123]
	s_nop 0
	v_pk_fma_f32 v[122:123], v[128:129], v[138:139], v[122:123]
	v_cvt_pk_f32_fp8_e32 v[126:127], v119
	v_pk_fma_f32 v[122:123], v[130:131], v[142:143], v[122:123]
	s_nop 0
	v_pk_fma_f32 v[122:123], v[124:125], v[140:141], v[122:123]
	v_cvt_pk_f32_fp8_sdwa v[124:125], v118 src0_sel:WORD_1
	v_add_f32_e32 v128, v122, v123
	v_cvt_pk_f32_fp8_e32 v[122:123], v118
	v_cvt_pk_f32_fp8_sdwa v[118:119], v119 src0_sel:WORD_1
	v_pk_fma_f32 v[122:123], v[122:123], v[204:205], 0 op_sel_hi:[1,1,0]
	s_nop 0
	v_pk_fma_f32 v[122:123], v[124:125], v[206:207], v[122:123]
	v_cvt_pk_f32_fp8_sdwa v[124:125], v120 src0_sel:WORD_1
	v_pk_fma_f32 v[122:123], v[126:127], v[208:209], v[122:123]
	v_cvt_pk_f32_fp8_e32 v[126:127], v121
	v_pk_fma_f32 v[118:119], v[118:119], v[144:145], v[122:123]
	v_cvt_pk_f32_fp8_e32 v[122:123], v120
	v_cvt_pk_f32_fp8_sdwa v[120:121], v121 src0_sel:WORD_1
	v_pk_fma_f32 v[118:119], v[122:123], v[202:203], v[118:119]
	s_nop 0
	v_pk_fma_f32 v[118:119], v[124:125], v[138:139], v[118:119]
	v_cvt_pk_f32_fp8_e32 v[122:123], v115
	v_pk_fma_f32 v[118:119], v[126:127], v[142:143], v[118:119]
	s_nop 0
	v_pk_fma_f32 v[118:119], v[120:121], v[140:141], v[118:119]
	v_cvt_pk_f32_fp8_sdwa v[120:121], v114 src0_sel:WORD_1
	v_add_f32_e32 v124, v118, v119
	v_cvt_pk_f32_fp8_e32 v[118:119], v114
	v_cvt_pk_f32_fp8_sdwa v[114:115], v115 src0_sel:WORD_1
	v_pk_fma_f32 v[118:119], v[118:119], v[204:205], 0 op_sel_hi:[1,1,0]
	s_nop 0
	v_pk_fma_f32 v[118:119], v[120:121], v[206:207], v[118:119]
	v_cvt_pk_f32_fp8_sdwa v[120:121], v116 src0_sel:WORD_1
	v_pk_fma_f32 v[118:119], v[122:123], v[208:209], v[118:119]
	v_cvt_pk_f32_fp8_e32 v[122:123], v117
	v_pk_fma_f32 v[114:115], v[114:115], v[144:145], v[118:119]
	v_cvt_pk_f32_fp8_e32 v[118:119], v116
	v_cvt_pk_f32_fp8_sdwa v[116:117], v117 src0_sel:WORD_1
	v_pk_fma_f32 v[114:115], v[118:119], v[202:203], v[114:115]
	s_nop 0
	v_pk_fma_f32 v[114:115], v[120:121], v[138:139], v[114:115]
	v_cvt_pk_f32_fp8_e32 v[118:119], v111
	v_pk_fma_f32 v[114:115], v[122:123], v[142:143], v[114:115]
	s_nop 0
	v_pk_fma_f32 v[114:115], v[116:117], v[140:141], v[114:115]
	v_cvt_pk_f32_fp8_sdwa v[116:117], v110 src0_sel:WORD_1
	v_add_f32_e32 v120, v114, v115
	v_cvt_pk_f32_fp8_e32 v[114:115], v110
	v_cvt_pk_f32_fp8_sdwa v[110:111], v111 src0_sel:WORD_1
	v_pk_fma_f32 v[114:115], v[114:115], v[204:205], 0 op_sel_hi:[1,1,0]
	s_nop 0
	v_pk_fma_f32 v[114:115], v[116:117], v[206:207], v[114:115]
	v_cvt_pk_f32_fp8_sdwa v[116:117], v112 src0_sel:WORD_1
	v_pk_fma_f32 v[114:115], v[118:119], v[208:209], v[114:115]
	v_cvt_pk_f32_fp8_e32 v[118:119], v113
	v_pk_fma_f32 v[110:111], v[110:111], v[144:145], v[114:115]
	v_cvt_pk_f32_fp8_e32 v[114:115], v112
	v_cvt_pk_f32_fp8_sdwa v[112:113], v113 src0_sel:WORD_1
	v_pk_fma_f32 v[110:111], v[114:115], v[202:203], v[110:111]
	s_nop 0
	v_pk_fma_f32 v[110:111], v[116:117], v[138:139], v[110:111]
	v_cvt_pk_f32_fp8_e32 v[114:115], v107
	v_pk_fma_f32 v[110:111], v[118:119], v[142:143], v[110:111]
	s_nop 0
	v_pk_fma_f32 v[110:111], v[112:113], v[140:141], v[110:111]
	v_cvt_pk_f32_fp8_sdwa v[112:113], v106 src0_sel:WORD_1
	v_add_f32_e32 v116, v110, v111
	v_cvt_pk_f32_fp8_e32 v[110:111], v106
	v_cvt_pk_f32_fp8_sdwa v[106:107], v107 src0_sel:WORD_1
	v_pk_fma_f32 v[110:111], v[110:111], v[204:205], 0 op_sel_hi:[1,1,0]
	s_nop 0
	v_pk_fma_f32 v[110:111], v[112:113], v[206:207], v[110:111]
	v_cvt_pk_f32_fp8_sdwa v[112:113], v108 src0_sel:WORD_1
	v_pk_fma_f32 v[110:111], v[114:115], v[208:209], v[110:111]
	v_cvt_pk_f32_fp8_e32 v[114:115], v109
	v_pk_fma_f32 v[106:107], v[106:107], v[144:145], v[110:111]
	v_cvt_pk_f32_fp8_e32 v[110:111], v108
	v_cvt_pk_f32_fp8_sdwa v[108:109], v109 src0_sel:WORD_1
	v_pk_fma_f32 v[106:107], v[110:111], v[202:203], v[106:107]
	s_nop 0
	v_pk_fma_f32 v[106:107], v[112:113], v[138:139], v[106:107]
	v_cvt_pk_f32_fp8_e32 v[110:111], v103
; DI float bflo(u32 u) { return __uint_as_float(u << 16); }
; DI float bfhi(u32 u) { return __uint_as_float(u & 0xffff0000u); }
; DI void dn2_math(const u32x4 (&W)[16], u32x4 x0, u32x4 x1, float* __restrict__ parow, int lane) {
;   f2 xf[8];
; #pragma unroll
;   for (int q = 0; q < 4; ++q) { xf[q] = f2{bflo(x0[q]), bfhi(x0[q])}; xf[4 + q] = f2{bflo(x1[q]), bfhi(x1[q])}; }
;   float pv[16];
; #pragma unroll
;   for (int j = 0; j < 16; ++j) {
;     f2 s2 = {0.f, 0.f};
; #pragma unroll
;     for (int d = 0; d < 4; ++d) {
;       f2 lo = __builtin_amdgcn_cvt_pk_f32_fp8((int)W[j][d], false);
;       f2 hi = __builtin_amdgcn_cvt_pk_f32_fp8((int)W[j][d], true);
;       s2 = lo * xf[2 * d] + s2;
;       s2 = hi * xf[2 * d + 1] + s2;
;     }
;     pv[j] = s2.x + s2.y;
;   }
	v_pk_fma_f32 v[106:107], v[114:115], v[142:143], v[106:107]
	s_nop 0
	v_pk_fma_f32 v[106:107], v[108:109], v[140:141], v[106:107]
	v_cvt_pk_f32_fp8_sdwa v[108:109], v102 src0_sel:WORD_1
	v_add_f32_e32 v112, v106, v107
	v_cvt_pk_f32_fp8_e32 v[106:107], v102
	v_cvt_pk_f32_fp8_sdwa v[102:103], v103 src0_sel:WORD_1
	v_pk_fma_f32 v[106:107], v[106:107], v[204:205], 0 op_sel_hi:[1,1,0]
	s_nop 0
	v_pk_fma_f32 v[106:107], v[108:109], v[206:207], v[106:107]
	v_cvt_pk_f32_fp8_sdwa v[108:109], v104 src0_sel:WORD_1
	v_pk_fma_f32 v[106:107], v[110:111], v[208:209], v[106:107]
	v_cvt_pk_f32_fp8_e32 v[110:111], v105
	v_pk_fma_f32 v[102:103], v[102:103], v[144:145], v[106:107]
	v_cvt_pk_f32_fp8_e32 v[106:107], v104
	v_cvt_pk_f32_fp8_sdwa v[104:105], v105 src0_sel:WORD_1
	v_pk_fma_f32 v[102:103], v[106:107], v[202:203], v[102:103]
	s_nop 0
	v_pk_fma_f32 v[102:103], v[108:109], v[138:139], v[102:103]
	v_cvt_pk_f32_fp8_e32 v[106:107], v99
	v_pk_fma_f32 v[102:103], v[110:111], v[142:143], v[102:103]
	s_nop 0
	v_pk_fma_f32 v[102:103], v[104:105], v[140:141], v[102:103]
	v_cvt_pk_f32_fp8_sdwa v[104:105], v98 src0_sel:WORD_1
	v_add_f32_e32 v108, v102, v103
	v_cvt_pk_f32_fp8_e32 v[102:103], v98
	v_cvt_pk_f32_fp8_sdwa v[98:99], v99 src0_sel:WORD_1
	v_pk_fma_f32 v[102:103], v[102:103], v[204:205], 0 op_sel_hi:[1,1,0]
	s_nop 0
	v_pk_fma_f32 v[102:103], v[104:105], v[206:207], v[102:103]
	v_cvt_pk_f32_fp8_sdwa v[104:105], v100 src0_sel:WORD_1
	v_pk_fma_f32 v[102:103], v[106:107], v[208:209], v[102:103]
	v_cvt_pk_f32_fp8_e32 v[106:107], v101
	v_pk_fma_f32 v[98:99], v[98:99], v[144:145], v[102:103]
	v_cvt_pk_f32_fp8_e32 v[102:103], v100
	v_cvt_pk_f32_fp8_sdwa v[100:101], v101 src0_sel:WORD_1
	v_pk_fma_f32 v[98:99], v[102:103], v[202:203], v[98:99]
	s_nop 0
	v_pk_fma_f32 v[98:99], v[104:105], v[138:139], v[98:99]
	v_cvt_pk_f32_fp8_e32 v[102:103], v95
	v_pk_fma_f32 v[98:99], v[106:107], v[142:143], v[98:99]
	s_nop 0
	v_pk_fma_f32 v[98:99], v[100:101], v[140:141], v[98:99]
	v_cvt_pk_f32_fp8_sdwa v[100:101], v94 src0_sel:WORD_1
	v_add_f32_e32 v104, v98, v99
	v_cvt_pk_f32_fp8_e32 v[98:99], v94
	v_cvt_pk_f32_fp8_sdwa v[94:95], v95 src0_sel:WORD_1
	v_pk_fma_f32 v[98:99], v[98:99], v[204:205], 0 op_sel_hi:[1,1,0]
	s_nop 0
	v_pk_fma_f32 v[98:99], v[100:101], v[206:207], v[98:99]
	v_cvt_pk_f32_fp8_sdwa v[100:101], v96 src0_sel:WORD_1
	v_pk_fma_f32 v[98:99], v[102:103], v[208:209], v[98:99]
	v_cvt_pk_f32_fp8_e32 v[102:103], v97
	v_pk_fma_f32 v[94:95], v[94:95], v[144:145], v[98:99]
	v_cvt_pk_f32_fp8_e32 v[98:99], v96
	v_cvt_pk_f32_fp8_sdwa v[96:97], v97 src0_sel:WORD_1
	v_pk_fma_f32 v[94:95], v[98:99], v[202:203], v[94:95]
	s_nop 0
	v_pk_fma_f32 v[94:95], v[100:101], v[138:139], v[94:95]
	v_cvt_pk_f32_fp8_e32 v[98:99], v91
	v_pk_fma_f32 v[94:95], v[102:103], v[142:143], v[94:95]
	s_nop 0
	v_pk_fma_f32 v[94:95], v[96:97], v[140:141], v[94:95]
	v_cvt_pk_f32_fp8_sdwa v[96:97], v90 src0_sel:WORD_1
	v_add_f32_e32 v100, v94, v95
	v_cvt_pk_f32_fp8_e32 v[94:95], v90
	v_cvt_pk_f32_fp8_sdwa v[90:91], v91 src0_sel:WORD_1
	v_pk_fma_f32 v[94:95], v[94:95], v[204:205], 0 op_sel_hi:[1,1,0]
	s_nop 0
	v_pk_fma_f32 v[94:95], v[96:97], v[206:207], v[94:95]
	v_cvt_pk_f32_fp8_sdwa v[96:97], v92 src0_sel:WORD_1
	v_pk_fma_f32 v[94:95], v[98:99], v[208:209], v[94:95]
	v_cvt_pk_f32_fp8_e32 v[98:99], v93
	v_pk_fma_f32 v[90:91], v[90:91], v[144:145], v[94:95]
	v_cvt_pk_f32_fp8_e32 v[94:95], v92
	v_cvt_pk_f32_fp8_sdwa v[92:93], v93 src0_sel:WORD_1
	v_pk_fma_f32 v[90:91], v[94:95], v[202:203], v[90:91]
	s_nop 0
	v_pk_fma_f32 v[90:91], v[96:97], v[138:139], v[90:91]
	v_cvt_pk_f32_fp8_e32 v[94:95], v87
	v_pk_fma_f32 v[90:91], v[98:99], v[142:143], v[90:91]
	s_nop 0
	v_pk_fma_f32 v[90:91], v[92:93], v[140:141], v[90:91]
	v_cvt_pk_f32_fp8_sdwa v[92:93], v86 src0_sel:WORD_1
	v_add_f32_e32 v96, v90, v91
	v_cvt_pk_f32_fp8_e32 v[90:91], v86
	v_cvt_pk_f32_fp8_sdwa v[86:87], v87 src0_sel:WORD_1
	v_pk_fma_f32 v[90:91], v[90:91], v[204:205], 0 op_sel_hi:[1,1,0]
	s_nop 0
	v_pk_fma_f32 v[90:91], v[92:93], v[206:207], v[90:91]
	v_cvt_pk_f32_fp8_sdwa v[92:93], v88 src0_sel:WORD_1
	v_pk_fma_f32 v[90:91], v[94:95], v[208:209], v[90:91]
	v_cvt_pk_f32_fp8_e32 v[94:95], v89
	v_pk_fma_f32 v[86:87], v[86:87], v[144:145], v[90:91]
	v_cvt_pk_f32_fp8_e32 v[90:91], v88
	v_cvt_pk_f32_fp8_sdwa v[88:89], v89 src0_sel:WORD_1
	v_pk_fma_f32 v[86:87], v[90:91], v[202:203], v[86:87]
	s_nop 0
	v_pk_fma_f32 v[86:87], v[92:93], v[138:139], v[86:87]
	v_cvt_pk_f32_fp8_e32 v[90:91], v83
	v_pk_fma_f32 v[86:87], v[94:95], v[142:143], v[86:87]
	s_nop 0
	v_pk_fma_f32 v[86:87], v[88:89], v[140:141], v[86:87]
	v_cvt_pk_f32_fp8_sdwa v[88:89], v82 src0_sel:WORD_1
	v_add_f32_e32 v92, v86, v87
	v_cvt_pk_f32_fp8_e32 v[86:87], v82
	v_cvt_pk_f32_fp8_sdwa v[82:83], v83 src0_sel:WORD_1
	v_pk_fma_f32 v[86:87], v[86:87], v[204:205], 0 op_sel_hi:[1,1,0]
	s_nop 0
	v_pk_fma_f32 v[86:87], v[88:89], v[206:207], v[86:87]
; DI float bflo(u32 u) { return __uint_as_float(u << 16); }
; DI float bfhi(u32 u) { return __uint_as_float(u & 0xffff0000u); }
; DI void dn2_math(const u32x4 (&W)[16], u32x4 x0, u32x4 x1, float* __restrict__ parow, int lane) {
;   f2 xf[8];
; #pragma unroll
;   for (int q = 0; q < 4; ++q) { xf[q] = f2{bflo(x0[q]), bfhi(x0[q])}; xf[4 + q] = f2{bflo(x1[q]), bfhi(x1[q])}; }
;   float pv[16];
; #pragma unroll
;   for (int j = 0; j < 16; ++j) {
;     f2 s2 = {0.f, 0.f};
; #pragma unroll
;     for (int d = 0; d < 4; ++d) {
;       f2 lo = __builtin_amdgcn_cvt_pk_f32_fp8((int)W[j][d], false);
;       f2 hi = __builtin_amdgcn_cvt_pk_f32_fp8((int)W[j][d], true);
;       s2 = lo * xf[2 * d] + s2;
;       s2 = hi * xf[2 * d + 1] + s2;
;     }
;     pv[j] = s2.x + s2.y;
;   }
;   const bool b2 = lane & 4, b1 = lane & 2, b0 = lane & 1;
;   float q8[8];
; #pragma unroll
;   for (int i = 0; i < 8; ++i) { float snd = b2 ? pv[i] : pv[i + 8]; float kp = b2 ? pv[i + 8] : pv[i]; q8[i] = kp + __shfl_xor(snd, 4); }
;   float q4[4];
; #pragma unroll
;   for (int i = 0; i < 4; ++i) { float snd = b1 ? q8[i] : q8[i + 4]; float kp = b1 ? q8[i + 4] : q8[i]; q4[i] = kp + __shfl_xor(snd, 2); }
;   float r2[2];
; #pragma unroll
;   for (int i = 0; i < 2; ++i) { float snd = b0 ? q4[i] : q4[i + 2]; float kp = b0 ? q4[i + 2] : q4[i]; r2[i] = kp + __shfl_xor(snd, 1); }
;   const int j0 = (b0 ? 2 : 0) + (b1 ? 4 : 0) + (b2 ? 8 : 0);
;   const int grp = lane >> 3;
;   parow[8 * j0 + grp] = r2[0];
;   parow[8 * (j0 + 1) + grp] = r2[1];
; }
	v_cvt_pk_f32_fp8_sdwa v[88:89], v84 src0_sel:WORD_1
	v_pk_fma_f32 v[86:87], v[90:91], v[208:209], v[86:87]
	v_cvt_pk_f32_fp8_e32 v[90:91], v85
	v_pk_fma_f32 v[82:83], v[82:83], v[144:145], v[86:87]
	v_cvt_pk_f32_fp8_e32 v[86:87], v84
	v_cvt_pk_f32_fp8_sdwa v[84:85], v85 src0_sel:WORD_1
	v_pk_fma_f32 v[82:83], v[86:87], v[202:203], v[82:83]
	s_nop 0
	v_pk_fma_f32 v[82:83], v[88:89], v[138:139], v[82:83]
	v_cvt_pk_f32_fp8_e32 v[86:87], v79
	v_pk_fma_f32 v[82:83], v[90:91], v[142:143], v[82:83]
	s_nop 0
	v_pk_fma_f32 v[82:83], v[84:85], v[140:141], v[82:83]
	v_cvt_pk_f32_fp8_sdwa v[84:85], v78 src0_sel:WORD_1
	v_add_f32_e32 v88, v82, v83
	v_cvt_pk_f32_fp8_e32 v[82:83], v78
	v_cvt_pk_f32_fp8_sdwa v[78:79], v79 src0_sel:WORD_1
	v_pk_fma_f32 v[82:83], v[82:83], v[204:205], 0 op_sel_hi:[1,1,0]
	s_nop 0
	v_pk_fma_f32 v[82:83], v[84:85], v[206:207], v[82:83]
	v_cvt_pk_f32_fp8_sdwa v[84:85], v80 src0_sel:WORD_1
	v_pk_fma_f32 v[82:83], v[86:87], v[208:209], v[82:83]
	v_cvt_pk_f32_fp8_e32 v[86:87], v81
	v_pk_fma_f32 v[78:79], v[78:79], v[144:145], v[82:83]
	v_cvt_pk_f32_fp8_e32 v[82:83], v80
	v_cvt_pk_f32_fp8_sdwa v[80:81], v81 src0_sel:WORD_1
	v_pk_fma_f32 v[78:79], v[82:83], v[202:203], v[78:79]
	s_nop 0
	v_pk_fma_f32 v[78:79], v[84:85], v[138:139], v[78:79]
	v_cvt_pk_f32_fp8_e32 v[82:83], v75
	v_pk_fma_f32 v[78:79], v[86:87], v[142:143], v[78:79]
	s_nop 0
	v_pk_fma_f32 v[78:79], v[80:81], v[140:141], v[78:79]
	v_cvt_pk_f32_fp8_sdwa v[80:81], v74 src0_sel:WORD_1
	v_add_f32_e32 v84, v78, v79
	v_cvt_pk_f32_fp8_e32 v[78:79], v74
	v_cvt_pk_f32_fp8_sdwa v[74:75], v75 src0_sel:WORD_1
	v_pk_fma_f32 v[78:79], v[78:79], v[204:205], 0 op_sel_hi:[1,1,0]
	s_nop 0
	v_pk_fma_f32 v[78:79], v[80:81], v[206:207], v[78:79]
	v_cvt_pk_f32_fp8_sdwa v[80:81], v76 src0_sel:WORD_1
	v_pk_fma_f32 v[78:79], v[82:83], v[208:209], v[78:79]
	v_cvt_pk_f32_fp8_e32 v[82:83], v77
	v_pk_fma_f32 v[74:75], v[74:75], v[144:145], v[78:79]
	v_cvt_pk_f32_fp8_e32 v[78:79], v76
	v_cvt_pk_f32_fp8_sdwa v[76:77], v77 src0_sel:WORD_1
	v_pk_fma_f32 v[74:75], v[78:79], v[202:203], v[74:75]
	s_nop 0
	v_pk_fma_f32 v[74:75], v[80:81], v[138:139], v[74:75]
	v_pk_fma_f32 v[74:75], v[82:83], v[142:143], v[74:75]
	v_pk_fma_f32 v[74:75], v[76:77], v[140:141], v[74:75]
	v_add_f32_e32 v74, v74, v75
	s_nop 1
	v_add_f32_dpp v75, v167, v167 row_shl:4 row_mask:0xf bank_mask:0x5
	v_add_f32_dpp v75, v108, v108 row_shr:4 row_mask:0xf bank_mask:0xa
	v_add_f32_dpp v76, v136, v136 row_shl:4 row_mask:0xf bank_mask:0x5
	v_add_f32_dpp v76, v104, v104 row_shr:4 row_mask:0xf bank_mask:0xa
	v_add_f32_dpp v77, v132, v132 row_shl:4 row_mask:0xf bank_mask:0x5
	v_add_f32_dpp v77, v100, v100 row_shr:4 row_mask:0xf bank_mask:0xa
	v_add_f32_dpp v78, v128, v128 row_shl:4 row_mask:0xf bank_mask:0x5
	v_add_f32_dpp v78, v96, v96 row_shr:4 row_mask:0xf bank_mask:0xa
	v_add_f32_dpp v79, v124, v124 row_shl:4 row_mask:0xf bank_mask:0x5
	v_add_f32_dpp v79, v92, v92 row_shr:4 row_mask:0xf bank_mask:0xa
	v_add_f32_dpp v80, v120, v120 row_shl:4 row_mask:0xf bank_mask:0x5
	v_add_f32_dpp v80, v88, v88 row_shr:4 row_mask:0xf bank_mask:0xa
	v_add_f32_dpp v81, v116, v116 row_shl:4 row_mask:0xf bank_mask:0x5
	v_add_f32_dpp v81, v84, v84 row_shr:4 row_mask:0xf bank_mask:0xa
	v_add_f32_dpp v74, v74, v74 row_shr:4 row_mask:0xf bank_mask:0xa
	v_add_f32_dpp v74, v112, v112 row_shl:4 row_mask:0xf bank_mask:0x5
	s_nop 1
	v_add_f32_dpp v75, v75, v75 quad_perm:[2,3,0,1] row_mask:0xf bank_mask:0xf
	v_add_f32_dpp v79, v79, v79 quad_perm:[2,3,0,1] row_mask:0xf bank_mask:0xf
	v_cndmask_b32_e64 v75, v79, v75, s[12:13]
	v_add_f32_dpp v77, v77, v77 quad_perm:[2,3,0,1] row_mask:0xf bank_mask:0xf
	v_add_f32_dpp v81, v81, v81 quad_perm:[2,3,0,1] row_mask:0xf bank_mask:0xf
	v_cndmask_b32_e64 v77, v81, v77, s[12:13]
	v_add_f32_dpp v76, v76, v76 quad_perm:[2,3,0,1] row_mask:0xf bank_mask:0xf
	v_add_f32_dpp v80, v80, v80 quad_perm:[2,3,0,1] row_mask:0xf bank_mask:0xf
	v_cndmask_b32_e64 v76, v80, v76, s[12:13]
	v_add_f32_dpp v78, v78, v78 quad_perm:[2,3,0,1] row_mask:0xf bank_mask:0xf
	v_add_f32_dpp v74, v74, v74 quad_perm:[2,3,0,1] row_mask:0xf bank_mask:0xf
	v_cndmask_b32_e64 v74, v74, v78, s[12:13]
	s_nop 1
	v_add_f32_dpp v75, v75, v75 quad_perm:[1,0,3,2] row_mask:0xf bank_mask:0xf
	v_add_f32_dpp v77, v77, v77 quad_perm:[1,0,3,2] row_mask:0xf bank_mask:0xf
	v_cndmask_b32_e64 v75, v77, v75, s[14:15]
	v_add_f32_dpp v76, v76, v76 quad_perm:[1,0,3,2] row_mask:0xf bank_mask:0xf
	v_add_f32_dpp v74, v74, v74 quad_perm:[1,0,3,2] row_mask:0xf bank_mask:0xf
	v_cndmask_b32_e64 v74, v74, v76, s[14:15]
	global_store_dword v[200:201], v75, off
	global_store_dword v[200:201], v74, off offset:32
	v_lshl_add_u64 v[198:199], v[198:199], 0, s[40:41]
	v_add_u32_e32 v165, 0x400, v165
	v_lshl_add_u64 v[200:201], v[200:201], 0, s[42:43]
	s_and_b64 vcc, exec, s[28:29]
	s_cbranch_vccnz .LBB0_681

; DI void peer_up_phase(const Params& p, unsigned char* smem, int layer, u32* ctr) {
;     ...
;   for (int si = 0; si < (stat ? 1 : 8); ++si) {
;     const int slice = stat ? xi : ((xcc + si) & 7);
;     for (;;) {
;       int item;
;       if (stat) { item = it_next; it_next += it_step; }
;       else {
;         __syncthreads();
;         if (tid == 0) *slot = (int)atomicAdd(ctr + slice, 1u);
;         __syncthreads();
;         item = *slot;
;       }
;       if (item >= 256) break;
;       const int t0 = item * 64 + 16 * w;
;       const unsigned char* wbase = wu + slice * 128 + c * 16;
;       {
;         const u32* src = hgp + (size_t)t0 * 128;
; #pragma unroll
;         for (int i = 0; i < 32; ++i) pl[i * 64 + lane] = src[i * 64 + lane];
;       }
;       float* ybase = yb + (size_t)t0 * 1024 + slice * 128;
;       u32x4 WA[16], WB[16];
;       u32 pA[16], pB[16];
;       up_issue(WA, pA, pl, wbase, grp);
.LBB0_824:
	v_cmp_lt_i32_e32 vcc, s48, v4
	s_mov_b64 s[28:29], -1
	s_cbranch_vccnz .LBB0_815
	s_waitcnt vmcnt(3)
	v_lshl_add_u32 v68, v4, 6, v3
	v_ashrrev_i32_e32 v69, 31, v68
	v_lshlrev_b64 v[4:5], 9, v[68:69]
	v_lshl_add_u64 v[4:5], s[38:39], 0, v[4:5]
	s_mov_b32 s100, 0x200000
	s_mov_b32 s101, 0
	v_lshl_add_u64 v[252:253], v[4:5], 0, s[100:101]
	v_mov_b32_e32 v248, v161
	v_mov_b32_e32 v249, 0
	v_lshl_add_u64 v[252:253], v[248:249], 7, v[252:253]
	v_mov_b32_e32 v139, v133
	v_lshl_add_u64 v[6:7], v[4:5], 0, v[138:139]
	global_load_dword v38, v[6:7], off
	global_load_dword v39, v[6:7], off offset:256
	v_mov_b32_e32 v141, v133
	v_mov_b32_e32 v143, v133
	v_mov_b32_e32 v145, v133
	v_mov_b32_e32 v147, v133
	v_mov_b32_e32 v149, v133
	v_mov_b32_e32 v151, v133
	v_mov_b32_e32 v153, v133
	v_mov_b32_e32 v155, v133
	v_mov_b32_e32 v157, v133
	v_mov_b32_e32 v159, v133
	v_mov_b32_e32 v163, v133
	v_mov_b32_e32 v165, v133
	v_mov_b32_e32 v167, v133
	v_mov_b32_e32 v169, v133
	v_mov_b32_e32 v171, v133
	v_mov_b32_e32 v173, v133
	v_lshl_add_u64 v[8:9], v[4:5], 0, v[140:141]
	v_lshl_add_u64 v[10:11], v[4:5], 0, v[142:143]
	v_lshl_add_u64 v[12:13], v[4:5], 0, v[144:145]
	v_lshl_add_u64 v[14:15], v[4:5], 0, v[146:147]
	v_lshl_add_u64 v[16:17], v[4:5], 0, v[148:149]
	v_lshl_add_u64 v[18:19], v[4:5], 0, v[150:151]
	v_lshl_add_u64 v[20:21], v[4:5], 0, v[152:153]
	v_lshl_add_u64 v[22:23], v[4:5], 0, v[154:155]
	v_lshl_add_u64 v[24:25], v[4:5], 0, v[156:157]
	v_lshl_add_u64 v[26:27], v[4:5], 0, v[158:159]
	v_lshl_add_u64 v[28:29], v[4:5], 0, v[162:163]
	v_lshl_add_u64 v[30:31], v[4:5], 0, v[164:165]
	v_lshl_add_u64 v[32:33], v[4:5], 0, v[166:167]
	v_lshl_add_u64 v[34:35], v[4:5], 0, v[168:169]
	v_lshl_add_u64 v[36:37], v[4:5], 0, v[170:171]
	v_lshl_add_u64 v[4:5], v[4:5], 0, v[172:173]
	global_load_dword v70, v[6:7], off offset:512
	global_load_dword v71, v[6:7], off offset:768
	global_load_dword v72, v[6:7], off offset:1024
	global_load_dword v73, v[6:7], off offset:1280
	global_load_dword v74, v[6:7], off offset:1536
	global_load_dword v75, v[6:7], off offset:1792
	global_load_dword v76, v[6:7], off offset:2048
	global_load_dword v77, v[6:7], off offset:2304
	global_load_dword v78, v[6:7], off offset:2560
	global_load_dword v79, v[6:7], off offset:2816
	global_load_dword v80, v[6:7], off offset:3072
	global_load_dword v81, v[6:7], off offset:3328
	global_load_dword v82, v[6:7], off offset:3584
	global_load_dword v83, v[6:7], off offset:3840
	global_load_dword v84, v[8:9], off
	global_load_dword v85, v[10:11], off
	global_load_dword v86, v[12:13], off
	global_load_dword v87, v[14:15], off
	global_load_dword v88, v[16:17], off
	global_load_dword v89, v[18:19], off
	global_load_dword v90, v[20:21], off
	global_load_dword v91, v[22:23], off
	global_load_dword v92, v[24:25], off
	global_load_dword v93, v[26:27], off
	global_load_dword v94, v[28:29], off
	global_load_dword v95, v[30:31], off
	global_load_dword v96, v[32:33], off
	global_load_dword v97, v[34:35], off
	global_load_dword v98, v[36:37], off
	global_load_dword v99, v[4:5], off
	v_cmp_lt_i32_e32 vcc, v223, v218
	v_lshlrev_b64 v[68:69], 12, v[68:69]
	s_mov_b32 s44, 0
	v_lshl_add_u64 v[188:189], v[176:177], 0, v[68:69]
	v_mov_b32_e32 v145, v214
	s_waitcnt vmcnt(30)
	ds_write2st64_b32 v213, v38, v39 offset0:1 offset1:2
	ds_read2_b32 v[178:179], v212 offset0:64 offset1:72
	ds_read2_b32 v[180:181], v212 offset0:80 offset1:88
	ds_read2_b32 v[182:183], v212 offset0:96 offset1:104
	ds_read2_b32 v[184:185], v212 offset0:112 offset1:120
	ds_read2_b32 v[186:187], v212 offset0:128 offset1:136
	s_waitcnt lgkmcnt(4)
	v_lshlrev_b32_sdwa v132, v215, v178 dst_sel:DWORD dst_unused:UNUSED_PAD src0_sel:DWORD src1_sel:WORD_1
	v_add_u32_e32 v4, v250, v132
	v_lshlrev_b32_sdwa v132, v215, v179 dst_sel:DWORD dst_unused:UNUSED_PAD src0_sel:DWORD src1_sel:WORD_1
	v_add_u32_e32 v8, v250, v132
	s_waitcnt lgkmcnt(3)
	v_lshlrev_b32_sdwa v132, v215, v180 dst_sel:DWORD dst_unused:UNUSED_PAD src0_sel:DWORD src1_sel:WORD_1
	v_add_u32_e32 v12, v250, v132
	v_lshlrev_b32_sdwa v132, v215, v181 dst_sel:DWORD dst_unused:UNUSED_PAD src0_sel:DWORD src1_sel:WORD_1
	v_add_u32_e32 v16, v250, v132
	s_waitcnt lgkmcnt(2)
	v_lshlrev_b32_sdwa v132, v215, v182 dst_sel:DWORD dst_unused:UNUSED_PAD src0_sel:DWORD src1_sel:WORD_1
	v_add_u32_e32 v20, v250, v132
	v_lshlrev_b32_sdwa v132, v215, v183 dst_sel:DWORD dst_unused:UNUSED_PAD src0_sel:DWORD src1_sel:WORD_1
	v_add_u32_e32 v24, v250, v132
	s_waitcnt lgkmcnt(1)
	v_lshlrev_b32_sdwa v132, v215, v184 dst_sel:DWORD dst_unused:UNUSED_PAD src0_sel:DWORD src1_sel:WORD_1
	v_add_u32_e32 v28, v250, v132
	v_lshlrev_b32_sdwa v132, v215, v185 dst_sel:DWORD dst_unused:UNUSED_PAD src0_sel:DWORD src1_sel:WORD_1
	v_add_u32_e32 v32, v250, v132
	global_load_dwordx4 v[4:7], v4, s[98:99]
	s_nop 0
	global_load_dwordx4 v[8:11], v8, s[98:99]
	s_nop 0
	global_load_dwordx4 v[12:15], v12, s[98:99]
	s_nop 0
	global_load_dwordx4 v[16:19], v16, s[98:99]
	s_nop 0
	global_load_dwordx4 v[20:23], v20, s[98:99]
	s_nop 0
	global_load_dwordx4 v[24:27], v24, s[98:99]
	s_nop 0
	global_load_dwordx4 v[28:31], v28, s[98:99]
	s_nop 0
	global_load_dwordx4 v[32:35], v32, s[98:99]
	ds_read2_b32 v[190:191], v212 offset0:144 offset1:152
	s_waitcnt lgkmcnt(1)
	v_lshlrev_b32_sdwa v132, v215, v186 dst_sel:DWORD dst_unused:UNUSED_PAD src0_sel:DWORD src1_sel:WORD_1
	v_add_u32_e32 v36, v250, v132
	v_lshlrev_b32_sdwa v132, v215, v187 dst_sel:DWORD dst_unused:UNUSED_PAD src0_sel:DWORD src1_sel:WORD_1
	v_add_u32_e32 v40, v250, v132
	s_waitcnt lgkmcnt(0)
; DI void up_issue(u32x4 (&W)[16], u32 (&pj)[16], const u32* pl, const unsigned char* wbase, int grp) {
; #pragma unroll
;   for (int j = 0; j < 16; ++j) {
;     pj[j] = pl[8 * j + grp];
;     W[j] = *(const u32x4*)(wbase + (size_t)(pj[j] >> 16) * 1024);
;   }
; }
; DI void up_math(const u32x4 (&W)[16], const u32 (&pj)[16], float* __restrict__ yrow, int lane) {
;   f2 y[8];
; #pragma unroll
;   for (int i = 0; i < 8; ++i) y[i] = f2{0.f, 0.f};
; #pragma unroll
;   for (int j = 0; j < 16; ++j) {
;     const float h = __uint_as_float(pj[j] << 16);
;     const f2 hh = {h, h};
; #pragma unroll
;     for (int d = 0; d < 4; ++d) {
;       f2 lo = __builtin_amdgcn_cvt_pk_f32_fp8((int)W[j][d], false);
;       f2 hi = __builtin_amdgcn_cvt_pk_f32_fp8((int)W[j][d], true);
;       y[2 * d] = lo * hh + y[2 * d];
;       y[2 * d + 1] = hi * hh + y[2 * d + 1];
;     }
;   }
; DI void peer_up_phase(const Params& p, unsigned char* smem, int layer, u32* ctr) {
;     ...
;       {
;         const u32* src = hgp + (size_t)t0 * 128;
; #pragma unroll
;         for (int i = 0; i < 32; ++i) pl[i * 64 + lane] = src[i * 64 + lane];
;       }
;       float* ybase = yb + (size_t)t0 * 1024 + slice * 128;
;       u32x4 WA[16], WB[16];
;       u32 pA[16], pB[16];
;       up_issue(WA, pA, pl, wbase, grp);
;       for (int tl = 0; tl < 16; tl += 2) {
;         up_issue(WB, pB, pl + (tl + 1) * 128, wbase, grp);
;         __builtin_amdgcn_sched_barrier(0);
;         up_math(WA, pA, ybase + (size_t)tl * 1024, lane);
;         __builtin_amdgcn_sched_barrier(0);
;         if (tl + 2 < 16) up_issue(WA, pA, pl + (tl + 2) * 128, wbase, grp);
	v_lshlrev_b32_sdwa v132, v215, v190 dst_sel:DWORD dst_unused:UNUSED_PAD src0_sel:DWORD src1_sel:WORD_1
	global_load_dwordx4 v[36:39], v36, s[98:99]
	s_nop 0
	global_load_dwordx4 v[40:43], v40, s[98:99]
	v_add_u32_e32 v44, v250, v132
	ds_read2_b32 v[192:193], v212 offset0:160 offset1:168
	v_lshlrev_b32_sdwa v132, v215, v191 dst_sel:DWORD dst_unused:UNUSED_PAD src0_sel:DWORD src1_sel:WORD_1
	v_add_u32_e32 v48, v250, v132
	global_load_dwordx4 v[44:47], v44, s[98:99]
	s_nop 0
	global_load_dwordx4 v[48:51], v48, s[98:99]
	ds_read2_b32 v[194:195], v212 offset0:176 offset1:184
	s_waitcnt lgkmcnt(1)
	v_lshlrev_b32_sdwa v132, v215, v192 dst_sel:DWORD dst_unused:UNUSED_PAD src0_sel:DWORD src1_sel:WORD_1
	v_add_u32_e32 v52, v250, v132
	v_lshlrev_b32_sdwa v132, v215, v193 dst_sel:DWORD dst_unused:UNUSED_PAD src0_sel:DWORD src1_sel:WORD_1
	v_add_u32_e32 v56, v250, v132
	s_waitcnt lgkmcnt(0)
	v_lshlrev_b32_sdwa v132, v215, v194 dst_sel:DWORD dst_unused:UNUSED_PAD src0_sel:DWORD src1_sel:WORD_1
	v_add_u32_e32 v60, v250, v132
	v_lshlrev_b32_sdwa v132, v215, v195 dst_sel:DWORD dst_unused:UNUSED_PAD src0_sel:DWORD src1_sel:WORD_1
	v_add_u32_e32 v64, v250, v132
	global_load_dwordx4 v[52:55], v52, s[98:99]
	s_nop 0
	global_load_dwordx4 v[56:59], v56, s[98:99]
	s_nop 0
	global_load_dwordx4 v[60:63], v60, s[98:99]
	s_nop 0
	global_load_dwordx4 v[64:67], v64, s[98:99]
	s_waitcnt vmcnt(44)
	ds_write2st64_b32 v213, v70, v71 offset0:3 offset1:4
	s_waitcnt vmcnt(42)
	ds_write2st64_b32 v213, v72, v73 offset0:5 offset1:6
	s_waitcnt vmcnt(40)
	ds_write2st64_b32 v213, v74, v75 offset0:7 offset1:8
	s_waitcnt vmcnt(38)
	ds_write2st64_b32 v213, v76, v77 offset0:9 offset1:10
	s_waitcnt vmcnt(36)
	ds_write2st64_b32 v213, v78, v79 offset0:11 offset1:12
	s_waitcnt vmcnt(34)
	ds_write2st64_b32 v213, v80, v81 offset0:13 offset1:14
	s_waitcnt vmcnt(32)
	ds_write2st64_b32 v213, v82, v83 offset0:15 offset1:16
	s_waitcnt vmcnt(30)
	ds_write2st64_b32 v213, v84, v85 offset0:17 offset1:18
	s_waitcnt vmcnt(28)
	ds_write2st64_b32 v213, v86, v87 offset0:19 offset1:20
	s_waitcnt vmcnt(26)
	ds_write2st64_b32 v213, v88, v89 offset0:21 offset1:22
	s_waitcnt vmcnt(24)
	ds_write2st64_b32 v213, v90, v91 offset0:23 offset1:24
	s_waitcnt vmcnt(22)
	ds_write2st64_b32 v213, v92, v93 offset0:25 offset1:26
	s_waitcnt vmcnt(20)
	ds_write2st64_b32 v213, v94, v95 offset0:27 offset1:28
	s_waitcnt vmcnt(18)
	ds_write2st64_b32 v213, v96, v97 offset0:29 offset1:30
	s_waitcnt vmcnt(16)
	ds_write2st64_b32 v213, v98, v99 offset0:31 offset1:32
	v_cndmask_b32_e32 v70, v161, v223, vcc
	v_cmp_lt_i32_e32 vcc, v224, v218
	v_lshlrev_b32_e32 v139, 2, v70
	s_nop 0
	v_cndmask_b32_e32 v70, v161, v224, vcc
	v_cmp_lt_i32_e32 vcc, v222, v218
	v_lshlrev_b32_e32 v141, 2, v70
	s_nop 0
	v_cndmask_b32_e32 v70, v161, v222, vcc
	v_lshlrev_b32_e32 v143, 2, v70
	v_lshlrev_b32_e32 v178, 16, v178
	v_lshlrev_b32_e32 v179, 16, v179
	v_lshlrev_b32_e32 v180, 16, v180
	v_lshlrev_b32_e32 v181, 16, v181
	v_lshlrev_b32_e32 v182, 16, v182
	v_lshlrev_b32_e32 v183, 16, v183
	v_lshlrev_b32_e32 v184, 16, v184
	v_lshlrev_b32_e32 v185, 16, v185
	v_lshlrev_b32_e32 v186, 16, v186
	v_lshlrev_b32_e32 v187, 16, v187
	v_lshlrev_b32_e32 v190, 16, v190
	v_lshlrev_b32_e32 v191, 16, v191
	v_lshlrev_b32_e32 v192, 16, v192
	v_lshlrev_b32_e32 v193, 16, v193
	v_lshlrev_b32_e32 v194, 16, v194
	v_lshlrev_b32_e32 v195, 16, v195
	v_mov_b32_e32 v210, 0
	v_mov_b32_e32 v211, 0
	v_mov_b32_e32 v208, 0
	v_mov_b32_e32 v209, 0
	v_mov_b32_e32 v206, 0
	v_mov_b32_e32 v207, 0
	v_mov_b32_e32 v204, 0
	v_mov_b32_e32 v205, 0
	v_mov_b32_e32 v202, 0
	v_mov_b32_e32 v203, 0
	v_mov_b32_e32 v200, 0
	v_mov_b32_e32 v201, 0
	v_mov_b32_e32 v198, 0
	v_mov_b32_e32 v199, 0
	v_mov_b32_e32 v196, 0
	v_mov_b32_e32 v197, 0
	s_branch .LBB0_827
.LBB0_826:
	s_add_i32 s44, s44, 2
	s_cmp_lg_u32 s44, 8
	s_cbranch_scc1 .Lmy_lpf_826
	global_load_dword v254, v[252:253], off
.Lmy_lpf_826:
	s_waitcnt vmcnt(16)
	v_cvt_pk_f32_fp8_e32 v[216:217], v128
	v_cvt_pk_f32_fp8_sdwa v[226:227], v128 src0_sel:WORD_1
	v_cvt_pk_f32_fp8_e32 v[228:229], v129
	v_cvt_pk_f32_fp8_sdwa v[128:129], v129 src0_sel:WORD_1
	v_cvt_pk_f32_fp8_e32 v[230:231], v130
	v_cvt_pk_f32_fp8_sdwa v[232:233], v130 src0_sel:WORD_1
	v_cvt_pk_f32_fp8_e32 v[234:235], v131
	v_cvt_pk_f32_fp8_sdwa v[130:131], v131 src0_sel:WORD_1
	v_pk_fma_f32 v[216:217], v[210:211], v[216:217], 0 op_sel_hi:[0,1,0]
	v_pk_fma_f32 v[226:227], v[210:211], v[226:227], 0 op_sel_hi:[0,1,0]
	v_pk_fma_f32 v[228:229], v[210:211], v[228:229], 0 op_sel_hi:[0,1,0]
	v_pk_fma_f32 v[128:129], v[210:211], v[128:129], 0 op_sel_hi:[0,1,0]
	v_pk_fma_f32 v[230:231], v[210:211], v[230:231], 0 op_sel_hi:[0,1,0]
	v_pk_fma_f32 v[232:233], v[210:211], v[232:233], 0 op_sel_hi:[0,1,0]
	v_pk_fma_f32 v[234:235], v[210:211], v[234:235], 0 op_sel_hi:[0,1,0]
	v_pk_fma_f32 v[130:131], v[210:211], v[130:131], 0 op_sel_hi:[0,1,0]
	v_mov_b32_e32 v132, v211
	s_waitcnt vmcnt(15)
	v_cvt_pk_f32_fp8_e32 v[210:211], v124
	v_cvt_pk_f32_fp8_sdwa v[236:237], v124 src0_sel:WORD_1
	v_cvt_pk_f32_fp8_e32 v[238:239], v125
	v_cvt_pk_f32_fp8_sdwa v[124:125], v125 src0_sel:WORD_1
	v_pk_fma_f32 v[210:211], v[132:133], v[210:211], v[216:217] op_sel_hi:[0,1,1]
	v_pk_fma_f32 v[216:217], v[132:133], v[236:237], v[226:227] op_sel_hi:[0,1,1]
	v_pk_fma_f32 v[226:227], v[132:133], v[238:239], v[228:229] op_sel_hi:[0,1,1]
	v_pk_fma_f32 v[124:125], v[132:133], v[124:125], v[128:129] op_sel_hi:[0,1,1]
	v_cvt_pk_f32_fp8_e32 v[128:129], v126
	v_cvt_pk_f32_fp8_sdwa v[228:229], v126 src0_sel:WORD_1
	v_cvt_pk_f32_fp8_e32 v[236:237], v127
	v_cvt_pk_f32_fp8_sdwa v[126:127], v127 src0_sel:WORD_1
	v_pk_fma_f32 v[128:129], v[132:133], v[128:129], v[230:231] op_sel_hi:[0,1,1]
	v_pk_fma_f32 v[228:229], v[132:133], v[228:229], v[232:233] op_sel_hi:[0,1,1]
	v_pk_fma_f32 v[230:231], v[132:133], v[236:237], v[234:235] op_sel_hi:[0,1,1]
	s_waitcnt vmcnt(14)
; DI void up_math(const u32x4 (&W)[16], const u32 (&pj)[16], float* __restrict__ yrow, int lane) {
;   f2 y[8];
; #pragma unroll
;   for (int i = 0; i < 8; ++i) y[i] = f2{0.f, 0.f};
; #pragma unroll
;   for (int j = 0; j < 16; ++j) {
;     const float h = __uint_as_float(pj[j] << 16);
;     const f2 hh = {h, h};
; #pragma unroll
;     for (int d = 0; d < 4; ++d) {
;       f2 lo = __builtin_amdgcn_cvt_pk_f32_fp8((int)W[j][d], false);
;       f2 hi = __builtin_amdgcn_cvt_pk_f32_fp8((int)W[j][d], true);
;       y[2 * d] = lo * hh + y[2 * d];
;       y[2 * d + 1] = hi * hh + y[2 * d + 1];
;     }
;   }
	v_cvt_pk_f32_fp8_e32 v[232:233], v120
	v_cvt_pk_f32_fp8_sdwa v[234:235], v120 src0_sel:WORD_1
	v_cvt_pk_f32_fp8_e32 v[236:237], v121
	v_cvt_pk_f32_fp8_sdwa v[120:121], v121 src0_sel:WORD_1
	v_pk_fma_f32 v[126:127], v[132:133], v[126:127], v[130:131] op_sel_hi:[0,1,1]
	v_pk_fma_f32 v[210:211], v[208:209], v[232:233], v[210:211] op_sel_hi:[0,1,1]
	v_pk_fma_f32 v[216:217], v[208:209], v[234:235], v[216:217] op_sel_hi:[0,1,1]
	v_pk_fma_f32 v[120:121], v[208:209], v[120:121], v[124:125] op_sel_hi:[0,1,1]
	v_cvt_pk_f32_fp8_e32 v[124:125], v122
	v_cvt_pk_f32_fp8_sdwa v[232:233], v122 src0_sel:WORD_1
	v_cvt_pk_f32_fp8_e32 v[234:235], v123
	v_cvt_pk_f32_fp8_sdwa v[122:123], v123 src0_sel:WORD_1
	v_pk_fma_f32 v[226:227], v[208:209], v[236:237], v[226:227] op_sel_hi:[0,1,1]
	v_pk_fma_f32 v[124:125], v[208:209], v[124:125], v[128:129] op_sel_hi:[0,1,1]
	v_pk_fma_f32 v[128:129], v[208:209], v[232:233], v[228:229] op_sel_hi:[0,1,1]
	v_pk_fma_f32 v[228:229], v[208:209], v[234:235], v[230:231] op_sel_hi:[0,1,1]
	v_pk_fma_f32 v[122:123], v[208:209], v[122:123], v[126:127] op_sel_hi:[0,1,1]
	v_mov_b32_e32 v126, v209
	s_waitcnt vmcnt(13)
	v_cvt_pk_f32_fp8_e32 v[130:131], v116
	v_cvt_pk_f32_fp8_sdwa v[208:209], v116 src0_sel:WORD_1
	v_cvt_pk_f32_fp8_e32 v[230:231], v117
	v_cvt_pk_f32_fp8_sdwa v[116:117], v117 src0_sel:WORD_1
	v_pk_fma_f32 v[130:131], v[126:127], v[130:131], v[210:211] op_sel_hi:[0,1,1]
	v_pk_fma_f32 v[208:209], v[126:127], v[208:209], v[216:217] op_sel_hi:[0,1,1]
	v_pk_fma_f32 v[210:211], v[126:127], v[230:231], v[226:227] op_sel_hi:[0,1,1]
	v_pk_fma_f32 v[116:117], v[126:127], v[116:117], v[120:121] op_sel_hi:[0,1,1]
	v_cvt_pk_f32_fp8_e32 v[120:121], v118
	v_cvt_pk_f32_fp8_sdwa v[216:217], v118 src0_sel:WORD_1
	v_cvt_pk_f32_fp8_e32 v[226:227], v119
	v_cvt_pk_f32_fp8_sdwa v[118:119], v119 src0_sel:WORD_1
	v_pk_fma_f32 v[120:121], v[126:127], v[120:121], v[124:125] op_sel_hi:[0,1,1]
	v_pk_fma_f32 v[124:125], v[126:127], v[216:217], v[128:129] op_sel_hi:[0,1,1]
	v_pk_fma_f32 v[128:129], v[126:127], v[226:227], v[228:229] op_sel_hi:[0,1,1]
	v_pk_fma_f32 v[118:119], v[126:127], v[118:119], v[122:123] op_sel_hi:[0,1,1]
	s_waitcnt vmcnt(12)
	v_cvt_pk_f32_fp8_e32 v[126:127], v112
	v_cvt_pk_f32_fp8_sdwa v[216:217], v112 src0_sel:WORD_1
	v_cvt_pk_f32_fp8_e32 v[226:227], v113
	v_cvt_pk_f32_fp8_sdwa v[112:113], v113 src0_sel:WORD_1
	v_pk_fma_f32 v[126:127], v[206:207], v[126:127], v[130:131] op_sel_hi:[0,1,1]
	v_pk_fma_f32 v[130:131], v[206:207], v[216:217], v[208:209] op_sel_hi:[0,1,1]
	v_pk_fma_f32 v[208:209], v[206:207], v[226:227], v[210:211] op_sel_hi:[0,1,1]
	v_pk_fma_f32 v[112:113], v[206:207], v[112:113], v[116:117] op_sel_hi:[0,1,1]
	v_cvt_pk_f32_fp8_e32 v[116:117], v114
	v_cvt_pk_f32_fp8_sdwa v[210:211], v114 src0_sel:WORD_1
	v_cvt_pk_f32_fp8_e32 v[216:217], v115
	v_cvt_pk_f32_fp8_sdwa v[114:115], v115 src0_sel:WORD_1
	v_pk_fma_f32 v[116:117], v[206:207], v[116:117], v[120:121] op_sel_hi:[0,1,1]
	v_pk_fma_f32 v[120:121], v[206:207], v[210:211], v[124:125] op_sel_hi:[0,1,1]
	v_pk_fma_f32 v[124:125], v[206:207], v[216:217], v[128:129] op_sel_hi:[0,1,1]
	v_pk_fma_f32 v[114:115], v[206:207], v[114:115], v[118:119] op_sel_hi:[0,1,1]
	v_mov_b32_e32 v118, v207
	s_waitcnt vmcnt(11)
	v_cvt_pk_f32_fp8_e32 v[122:123], v108
	v_cvt_pk_f32_fp8_sdwa v[128:129], v108 src0_sel:WORD_1
	v_cvt_pk_f32_fp8_e32 v[206:207], v109
	v_cvt_pk_f32_fp8_sdwa v[108:109], v109 src0_sel:WORD_1
	v_pk_fma_f32 v[122:123], v[118:119], v[122:123], v[126:127] op_sel_hi:[0,1,1]
	v_pk_fma_f32 v[126:127], v[118:119], v[128:129], v[130:131] op_sel_hi:[0,1,1]
	v_pk_fma_f32 v[128:129], v[118:119], v[206:207], v[208:209] op_sel_hi:[0,1,1]
	v_pk_fma_f32 v[108:109], v[118:119], v[108:109], v[112:113] op_sel_hi:[0,1,1]
	v_cvt_pk_f32_fp8_e32 v[112:113], v110
	v_cvt_pk_f32_fp8_sdwa v[130:131], v110 src0_sel:WORD_1
	v_cvt_pk_f32_fp8_e32 v[206:207], v111
	v_cvt_pk_f32_fp8_sdwa v[110:111], v111 src0_sel:WORD_1
	v_pk_fma_f32 v[112:113], v[118:119], v[112:113], v[116:117] op_sel_hi:[0,1,1]
	v_pk_fma_f32 v[116:117], v[118:119], v[130:131], v[120:121] op_sel_hi:[0,1,1]
	v_pk_fma_f32 v[120:121], v[118:119], v[206:207], v[124:125] op_sel_hi:[0,1,1]
	v_pk_fma_f32 v[110:111], v[118:119], v[110:111], v[114:115] op_sel_hi:[0,1,1]
	s_waitcnt vmcnt(10)
	v_cvt_pk_f32_fp8_e32 v[118:119], v104
	v_cvt_pk_f32_fp8_sdwa v[124:125], v104 src0_sel:WORD_1
	v_cvt_pk_f32_fp8_e32 v[130:131], v105
	v_cvt_pk_f32_fp8_sdwa v[104:105], v105 src0_sel:WORD_1
	v_pk_fma_f32 v[118:119], v[204:205], v[118:119], v[122:123] op_sel_hi:[0,1,1]
	v_pk_fma_f32 v[122:123], v[204:205], v[124:125], v[126:127] op_sel_hi:[0,1,1]
	v_pk_fma_f32 v[124:125], v[204:205], v[130:131], v[128:129] op_sel_hi:[0,1,1]
	v_pk_fma_f32 v[104:105], v[204:205], v[104:105], v[108:109] op_sel_hi:[0,1,1]
	v_cvt_pk_f32_fp8_e32 v[108:109], v106
	v_cvt_pk_f32_fp8_sdwa v[126:127], v106 src0_sel:WORD_1
	v_cvt_pk_f32_fp8_e32 v[128:129], v107
	v_cvt_pk_f32_fp8_sdwa v[106:107], v107 src0_sel:WORD_1
	v_pk_fma_f32 v[108:109], v[204:205], v[108:109], v[112:113] op_sel_hi:[0,1,1]
	v_pk_fma_f32 v[112:113], v[204:205], v[126:127], v[116:117] op_sel_hi:[0,1,1]
	v_pk_fma_f32 v[116:117], v[204:205], v[128:129], v[120:121] op_sel_hi:[0,1,1]
	v_pk_fma_f32 v[106:107], v[204:205], v[106:107], v[110:111] op_sel_hi:[0,1,1]
	s_waitcnt vmcnt(9)
; DI void up_math(const u32x4 (&W)[16], const u32 (&pj)[16], float* __restrict__ yrow, int lane) {
;   f2 y[8];
; #pragma unroll
;   for (int i = 0; i < 8; ++i) y[i] = f2{0.f, 0.f};
; #pragma unroll
;   for (int j = 0; j < 16; ++j) {
;     const float h = __uint_as_float(pj[j] << 16);
;     const f2 hh = {h, h};
; #pragma unroll
;     for (int d = 0; d < 4; ++d) {
;       f2 lo = __builtin_amdgcn_cvt_pk_f32_fp8((int)W[j][d], false);
;       f2 hi = __builtin_amdgcn_cvt_pk_f32_fp8((int)W[j][d], true);
;       y[2 * d] = lo * hh + y[2 * d];
;       y[2 * d + 1] = hi * hh + y[2 * d + 1];
;     }
;   }
	v_cvt_pk_f32_fp8_e32 v[114:115], v100
	v_cvt_pk_f32_fp8_sdwa v[120:121], v100 src0_sel:WORD_1
	v_cvt_pk_f32_fp8_e32 v[126:127], v101
	v_cvt_pk_f32_fp8_sdwa v[100:101], v101 src0_sel:WORD_1
	v_pk_fma_f32 v[114:115], v[204:205], v[114:115], v[118:119] op_sel:[1,0,0] op_sel_hi:[1,1,1]
	v_pk_fma_f32 v[118:119], v[204:205], v[120:121], v[122:123] op_sel:[1,0,0] op_sel_hi:[1,1,1]
	v_pk_fma_f32 v[120:121], v[204:205], v[126:127], v[124:125] op_sel:[1,0,0] op_sel_hi:[1,1,1]
	v_pk_fma_f32 v[100:101], v[204:205], v[100:101], v[104:105] op_sel:[1,0,0] op_sel_hi:[1,1,1]
	v_cvt_pk_f32_fp8_e32 v[104:105], v102
	v_cvt_pk_f32_fp8_sdwa v[122:123], v102 src0_sel:WORD_1
	v_cvt_pk_f32_fp8_e32 v[124:125], v103
	v_cvt_pk_f32_fp8_sdwa v[102:103], v103 src0_sel:WORD_1
	v_pk_fma_f32 v[104:105], v[204:205], v[104:105], v[108:109] op_sel:[1,0,0] op_sel_hi:[1,1,1]
	v_pk_fma_f32 v[108:109], v[204:205], v[122:123], v[112:113] op_sel:[1,0,0] op_sel_hi:[1,1,1]
	v_pk_fma_f32 v[112:113], v[204:205], v[124:125], v[116:117] op_sel:[1,0,0] op_sel_hi:[1,1,1]
	v_pk_fma_f32 v[102:103], v[204:205], v[102:103], v[106:107] op_sel:[1,0,0] op_sel_hi:[1,1,1]
	s_waitcnt vmcnt(8)
	v_cvt_pk_f32_fp8_e32 v[110:111], v96
	v_cvt_pk_f32_fp8_sdwa v[116:117], v96 src0_sel:WORD_1
	v_cvt_pk_f32_fp8_e32 v[122:123], v97
	v_cvt_pk_f32_fp8_sdwa v[96:97], v97 src0_sel:WORD_1
	v_pk_fma_f32 v[110:111], v[202:203], v[110:111], v[114:115] op_sel_hi:[0,1,1]
	v_pk_fma_f32 v[114:115], v[202:203], v[116:117], v[118:119] op_sel_hi:[0,1,1]
	v_pk_fma_f32 v[116:117], v[202:203], v[122:123], v[120:121] op_sel_hi:[0,1,1]
	v_pk_fma_f32 v[96:97], v[202:203], v[96:97], v[100:101] op_sel_hi:[0,1,1]
	v_cvt_pk_f32_fp8_e32 v[100:101], v98
	v_cvt_pk_f32_fp8_sdwa v[118:119], v98 src0_sel:WORD_1
	v_cvt_pk_f32_fp8_e32 v[120:121], v99
	v_cvt_pk_f32_fp8_sdwa v[98:99], v99 src0_sel:WORD_1
	v_pk_fma_f32 v[100:101], v[202:203], v[100:101], v[104:105] op_sel_hi:[0,1,1]
	v_pk_fma_f32 v[104:105], v[202:203], v[118:119], v[108:109] op_sel_hi:[0,1,1]
	v_pk_fma_f32 v[108:109], v[202:203], v[120:121], v[112:113] op_sel_hi:[0,1,1]
	v_pk_fma_f32 v[98:99], v[202:203], v[98:99], v[102:103] op_sel_hi:[0,1,1]
	s_waitcnt vmcnt(7)
	v_cvt_pk_f32_fp8_e32 v[106:107], v92
	v_cvt_pk_f32_fp8_sdwa v[112:113], v92 src0_sel:WORD_1
	v_cvt_pk_f32_fp8_e32 v[118:119], v93
	v_cvt_pk_f32_fp8_sdwa v[92:93], v93 src0_sel:WORD_1
	v_pk_fma_f32 v[106:107], v[202:203], v[106:107], v[110:111] op_sel:[1,0,0] op_sel_hi:[1,1,1]
	v_pk_fma_f32 v[110:111], v[202:203], v[112:113], v[114:115] op_sel:[1,0,0] op_sel_hi:[1,1,1]
	v_pk_fma_f32 v[112:113], v[202:203], v[118:119], v[116:117] op_sel:[1,0,0] op_sel_hi:[1,1,1]
	v_pk_fma_f32 v[92:93], v[202:203], v[92:93], v[96:97] op_sel:[1,0,0] op_sel_hi:[1,1,1]
	v_cvt_pk_f32_fp8_e32 v[96:97], v94
	v_cvt_pk_f32_fp8_sdwa v[114:115], v94 src0_sel:WORD_1
	v_cvt_pk_f32_fp8_e32 v[116:117], v95
	v_cvt_pk_f32_fp8_sdwa v[94:95], v95 src0_sel:WORD_1
	v_pk_fma_f32 v[96:97], v[202:203], v[96:97], v[100:101] op_sel:[1,0,0] op_sel_hi:[1,1,1]
	v_pk_fma_f32 v[100:101], v[202:203], v[114:115], v[104:105] op_sel:[1,0,0] op_sel_hi:[1,1,1]
	v_pk_fma_f32 v[104:105], v[202:203], v[116:117], v[108:109] op_sel:[1,0,0] op_sel_hi:[1,1,1]
	v_pk_fma_f32 v[94:95], v[202:203], v[94:95], v[98:99] op_sel:[1,0,0] op_sel_hi:[1,1,1]
	s_waitcnt vmcnt(6)
	v_cvt_pk_f32_fp8_e32 v[102:103], v88
	v_cvt_pk_f32_fp8_sdwa v[108:109], v88 src0_sel:WORD_1
	v_cvt_pk_f32_fp8_e32 v[114:115], v89
	v_cvt_pk_f32_fp8_sdwa v[88:89], v89 src0_sel:WORD_1
	v_pk_fma_f32 v[102:103], v[200:201], v[102:103], v[106:107] op_sel_hi:[0,1,1]
	v_pk_fma_f32 v[106:107], v[200:201], v[108:109], v[110:111] op_sel_hi:[0,1,1]
	v_pk_fma_f32 v[108:109], v[200:201], v[114:115], v[112:113] op_sel_hi:[0,1,1]
	v_pk_fma_f32 v[88:89], v[200:201], v[88:89], v[92:93] op_sel_hi:[0,1,1]
	v_cvt_pk_f32_fp8_e32 v[92:93], v90
	v_cvt_pk_f32_fp8_sdwa v[110:111], v90 src0_sel:WORD_1
	v_cvt_pk_f32_fp8_e32 v[112:113], v91
	v_cvt_pk_f32_fp8_sdwa v[90:91], v91 src0_sel:WORD_1
	v_pk_fma_f32 v[92:93], v[200:201], v[92:93], v[96:97] op_sel_hi:[0,1,1]
	v_pk_fma_f32 v[96:97], v[200:201], v[110:111], v[100:101] op_sel_hi:[0,1,1]
	v_pk_fma_f32 v[100:101], v[200:201], v[112:113], v[104:105] op_sel_hi:[0,1,1]
	v_pk_fma_f32 v[90:91], v[200:201], v[90:91], v[94:95] op_sel_hi:[0,1,1]
	s_waitcnt vmcnt(5)
	v_cvt_pk_f32_fp8_e32 v[98:99], v84
	v_cvt_pk_f32_fp8_sdwa v[104:105], v84 src0_sel:WORD_1
	v_cvt_pk_f32_fp8_e32 v[110:111], v85
	v_cvt_pk_f32_fp8_sdwa v[84:85], v85 src0_sel:WORD_1
	v_pk_fma_f32 v[98:99], v[200:201], v[98:99], v[102:103] op_sel:[1,0,0] op_sel_hi:[1,1,1]
	v_pk_fma_f32 v[102:103], v[200:201], v[104:105], v[106:107] op_sel:[1,0,0] op_sel_hi:[1,1,1]
	v_pk_fma_f32 v[104:105], v[200:201], v[110:111], v[108:109] op_sel:[1,0,0] op_sel_hi:[1,1,1]
	v_pk_fma_f32 v[84:85], v[200:201], v[84:85], v[88:89] op_sel:[1,0,0] op_sel_hi:[1,1,1]
	v_cvt_pk_f32_fp8_e32 v[88:89], v86
	v_cvt_pk_f32_fp8_sdwa v[106:107], v86 src0_sel:WORD_1
	v_cvt_pk_f32_fp8_e32 v[108:109], v87
	v_cvt_pk_f32_fp8_sdwa v[86:87], v87 src0_sel:WORD_1
	v_pk_fma_f32 v[88:89], v[200:201], v[88:89], v[92:93] op_sel:[1,0,0] op_sel_hi:[1,1,1]
	v_pk_fma_f32 v[92:93], v[200:201], v[106:107], v[96:97] op_sel:[1,0,0] op_sel_hi:[1,1,1]
	v_pk_fma_f32 v[96:97], v[200:201], v[108:109], v[100:101] op_sel:[1,0,0] op_sel_hi:[1,1,1]
	v_pk_fma_f32 v[86:87], v[200:201], v[86:87], v[90:91] op_sel:[1,0,0] op_sel_hi:[1,1,1]
	s_waitcnt vmcnt(4)
; DI void up_math(const u32x4 (&W)[16], const u32 (&pj)[16], float* __restrict__ yrow, int lane) {
;   f2 y[8];
; #pragma unroll
;   for (int i = 0; i < 8; ++i) y[i] = f2{0.f, 0.f};
; #pragma unroll
;   for (int j = 0; j < 16; ++j) {
;     const float h = __uint_as_float(pj[j] << 16);
;     const f2 hh = {h, h};
; #pragma unroll
;     for (int d = 0; d < 4; ++d) {
;       f2 lo = __builtin_amdgcn_cvt_pk_f32_fp8((int)W[j][d], false);
;       f2 hi = __builtin_amdgcn_cvt_pk_f32_fp8((int)W[j][d], true);
;       y[2 * d] = lo * hh + y[2 * d];
;       y[2 * d + 1] = hi * hh + y[2 * d + 1];
;     }
;   }
;   const bool b5 = lane & 32, b4 = lane & 16, b3 = lane & 8;
;   f2 q4[4];
; #pragma unroll
;   for (int i = 0; i < 4; ++i) {
;     f2 snd = b5 ? y[i] : y[i + 4]; f2 kp = b5 ? y[i + 4] : y[i];
;     q4[i] = f2{kp.x + __shfl_xor(snd.x, 32), kp.y + __shfl_xor(snd.y, 32)};
;   }
;   f2 r2[2];
; #pragma unroll
;   for (int i = 0; i < 2; ++i) {
;     f2 snd = b4 ? q4[i] : q4[i + 2]; f2 kp = b4 ? q4[i + 2] : q4[i];
;     r2[i] = f2{kp.x + __shfl_xor(snd.x, 16), kp.y + __shfl_xor(snd.y, 16)};
;   }
;   f2 a;
;   { f2 snd = b3 ? r2[0] : r2[1]; f2 kp = b3 ? r2[1] : r2[0]; a = f2{kp.x + __shfl_xor(snd.x, 8), kp.y + __shfl_xor(snd.y, 8)}; }
;   const int ci = (b5 ? 4 : 0) + (b4 ? 2 : 0) + (b3 ? 1 : 0);
;   *(float2*)(yrow + (lane & 7) * 16 + 2 * ci) = make_float2(a.x, a.y);
; }
	v_cvt_pk_f32_fp8_e32 v[94:95], v80
	v_cvt_pk_f32_fp8_sdwa v[100:101], v80 src0_sel:WORD_1
	v_cvt_pk_f32_fp8_e32 v[106:107], v81
	v_cvt_pk_f32_fp8_sdwa v[80:81], v81 src0_sel:WORD_1
	v_pk_fma_f32 v[94:95], v[198:199], v[94:95], v[98:99] op_sel_hi:[0,1,1]
	v_pk_fma_f32 v[98:99], v[198:199], v[100:101], v[102:103] op_sel_hi:[0,1,1]
	v_pk_fma_f32 v[100:101], v[198:199], v[106:107], v[104:105] op_sel_hi:[0,1,1]
	v_pk_fma_f32 v[80:81], v[198:199], v[80:81], v[84:85] op_sel_hi:[0,1,1]
	v_cvt_pk_f32_fp8_e32 v[84:85], v82
	v_cvt_pk_f32_fp8_sdwa v[102:103], v82 src0_sel:WORD_1
	v_cvt_pk_f32_fp8_e32 v[104:105], v83
	v_cvt_pk_f32_fp8_sdwa v[82:83], v83 src0_sel:WORD_1
	v_pk_fma_f32 v[84:85], v[198:199], v[84:85], v[88:89] op_sel_hi:[0,1,1]
	v_pk_fma_f32 v[88:89], v[198:199], v[102:103], v[92:93] op_sel_hi:[0,1,1]
	v_pk_fma_f32 v[92:93], v[198:199], v[104:105], v[96:97] op_sel_hi:[0,1,1]
	v_pk_fma_f32 v[82:83], v[198:199], v[82:83], v[86:87] op_sel_hi:[0,1,1]
	s_waitcnt vmcnt(3)
	v_cvt_pk_f32_fp8_e32 v[90:91], v76
	v_cvt_pk_f32_fp8_sdwa v[96:97], v76 src0_sel:WORD_1
	v_cvt_pk_f32_fp8_e32 v[102:103], v77
	v_cvt_pk_f32_fp8_sdwa v[76:77], v77 src0_sel:WORD_1
	v_pk_fma_f32 v[90:91], v[198:199], v[90:91], v[94:95] op_sel:[1,0,0] op_sel_hi:[1,1,1]
	v_pk_fma_f32 v[94:95], v[198:199], v[96:97], v[98:99] op_sel:[1,0,0] op_sel_hi:[1,1,1]
	v_pk_fma_f32 v[96:97], v[198:199], v[102:103], v[100:101] op_sel:[1,0,0] op_sel_hi:[1,1,1]
	v_pk_fma_f32 v[76:77], v[198:199], v[76:77], v[80:81] op_sel:[1,0,0] op_sel_hi:[1,1,1]
	v_cvt_pk_f32_fp8_e32 v[80:81], v78
	v_cvt_pk_f32_fp8_sdwa v[98:99], v78 src0_sel:WORD_1
	v_cvt_pk_f32_fp8_e32 v[100:101], v79
	v_cvt_pk_f32_fp8_sdwa v[78:79], v79 src0_sel:WORD_1
	v_pk_fma_f32 v[80:81], v[198:199], v[80:81], v[84:85] op_sel:[1,0,0] op_sel_hi:[1,1,1]
	v_pk_fma_f32 v[84:85], v[198:199], v[98:99], v[88:89] op_sel:[1,0,0] op_sel_hi:[1,1,1]
	v_pk_fma_f32 v[88:89], v[198:199], v[100:101], v[92:93] op_sel:[1,0,0] op_sel_hi:[1,1,1]
	v_pk_fma_f32 v[78:79], v[198:199], v[78:79], v[82:83] op_sel:[1,0,0] op_sel_hi:[1,1,1]
	s_waitcnt vmcnt(2)
	v_cvt_pk_f32_fp8_e32 v[86:87], v72
	v_cvt_pk_f32_fp8_sdwa v[92:93], v72 src0_sel:WORD_1
	v_cvt_pk_f32_fp8_e32 v[98:99], v73
	v_cvt_pk_f32_fp8_sdwa v[72:73], v73 src0_sel:WORD_1
	v_pk_fma_f32 v[86:87], v[196:197], v[86:87], v[90:91] op_sel_hi:[0,1,1]
	v_pk_fma_f32 v[90:91], v[196:197], v[92:93], v[94:95] op_sel_hi:[0,1,1]
	v_pk_fma_f32 v[92:93], v[196:197], v[98:99], v[96:97] op_sel_hi:[0,1,1]
	v_pk_fma_f32 v[72:73], v[196:197], v[72:73], v[76:77] op_sel_hi:[0,1,1]
	v_cvt_pk_f32_fp8_e32 v[76:77], v74
	v_cvt_pk_f32_fp8_sdwa v[94:95], v74 src0_sel:WORD_1
	v_cvt_pk_f32_fp8_e32 v[96:97], v75
	v_cvt_pk_f32_fp8_sdwa v[74:75], v75 src0_sel:WORD_1
	v_pk_fma_f32 v[76:77], v[196:197], v[76:77], v[80:81] op_sel_hi:[0,1,1]
	v_pk_fma_f32 v[80:81], v[196:197], v[94:95], v[84:85] op_sel_hi:[0,1,1]
	v_pk_fma_f32 v[84:85], v[196:197], v[96:97], v[88:89] op_sel_hi:[0,1,1]
	v_pk_fma_f32 v[74:75], v[196:197], v[74:75], v[78:79] op_sel_hi:[0,1,1]
	s_waitcnt vmcnt(1)
	v_cvt_pk_f32_fp8_e32 v[82:83], v68
	v_cvt_pk_f32_fp8_sdwa v[88:89], v68 src0_sel:WORD_1
	v_cvt_pk_f32_fp8_e32 v[94:95], v69
	v_cvt_pk_f32_fp8_sdwa v[68:69], v69 src0_sel:WORD_1
	v_pk_fma_f32 v[82:83], v[196:197], v[82:83], v[86:87] op_sel:[1,0,0] op_sel_hi:[1,1,1]
	v_pk_fma_f32 v[86:87], v[196:197], v[88:89], v[90:91] op_sel:[1,0,0] op_sel_hi:[1,1,1]
	v_pk_fma_f32 v[68:69], v[196:197], v[68:69], v[72:73] op_sel:[1,0,0] op_sel_hi:[1,1,1]
	v_cvt_pk_f32_fp8_e32 v[72:73], v70
	v_pk_fma_f32 v[88:89], v[196:197], v[94:95], v[92:93] op_sel:[1,0,0] op_sel_hi:[1,1,1]
	v_cvt_pk_f32_fp8_sdwa v[90:91], v70 src0_sel:WORD_1
	v_cvt_pk_f32_fp8_e32 v[92:93], v71
	v_cvt_pk_f32_fp8_sdwa v[70:71], v71 src0_sel:WORD_1
	v_pk_fma_f32 v[72:73], v[196:197], v[72:73], v[76:77] op_sel:[1,0,0] op_sel_hi:[1,1,1]
	v_pk_fma_f32 v[76:77], v[196:197], v[90:91], v[80:81] op_sel:[1,0,0] op_sel_hi:[1,1,1]
	v_pk_fma_f32 v[80:81], v[196:197], v[92:93], v[84:85] op_sel:[1,0,0] op_sel_hi:[1,1,1]
	v_pk_fma_f32 v[70:71], v[196:197], v[70:71], v[74:75] op_sel:[1,0,0] op_sel_hi:[1,1,1]
	s_nop 1
	v_permlane32_swap_b32_e32 v82, v72
	v_permlane32_swap_b32_e32 v83, v73
	v_permlane32_swap_b32_e32 v86, v76
	v_permlane32_swap_b32_e32 v87, v77
	v_permlane32_swap_b32_e32 v88, v80
	v_permlane32_swap_b32_e32 v89, v81
	v_permlane32_swap_b32_e32 v68, v70
	v_permlane32_swap_b32_e32 v69, v71
	v_pk_add_f32 v[72:73], v[82:83], v[72:73]
	v_pk_add_f32 v[74:75], v[86:87], v[76:77]
	v_pk_add_f32 v[76:77], v[88:89], v[80:81]
	v_pk_add_f32 v[68:69], v[68:69], v[70:71]
	s_nop 1
	v_permlane16_swap_b32_e32 v72, v76
	v_permlane16_swap_b32_e32 v73, v77
	v_permlane16_swap_b32_e32 v74, v68
	v_permlane16_swap_b32_e32 v75, v69
	v_pk_add_f32 v[70:71], v[72:73], v[76:77]
	v_pk_add_f32 v[68:69], v[74:75], v[68:69]
	s_nop 0
	v_cndmask_b32_e64 v73, v71, v69, s[14:15]
	v_cndmask_b32_e64 v72, v70, v68, s[14:15]
	ds_bpermute_b32 v72, v143, v72
	ds_bpermute_b32 v73, v143, v73
	v_cndmask_b32_e64 v69, v69, v71, s[14:15]
	v_cndmask_b32_e64 v68, v68, v70, s[14:15]
	v_add_co_u32_e32 v70, vcc, 0x1000, v188
	s_waitcnt lgkmcnt(0)
	v_pk_add_f32 v[68:69], v[68:69], v[72:73]
	v_addc_co_u32_e32 v71, vcc, 0, v189, vcc
	global_store_dwordx2 v[70:71], v[68:69], off
	v_add_u32_e32 v145, 0x400, v145
	v_lshl_add_u64 v[188:189], v[188:189], 0, s[40:41]
	s_and_b64 vcc, exec, s[28:29]
	s_cbranch_vccnz .LBB0_814

; DI void peer_down2_phase(const Params& p, unsigned char* smem, int layer, const bf16* __restrict__ x1b, u32* ctr) {
;     ...
;   for (int si = 0; si < (stat ? 1 : 8); ++si) {
;     const int slice = stat ? xi : ((xcc + si) & 7);
;     for (;;) {
;       int item;
;       if (stat) { item = it_next; it_next += it_step; }
;       else {
;         __syncthreads();
;         if (tid == 0) *slot = (int)atomicAdd(ctr + slice, 1u);
;         __syncthreads();
;         item = *slot;
;       }
;       if (item >= 256) break;
;       const int t0 = item * 64 + 16 * w;
;       const unsigned char* wbase = wd + slice * 128 + c * 16;
;       {
;         const int* src = ex + (size_t)t0 * 128;
; #pragma unroll
;         for (int i = 0; i < 32; ++i) pl[i * 64 + lane] = src[i * 64 + lane];
;       }
;       const bf16* xb0 = x1b + (size_t)t0 * 1024 + slice * 128 + c * 16;
;       float* pbase = pa + ((size_t)slice * T_TOK + t0) * 128;
;       u32x4 WA[16], WB[16];
;       u32x4 xa0, xa1, xb_0, xb_1;
;       dn2_issue(WA, pl, wbase, grp);
;       xa0 = *(const u32x4*)(xb0); xa1 = *(const u32x4*)(xb0 + 8);
;       for (int tl = 0; tl < 16; tl += 2) {
;         dn2_issue(WB, pl + (tl + 1) * 128, wbase, grp);
;         xb_0 = *(const u32x4*)(xb0 + (size_t)(tl + 1) * 1024); xb_1 = *(const u32x4*)(xb0 + (size_t)(tl + 1) * 1024 + 8);
.LBB0_1514:
	v_cmp_lt_i32_e32 vcc, s44, v2
	s_mov_b64 s[28:29], -1
	s_cbranch_vccnz .LBB0_1505
	v_lshl_add_u32 v2, v2, 6, v225
	v_ashrrev_i32_e32 v3, 31, v2
	v_lshlrev_b64 v[74:75], 9, v[2:3]
	v_lshl_add_u64 v[4:5], s[16:17], 0, v[74:75]
	s_mov_b32 s100, 0x200000
	s_mov_b32 s101, 0
	v_lshl_add_u64 v[252:253], v[4:5], 0, s[100:101]
	v_mov_b32_e32 v248, v161
	v_mov_b32_e32 v249, 0
	v_lshl_add_u64 v[252:253], v[248:249], 7, v[252:253]
	v_lshl_add_u64 v[6:7], v[4:5], 0, v[146:147]
	global_load_dword v36, v[6:7], off
	global_load_dword v37, v[6:7], off offset:256
	v_mov_b32_e32 v157, v147
	v_mov_b32_e32 v159, v147
	v_mov_b32_e32 v163, v147
	v_mov_b32_e32 v165, v147
	v_mov_b32_e32 v167, v147
	v_mov_b32_e32 v169, v147
	v_mov_b32_e32 v171, v147
	v_mov_b32_e32 v173, v147
	v_lshlrev_b64 v[76:77], 11, v[2:3]
	v_lshl_add_u64 v[2:3], v[4:5], 0, v[156:157]
	v_lshl_add_u64 v[8:9], v[4:5], 0, v[158:159]
	v_lshl_add_u64 v[10:11], v[4:5], 0, v[162:163]
	v_lshl_add_u64 v[12:13], v[4:5], 0, v[164:165]
	v_lshl_add_u64 v[14:15], v[4:5], 0, v[166:167]
	v_lshl_add_u64 v[16:17], v[4:5], 0, v[168:169]
	v_lshl_add_u64 v[18:19], v[4:5], 0, v[170:171]
	v_lshl_add_u64 v[20:21], v[4:5], 0, v[172:173]
	global_load_dword v78, v[6:7], off offset:512
	global_load_dword v79, v[6:7], off offset:768
	global_load_dword v80, v[6:7], off offset:1024
	global_load_dword v81, v[6:7], off offset:1280
	global_load_dword v82, v[6:7], off offset:1536
	global_load_dword v83, v[6:7], off offset:1792
	global_load_dword v84, v[6:7], off offset:2048
	global_load_dword v85, v[6:7], off offset:2304
	global_load_dword v86, v[6:7], off offset:2560
	global_load_dword v87, v[6:7], off offset:2816
	global_load_dword v88, v[6:7], off offset:3072
	global_load_dword v89, v[6:7], off offset:3328
	global_load_dword v90, v[6:7], off offset:3584
	global_load_dword v91, v[6:7], off offset:3840
	global_load_dword v92, v[2:3], off
	global_load_dword v93, v[8:9], off
	global_load_dword v94, v[10:11], off
	global_load_dword v95, v[12:13], off
	global_load_dword v96, v[14:15], off
	global_load_dword v97, v[16:17], off
	global_load_dword v98, v[18:19], off
	global_load_dword v99, v[20:21], off
	v_mov_b32_e32 v175, v147
	v_mov_b32_e32 v177, v147
	v_mov_b32_e32 v179, v147
	v_mov_b32_e32 v181, v147
	v_mov_b32_e32 v183, v147
	v_mov_b32_e32 v185, v147
	v_mov_b32_e32 v187, v147
	v_mov_b32_e32 v189, v147
	v_lshl_add_u64 v[22:23], v[4:5], 0, v[174:175]
	v_lshl_add_u64 v[24:25], v[4:5], 0, v[176:177]
	v_lshl_add_u64 v[26:27], v[4:5], 0, v[178:179]
	v_lshl_add_u64 v[28:29], v[4:5], 0, v[180:181]
	v_lshl_add_u64 v[30:31], v[4:5], 0, v[182:183]
	v_lshl_add_u64 v[32:33], v[4:5], 0, v[184:185]
	v_lshl_add_u64 v[34:35], v[4:5], 0, v[186:187]
	v_lshl_add_u64 v[4:5], v[4:5], 0, v[188:189]
	s_waitcnt vmcnt(26)
	v_lshl_add_u64 v[70:71], v[192:193], 0, v[76:77]
	v_cmp_lt_i32_e32 vcc, v221, v218
	s_mov_b32 s40, 0
	v_lshl_add_u64 v[198:199], v[194:195], 0, v[76:77]
	v_lshl_add_u64 v[200:201], v[196:197], 0, v[74:75]
	v_mov_b32_e32 v165, v228
	s_waitcnt vmcnt(22)
	ds_write2st64_b32 v227, v36, v37 offset0:1 offset1:2
	ds_read2_b32 v[2:3], v226 offset0:64 offset1:72
	global_load_dword v100, v[22:23], off
	global_load_dword v101, v[24:25], off
	global_load_dword v102, v[26:27], off
	global_load_dword v103, v[28:29], off
	global_load_dword v104, v[30:31], off
	global_load_dword v105, v[32:33], off
	global_load_dword v106, v[34:35], off
	global_load_dword v107, v[4:5], off
	ds_read2_b32 v[4:5], v226 offset0:80 offset1:88
	ds_read2_b32 v[18:19], v226 offset0:96 offset1:104
	s_waitcnt lgkmcnt(2)
	v_ashrrev_i32_e32 v7, 31, v2
	v_mov_b32_e32 v6, v2
	v_ashrrev_i32_e32 v9, 31, v3
	v_mov_b32_e32 v8, v3
	s_waitcnt lgkmcnt(1)
	v_ashrrev_i32_e32 v3, 31, v4
	v_mov_b32_e32 v2, v4
	v_ashrrev_i32_e32 v11, 31, v5
	v_mov_b32_e32 v10, v5
	v_lshlrev_b64 v[4:5], 10, v[6:7]
	v_lshlrev_b64 v[6:7], 10, v[8:9]
	v_lshlrev_b64 v[2:3], 10, v[2:3]
	v_lshlrev_b64 v[8:9], 10, v[10:11]
	v_lshl_add_u64 v[20:21], v[190:191], 0, v[4:5]
	v_lshl_add_u64 v[22:23], v[190:191], 0, v[6:7]
	v_lshl_add_u64 v[24:25], v[190:191], 0, v[2:3]
	v_lshl_add_u64 v[26:27], v[190:191], 0, v[8:9]
	global_load_dwordx4 v[2:5], v[20:21], off
	global_load_dwordx4 v[6:9], v[22:23], off
	global_load_dwordx4 v[10:13], v[24:25], off
	global_load_dwordx4 v[14:17], v[26:27], off
	ds_read2_b32 v[28:29], v226 offset0:112 offset1:120
	s_waitcnt lgkmcnt(1)
	v_ashrrev_i32_e32 v21, 31, v18
	v_mov_b32_e32 v20, v18
	v_lshlrev_b64 v[20:21], 10, v[20:21]
	v_lshl_add_u64 v[26:27], v[190:191], 0, v[20:21]
	v_ashrrev_i32_e32 v21, 31, v19
	v_mov_b32_e32 v20, v19
	v_lshlrev_b64 v[18:19], 10, v[20:21]
	v_lshl_add_u64 v[30:31], v[190:191], 0, v[18:19]
	global_load_dwordx4 v[18:21], v[26:27], off
	global_load_dwordx4 v[22:25], v[30:31], off
	s_waitcnt lgkmcnt(0)
	v_ashrrev_i32_e32 v27, 31, v28
	v_mov_b32_e32 v26, v28
	v_lshlrev_b64 v[26:27], 10, v[26:27]
	v_lshl_add_u64 v[34:35], v[190:191], 0, v[26:27]
	v_ashrrev_i32_e32 v27, 31, v29
	v_mov_b32_e32 v26, v29
	v_lshlrev_b64 v[26:27], 10, v[26:27]
	ds_read2_b32 v[36:37], v226 offset0:128 offset1:136
	v_lshl_add_u64 v[38:39], v[190:191], 0, v[26:27]
	global_load_dwordx4 v[26:29], v[34:35], off
	global_load_dwordx4 v[30:33], v[38:39], off
	ds_read2_b32 v[42:43], v226 offset0:144 offset1:152
	s_waitcnt lgkmcnt(1)
	v_ashrrev_i32_e32 v35, 31, v36
	v_mov_b32_e32 v34, v36
	v_ashrrev_i32_e32 v39, 31, v37
	v_mov_b32_e32 v38, v37
	s_waitcnt lgkmcnt(0)
; DI float bflo(u32 u) { return __uint_as_float(u << 16); }
; DI float bfhi(u32 u) { return __uint_as_float(u & 0xffff0000u); }
; DI void dn2_math(const u32x4 (&W)[16], u32x4 x0, u32x4 x1, float* __restrict__ parow, int lane) {
;   f2 xf[8];
; #pragma unroll
;   for (int q = 0; q < 4; ++q) { xf[q] = f2{bflo(x0[q]), bfhi(x0[q])}; xf[4 + q] = f2{bflo(x1[q]), bfhi(x1[q])}; }
;   float pv[16];
; #pragma unroll
;   for (int j = 0; j < 16; ++j) {
;     f2 s2 = {0.f, 0.f};
; #pragma unroll
;     for (int d = 0; d < 4; ++d) {
;       f2 lo = __builtin_amdgcn_cvt_pk_f32_fp8((int)W[j][d], false);
;       f2 hi = __builtin_amdgcn_cvt_pk_f32_fp8((int)W[j][d], true);
;       s2 = lo * xf[2 * d] + s2;
;       s2 = hi * xf[2 * d + 1] + s2;
;     }
;     pv[j] = s2.x + s2.y;
;   }
; DI void peer_down2_phase(const Params& p, unsigned char* smem, int layer, const bf16* __restrict__ x1b, u32* ctr) {
;     ...
;       {
;         const int* src = ex + (size_t)t0 * 128;
; #pragma unroll
;         for (int i = 0; i < 32; ++i) pl[i * 64 + lane] = src[i * 64 + lane];
;       }
;       const bf16* xb0 = x1b + (size_t)t0 * 1024 + slice * 128 + c * 16;
;       float* pbase = pa + ((size_t)slice * T_TOK + t0) * 128;
;       u32x4 WA[16], WB[16];
;       u32x4 xa0, xa1, xb_0, xb_1;
;       dn2_issue(WA, pl, wbase, grp);
;       xa0 = *(const u32x4*)(xb0); xa1 = *(const u32x4*)(xb0 + 8);
;       for (int tl = 0; tl < 16; tl += 2) {
;         dn2_issue(WB, pl + (tl + 1) * 128, wbase, grp);
;         xb_0 = *(const u32x4*)(xb0 + (size_t)(tl + 1) * 1024); xb_1 = *(const u32x4*)(xb0 + (size_t)(tl + 1) * 1024 + 8);
;         __builtin_amdgcn_sched_barrier(0);
;         dn2_math(WA, xa0, xa1, pbase + (size_t)tl * 128, lane);
;         __builtin_amdgcn_sched_barrier(0);
;         if (tl + 2 < 16) {
;           dn2_issue(WA, pl + (tl + 2) * 128, wbase, grp);
;           xa0 = *(const u32x4*)(xb0 + (size_t)(tl + 2) * 1024); xa1 = *(const u32x4*)(xb0 + (size_t)(tl + 2) * 1024 + 8);
;         }
;         __builtin_amdgcn_sched_barrier(0);
;         dn2_math(WB, xb_0, xb_1, pbase + (size_t)(tl + 1) * 128, lane);
	v_ashrrev_i32_e32 v45, 31, v42
	v_mov_b32_e32 v44, v42
	v_ashrrev_i32_e32 v47, 31, v43
	v_mov_b32_e32 v46, v43
	v_lshlrev_b64 v[34:35], 10, v[34:35]
	v_lshlrev_b64 v[36:37], 10, v[38:39]
	v_lshlrev_b64 v[44:45], 10, v[44:45]
	v_lshlrev_b64 v[42:43], 10, v[46:47]
	v_lshl_add_u64 v[34:35], v[190:191], 0, v[34:35]
	v_lshl_add_u64 v[38:39], v[190:191], 0, v[36:37]
	v_lshl_add_u64 v[44:45], v[190:191], 0, v[44:45]
	v_lshl_add_u64 v[46:47], v[190:191], 0, v[42:43]
	global_load_dwordx4 v[34:37], v[34:35], off
	s_nop 0
	global_load_dwordx4 v[38:41], v[38:39], off
	ds_read2_b32 v[50:51], v226 offset0:160 offset1:168
	global_load_dwordx4 v[42:45], v[44:45], off
	s_nop 0
	global_load_dwordx4 v[46:49], v[46:47], off
	ds_read2_b32 v[58:59], v226 offset0:176 offset1:184
	s_waitcnt lgkmcnt(1)
	v_ashrrev_i32_e32 v53, 31, v50
	v_mov_b32_e32 v52, v50
	v_ashrrev_i32_e32 v55, 31, v51
	v_mov_b32_e32 v54, v51
	s_waitcnt lgkmcnt(0)
	v_ashrrev_i32_e32 v61, 31, v58
	v_mov_b32_e32 v60, v58
	v_ashrrev_i32_e32 v63, 31, v59
	v_mov_b32_e32 v62, v59
	v_lshlrev_b64 v[52:53], 10, v[52:53]
	v_lshlrev_b64 v[50:51], 10, v[54:55]
	v_lshlrev_b64 v[60:61], 10, v[60:61]
	v_lshlrev_b64 v[58:59], 10, v[62:63]
	v_lshl_add_u64 v[52:53], v[190:191], 0, v[52:53]
	v_lshl_add_u64 v[54:55], v[190:191], 0, v[50:51]
	v_lshl_add_u64 v[60:61], v[190:191], 0, v[60:61]
	v_lshl_add_u64 v[62:63], v[190:191], 0, v[58:59]
	global_load_dwordx4 v[50:53], v[52:53], off
	s_nop 0
	global_load_dwordx4 v[54:57], v[54:55], off
	s_nop 0
	global_load_dwordx4 v[58:61], v[60:61], off
	s_nop 0
	global_load_dwordx4 v[62:65], v[62:63], off
	s_nop 0
	global_load_dwordx4 v[66:69], v[70:71], off offset:16
	s_nop 0
	global_load_dwordx4 v[70:73], v[70:71], off
	s_waitcnt vmcnt(46)
	ds_write2st64_b32 v227, v78, v79 offset0:3 offset1:4
	s_waitcnt vmcnt(44)
	ds_write2st64_b32 v227, v80, v81 offset0:5 offset1:6
	s_waitcnt vmcnt(42)
	ds_write2st64_b32 v227, v82, v83 offset0:7 offset1:8
	s_waitcnt vmcnt(40)
	ds_write2st64_b32 v227, v84, v85 offset0:9 offset1:10
	s_waitcnt vmcnt(38)
	ds_write2st64_b32 v227, v86, v87 offset0:11 offset1:12
	s_waitcnt vmcnt(36)
	ds_write2st64_b32 v227, v88, v89 offset0:13 offset1:14
	s_waitcnt vmcnt(34)
	ds_write2st64_b32 v227, v90, v91 offset0:15 offset1:16
	s_waitcnt vmcnt(32)
	ds_write2st64_b32 v227, v92, v93 offset0:17 offset1:18
	s_waitcnt vmcnt(30)
	ds_write2st64_b32 v227, v94, v95 offset0:19 offset1:20
	s_waitcnt vmcnt(28)
	ds_write2st64_b32 v227, v96, v97 offset0:21 offset1:22
	s_waitcnt vmcnt(26)
	ds_write2st64_b32 v227, v98, v99 offset0:23 offset1:24
	s_waitcnt vmcnt(24)
	ds_write2st64_b32 v227, v100, v101 offset0:25 offset1:26
	s_waitcnt vmcnt(22)
	ds_write2st64_b32 v227, v102, v103 offset0:27 offset1:28
	s_waitcnt vmcnt(20)
	ds_write2st64_b32 v227, v104, v105 offset0:29 offset1:30
	s_waitcnt vmcnt(18)
	ds_write2st64_b32 v227, v106, v107 offset0:31 offset1:32
	v_cndmask_b32_e32 v78, v161, v221, vcc
	v_cmp_lt_i32_e32 vcc, v220, v218
	v_lshlrev_b32_e32 v157, 2, v78
	s_nop 0
	v_cndmask_b32_e32 v78, v161, v220, vcc
	v_cmp_lt_i32_e32 vcc, v219, v218
	v_lshlrev_b32_e32 v159, 2, v78
	s_nop 0
	v_cndmask_b32_e32 v78, v161, v219, vcc
	v_lshlrev_b32_e32 v163, 2, v78
	s_branch .LBB0_1517
.LBB0_1516:
	s_add_i32 s40, s40, 2
	s_cmp_lg_u32 s40, 8
	s_cbranch_scc1 .Lmy_lpf_1516
	global_load_dword v254, v[252:253], off
.Lmy_lpf_1516:
	s_waitcnt vmcnt(19)
	v_cvt_pk_f32_fp8_e32 v[210:211], v134
	v_cvt_pk_f32_fp8_sdwa v[212:213], v134 src0_sel:WORD_1
	v_cvt_pk_f32_fp8_e32 v[214:215], v135
	s_waitcnt vmcnt(2)
	v_lshlrev_b32_e32 v204, 16, v142
	v_and_b32_e32 v205, 0xffff0000, v142
	v_cvt_pk_f32_fp8_sdwa v[134:135], v135 src0_sel:WORD_1
	v_lshlrev_b32_e32 v206, 16, v143
	v_and_b32_e32 v207, 0xffff0000, v143
	v_pk_fma_f32 v[210:211], v[210:211], v[204:205], 0 op_sel_hi:[1,1,0]
	v_lshlrev_b32_e32 v208, 16, v144
	v_and_b32_e32 v209, 0xffff0000, v144
	v_pk_fma_f32 v[210:211], v[212:213], v[206:207], v[210:211]
	v_lshlrev_b32_e32 v144, 16, v145
	v_and_b32_e32 v145, 0xffff0000, v145
	v_pk_fma_f32 v[210:211], v[214:215], v[208:209], v[210:211]
	v_cvt_pk_f32_fp8_sdwa v[212:213], v136 src0_sel:WORD_1
	v_pk_fma_f32 v[134:135], v[134:135], v[144:145], v[210:211]
	v_cvt_pk_f32_fp8_e32 v[210:211], v136
	v_cvt_pk_f32_fp8_e32 v[214:215], v137
	v_lshlrev_b32_e32 v202, 16, v138
	v_and_b32_e32 v203, 0xffff0000, v138
	v_cvt_pk_f32_fp8_sdwa v[136:137], v137 src0_sel:WORD_1
	v_lshlrev_b32_e32 v138, 16, v139
	v_and_b32_e32 v139, 0xffff0000, v139
	v_pk_fma_f32 v[134:135], v[210:211], v[202:203], v[134:135]
	v_lshlrev_b32_e32 v142, 16, v140
	v_and_b32_e32 v143, 0xffff0000, v140
	v_pk_fma_f32 v[134:135], v[212:213], v[138:139], v[134:135]
	v_lshlrev_b32_e32 v140, 16, v141
	v_and_b32_e32 v141, 0xffff0000, v141
	v_pk_fma_f32 v[134:135], v[214:215], v[142:143], v[134:135]
	v_cvt_pk_f32_fp8_e32 v[210:211], v131
	v_pk_fma_f32 v[134:135], v[136:137], v[140:141], v[134:135]
	v_cvt_pk_f32_fp8_sdwa v[136:137], v130 src0_sel:WORD_1
	v_add_f32_e32 v167, v134, v135
	v_cvt_pk_f32_fp8_e32 v[134:135], v130
	v_cvt_pk_f32_fp8_sdwa v[130:131], v131 src0_sel:WORD_1
	v_pk_fma_f32 v[134:135], v[134:135], v[204:205], 0 op_sel_hi:[1,1,0]
	s_nop 0
	v_pk_fma_f32 v[134:135], v[136:137], v[206:207], v[134:135]
	v_cvt_pk_f32_fp8_sdwa v[136:137], v132 src0_sel:WORD_1
	v_pk_fma_f32 v[134:135], v[210:211], v[208:209], v[134:135]
	v_cvt_pk_f32_fp8_e32 v[210:211], v133
	v_pk_fma_f32 v[130:131], v[130:131], v[144:145], v[134:135]
	v_cvt_pk_f32_fp8_e32 v[134:135], v132
	v_cvt_pk_f32_fp8_sdwa v[132:133], v133 src0_sel:WORD_1
	v_pk_fma_f32 v[130:131], v[134:135], v[202:203], v[130:131]
	s_nop 0
	v_pk_fma_f32 v[130:131], v[136:137], v[138:139], v[130:131]
; DI float bflo(u32 u) { return __uint_as_float(u << 16); }
; DI float bfhi(u32 u) { return __uint_as_float(u & 0xffff0000u); }
; DI void dn2_math(const u32x4 (&W)[16], u32x4 x0, u32x4 x1, float* __restrict__ parow, int lane) {
;   f2 xf[8];
; #pragma unroll
;   for (int q = 0; q < 4; ++q) { xf[q] = f2{bflo(x0[q]), bfhi(x0[q])}; xf[4 + q] = f2{bflo(x1[q]), bfhi(x1[q])}; }
;   float pv[16];
; #pragma unroll
;   for (int j = 0; j < 16; ++j) {
;     f2 s2 = {0.f, 0.f};
; #pragma unroll
;     for (int d = 0; d < 4; ++d) {
;       f2 lo = __builtin_amdgcn_cvt_pk_f32_fp8((int)W[j][d], false);
;       f2 hi = __builtin_amdgcn_cvt_pk_f32_fp8((int)W[j][d], true);
;       s2 = lo * xf[2 * d] + s2;
;       s2 = hi * xf[2 * d + 1] + s2;
;     }
;     pv[j] = s2.x + s2.y;
;   }
	v_cvt_pk_f32_fp8_e32 v[134:135], v127
	v_pk_fma_f32 v[130:131], v[210:211], v[142:143], v[130:131]
	s_nop 0
	v_pk_fma_f32 v[130:131], v[132:133], v[140:141], v[130:131]
	v_cvt_pk_f32_fp8_sdwa v[132:133], v126 src0_sel:WORD_1
	v_add_f32_e32 v136, v130, v131
	v_cvt_pk_f32_fp8_e32 v[130:131], v126
	v_cvt_pk_f32_fp8_sdwa v[126:127], v127 src0_sel:WORD_1
	v_pk_fma_f32 v[130:131], v[130:131], v[204:205], 0 op_sel_hi:[1,1,0]
	s_nop 0
	v_pk_fma_f32 v[130:131], v[132:133], v[206:207], v[130:131]
	v_cvt_pk_f32_fp8_sdwa v[132:133], v128 src0_sel:WORD_1
	v_pk_fma_f32 v[130:131], v[134:135], v[208:209], v[130:131]
	v_cvt_pk_f32_fp8_e32 v[134:135], v129
	v_pk_fma_f32 v[126:127], v[126:127], v[144:145], v[130:131]
	v_cvt_pk_f32_fp8_e32 v[130:131], v128
	v_cvt_pk_f32_fp8_sdwa v[128:129], v129 src0_sel:WORD_1
	v_pk_fma_f32 v[126:127], v[130:131], v[202:203], v[126:127]
	s_nop 0
	v_pk_fma_f32 v[126:127], v[132:133], v[138:139], v[126:127]
	v_cvt_pk_f32_fp8_e32 v[130:131], v123
	v_pk_fma_f32 v[126:127], v[134:135], v[142:143], v[126:127]
	s_nop 0
	v_pk_fma_f32 v[126:127], v[128:129], v[140:141], v[126:127]
	v_cvt_pk_f32_fp8_sdwa v[128:129], v122 src0_sel:WORD_1
	v_add_f32_e32 v132, v126, v127
	v_cvt_pk_f32_fp8_e32 v[126:127], v122
	v_cvt_pk_f32_fp8_sdwa v[122:123], v123 src0_sel:WORD_1
	v_pk_fma_f32 v[126:127], v[126:127], v[204:205], 0 op_sel_hi:[1,1,0]
	s_nop 0
	v_pk_fma_f32 v[126:127], v[128:129], v[206:207], v[126:127]
	v_cvt_pk_f32_fp8_sdwa v[128:129], v124 src0_sel:WORD_1
	v_pk_fma_f32 v[126:127], v[130:131], v[208:209], v[126:127]
	v_cvt_pk_f32_fp8_e32 v[130:131], v125
	v_pk_fma_f32 v[122:123], v[122:123], v[144:145], v[126:127]
	v_cvt_pk_f32_fp8_e32 v[126:127], v124
	v_cvt_pk_f32_fp8_sdwa v[124:125], v125 src0_sel:WORD_1
	v_pk_fma_f32 v[122:123], v[126:127], v[202:203], v[122:123]
	s_nop 0
	v_pk_fma_f32 v[122:123], v[128:129], v[138:139], v[122:123]
	v_cvt_pk_f32_fp8_e32 v[126:127], v119
	v_pk_fma_f32 v[122:123], v[130:131], v[142:143], v[122:123]
	s_nop 0
	v_pk_fma_f32 v[122:123], v[124:125], v[140:141], v[122:123]
	v_cvt_pk_f32_fp8_sdwa v[124:125], v118 src0_sel:WORD_1
	v_add_f32_e32 v128, v122, v123
	v_cvt_pk_f32_fp8_e32 v[122:123], v118
	v_cvt_pk_f32_fp8_sdwa v[118:119], v119 src0_sel:WORD_1
	v_pk_fma_f32 v[122:123], v[122:123], v[204:205], 0 op_sel_hi:[1,1,0]
	s_nop 0
	v_pk_fma_f32 v[122:123], v[124:125], v[206:207], v[122:123]
	v_cvt_pk_f32_fp8_sdwa v[124:125], v120 src0_sel:WORD_1
	v_pk_fma_f32 v[122:123], v[126:127], v[208:209], v[122:123]
	v_cvt_pk_f32_fp8_e32 v[126:127], v121
	v_pk_fma_f32 v[118:119], v[118:119], v[144:145], v[122:123]
	v_cvt_pk_f32_fp8_e32 v[122:123], v120
	v_cvt_pk_f32_fp8_sdwa v[120:121], v121 src0_sel:WORD_1
	v_pk_fma_f32 v[118:119], v[122:123], v[202:203], v[118:119]
	s_nop 0
	v_pk_fma_f32 v[118:119], v[124:125], v[138:139], v[118:119]
	v_cvt_pk_f32_fp8_e32 v[122:123], v115
	v_pk_fma_f32 v[118:119], v[126:127], v[142:143], v[118:119]
	s_nop 0
	v_pk_fma_f32 v[118:119], v[120:121], v[140:141], v[118:119]
	v_cvt_pk_f32_fp8_sdwa v[120:121], v114 src0_sel:WORD_1
	v_add_f32_e32 v124, v118, v119
	v_cvt_pk_f32_fp8_e32 v[118:119], v114
	v_cvt_pk_f32_fp8_sdwa v[114:115], v115 src0_sel:WORD_1
	v_pk_fma_f32 v[118:119], v[118:119], v[204:205], 0 op_sel_hi:[1,1,0]
	s_nop 0
	v_pk_fma_f32 v[118:119], v[120:121], v[206:207], v[118:119]
	v_cvt_pk_f32_fp8_sdwa v[120:121], v116 src0_sel:WORD_1
	v_pk_fma_f32 v[118:119], v[122:123], v[208:209], v[118:119]
	v_cvt_pk_f32_fp8_e32 v[122:123], v117
	v_pk_fma_f32 v[114:115], v[114:115], v[144:145], v[118:119]
	v_cvt_pk_f32_fp8_e32 v[118:119], v116
	v_cvt_pk_f32_fp8_sdwa v[116:117], v117 src0_sel:WORD_1
	v_pk_fma_f32 v[114:115], v[118:119], v[202:203], v[114:115]
	s_nop 0
	v_pk_fma_f32 v[114:115], v[120:121], v[138:139], v[114:115]
	v_cvt_pk_f32_fp8_e32 v[118:119], v111
	v_pk_fma_f32 v[114:115], v[122:123], v[142:143], v[114:115]
	s_nop 0
	v_pk_fma_f32 v[114:115], v[116:117], v[140:141], v[114:115]
	v_cvt_pk_f32_fp8_sdwa v[116:117], v110 src0_sel:WORD_1
	v_add_f32_e32 v120, v114, v115
	v_cvt_pk_f32_fp8_e32 v[114:115], v110
	v_cvt_pk_f32_fp8_sdwa v[110:111], v111 src0_sel:WORD_1
	v_pk_fma_f32 v[114:115], v[114:115], v[204:205], 0 op_sel_hi:[1,1,0]
	s_nop 0
	v_pk_fma_f32 v[114:115], v[116:117], v[206:207], v[114:115]
	v_cvt_pk_f32_fp8_sdwa v[116:117], v112 src0_sel:WORD_1
	v_pk_fma_f32 v[114:115], v[118:119], v[208:209], v[114:115]
	v_cvt_pk_f32_fp8_e32 v[118:119], v113
	v_pk_fma_f32 v[110:111], v[110:111], v[144:145], v[114:115]
	v_cvt_pk_f32_fp8_e32 v[114:115], v112
	v_cvt_pk_f32_fp8_sdwa v[112:113], v113 src0_sel:WORD_1
	v_pk_fma_f32 v[110:111], v[114:115], v[202:203], v[110:111]
	s_nop 0
	v_pk_fma_f32 v[110:111], v[116:117], v[138:139], v[110:111]
	v_cvt_pk_f32_fp8_e32 v[114:115], v107
	v_pk_fma_f32 v[110:111], v[118:119], v[142:143], v[110:111]
	s_nop 0
	v_pk_fma_f32 v[110:111], v[112:113], v[140:141], v[110:111]
	v_cvt_pk_f32_fp8_sdwa v[112:113], v106 src0_sel:WORD_1
	v_add_f32_e32 v116, v110, v111
	v_cvt_pk_f32_fp8_e32 v[110:111], v106
	v_cvt_pk_f32_fp8_sdwa v[106:107], v107 src0_sel:WORD_1
	v_pk_fma_f32 v[110:111], v[110:111], v[204:205], 0 op_sel_hi:[1,1,0]
	s_nop 0
	v_pk_fma_f32 v[110:111], v[112:113], v[206:207], v[110:111]
	v_cvt_pk_f32_fp8_sdwa v[112:113], v108 src0_sel:WORD_1
	v_pk_fma_f32 v[110:111], v[114:115], v[208:209], v[110:111]
	v_cvt_pk_f32_fp8_e32 v[114:115], v109
	v_pk_fma_f32 v[106:107], v[106:107], v[144:145], v[110:111]
	v_cvt_pk_f32_fp8_e32 v[110:111], v108
	v_cvt_pk_f32_fp8_sdwa v[108:109], v109 src0_sel:WORD_1
	v_pk_fma_f32 v[106:107], v[110:111], v[202:203], v[106:107]
	s_nop 0
	v_pk_fma_f32 v[106:107], v[112:113], v[138:139], v[106:107]
	v_cvt_pk_f32_fp8_e32 v[110:111], v103
; DI void dn2_math(const u32x4 (&W)[16], u32x4 x0, u32x4 x1, float* __restrict__ parow, int lane) {
;     ...
;   for (int j = 0; j < 16; ++j) {
;     f2 s2 = {0.f, 0.f};
; #pragma unroll
;     for (int d = 0; d < 4; ++d) {
;       f2 lo = __builtin_amdgcn_cvt_pk_f32_fp8((int)W[j][d], false);
;       f2 hi = __builtin_amdgcn_cvt_pk_f32_fp8((int)W[j][d], true);
;       s2 = lo * xf[2 * d] + s2;
;       s2 = hi * xf[2 * d + 1] + s2;
;     }
;     pv[j] = s2.x + s2.y;
	v_pk_fma_f32 v[106:107], v[114:115], v[142:143], v[106:107]
	s_nop 0
	v_pk_fma_f32 v[106:107], v[108:109], v[140:141], v[106:107]
	v_cvt_pk_f32_fp8_sdwa v[108:109], v102 src0_sel:WORD_1
	v_add_f32_e32 v112, v106, v107
	v_cvt_pk_f32_fp8_e32 v[106:107], v102
	v_cvt_pk_f32_fp8_sdwa v[102:103], v103 src0_sel:WORD_1
	v_pk_fma_f32 v[106:107], v[106:107], v[204:205], 0 op_sel_hi:[1,1,0]
	s_nop 0
	v_pk_fma_f32 v[106:107], v[108:109], v[206:207], v[106:107]
	v_cvt_pk_f32_fp8_sdwa v[108:109], v104 src0_sel:WORD_1
	v_pk_fma_f32 v[106:107], v[110:111], v[208:209], v[106:107]
	v_cvt_pk_f32_fp8_e32 v[110:111], v105
	v_pk_fma_f32 v[102:103], v[102:103], v[144:145], v[106:107]
	v_cvt_pk_f32_fp8_e32 v[106:107], v104
	v_cvt_pk_f32_fp8_sdwa v[104:105], v105 src0_sel:WORD_1
	v_pk_fma_f32 v[102:103], v[106:107], v[202:203], v[102:103]
	s_nop 0
	v_pk_fma_f32 v[102:103], v[108:109], v[138:139], v[102:103]
	v_cvt_pk_f32_fp8_e32 v[106:107], v99
	v_pk_fma_f32 v[102:103], v[110:111], v[142:143], v[102:103]
	s_nop 0
	v_pk_fma_f32 v[102:103], v[104:105], v[140:141], v[102:103]
	v_cvt_pk_f32_fp8_sdwa v[104:105], v98 src0_sel:WORD_1
	v_add_f32_e32 v108, v102, v103
	v_cvt_pk_f32_fp8_e32 v[102:103], v98
	v_cvt_pk_f32_fp8_sdwa v[98:99], v99 src0_sel:WORD_1
	v_pk_fma_f32 v[102:103], v[102:103], v[204:205], 0 op_sel_hi:[1,1,0]
	s_nop 0
	v_pk_fma_f32 v[102:103], v[104:105], v[206:207], v[102:103]
	v_cvt_pk_f32_fp8_sdwa v[104:105], v100 src0_sel:WORD_1
	v_pk_fma_f32 v[102:103], v[106:107], v[208:209], v[102:103]
	v_cvt_pk_f32_fp8_e32 v[106:107], v101
	v_pk_fma_f32 v[98:99], v[98:99], v[144:145], v[102:103]
	v_cvt_pk_f32_fp8_e32 v[102:103], v100
	v_cvt_pk_f32_fp8_sdwa v[100:101], v101 src0_sel:WORD_1
	v_pk_fma_f32 v[98:99], v[102:103], v[202:203], v[98:99]
	s_nop 0
	v_pk_fma_f32 v[98:99], v[104:105], v[138:139], v[98:99]
	v_cvt_pk_f32_fp8_e32 v[102:103], v95
	v_pk_fma_f32 v[98:99], v[106:107], v[142:143], v[98:99]
	s_nop 0
	v_pk_fma_f32 v[98:99], v[100:101], v[140:141], v[98:99]
	v_cvt_pk_f32_fp8_sdwa v[100:101], v94 src0_sel:WORD_1
	v_add_f32_e32 v104, v98, v99
	v_cvt_pk_f32_fp8_e32 v[98:99], v94
	v_cvt_pk_f32_fp8_sdwa v[94:95], v95 src0_sel:WORD_1
	v_pk_fma_f32 v[98:99], v[98:99], v[204:205], 0 op_sel_hi:[1,1,0]
	s_nop 0
	v_pk_fma_f32 v[98:99], v[100:101], v[206:207], v[98:99]
	v_cvt_pk_f32_fp8_sdwa v[100:101], v96 src0_sel:WORD_1
	v_pk_fma_f32 v[98:99], v[102:103], v[208:209], v[98:99]
	v_cvt_pk_f32_fp8_e32 v[102:103], v97
	v_pk_fma_f32 v[94:95], v[94:95], v[144:145], v[98:99]
	v_cvt_pk_f32_fp8_e32 v[98:99], v96
	v_cvt_pk_f32_fp8_sdwa v[96:97], v97 src0_sel:WORD_1
	v_pk_fma_f32 v[94:95], v[98:99], v[202:203], v[94:95]
	s_nop 0
	v_pk_fma_f32 v[94:95], v[100:101], v[138:139], v[94:95]
	v_cvt_pk_f32_fp8_e32 v[98:99], v91
	v_pk_fma_f32 v[94:95], v[102:103], v[142:143], v[94:95]
	s_nop 0
	v_pk_fma_f32 v[94:95], v[96:97], v[140:141], v[94:95]
	v_cvt_pk_f32_fp8_sdwa v[96:97], v90 src0_sel:WORD_1
	v_add_f32_e32 v100, v94, v95
	v_cvt_pk_f32_fp8_e32 v[94:95], v90
	v_cvt_pk_f32_fp8_sdwa v[90:91], v91 src0_sel:WORD_1
	v_pk_fma_f32 v[94:95], v[94:95], v[204:205], 0 op_sel_hi:[1,1,0]
	s_nop 0
	v_pk_fma_f32 v[94:95], v[96:97], v[206:207], v[94:95]
	v_cvt_pk_f32_fp8_sdwa v[96:97], v92 src0_sel:WORD_1
	v_pk_fma_f32 v[94:95], v[98:99], v[208:209], v[94:95]
	v_cvt_pk_f32_fp8_e32 v[98:99], v93
	v_pk_fma_f32 v[90:91], v[90:91], v[144:145], v[94:95]
	v_cvt_pk_f32_fp8_e32 v[94:95], v92
	v_cvt_pk_f32_fp8_sdwa v[92:93], v93 src0_sel:WORD_1
	v_pk_fma_f32 v[90:91], v[94:95], v[202:203], v[90:91]
	s_nop 0
	v_pk_fma_f32 v[90:91], v[96:97], v[138:139], v[90:91]
	v_cvt_pk_f32_fp8_e32 v[94:95], v87
	v_pk_fma_f32 v[90:91], v[98:99], v[142:143], v[90:91]
	s_nop 0
	v_pk_fma_f32 v[90:91], v[92:93], v[140:141], v[90:91]
	v_cvt_pk_f32_fp8_sdwa v[92:93], v86 src0_sel:WORD_1
	v_add_f32_e32 v96, v90, v91
	v_cvt_pk_f32_fp8_e32 v[90:91], v86
	v_cvt_pk_f32_fp8_sdwa v[86:87], v87 src0_sel:WORD_1
	v_pk_fma_f32 v[90:91], v[90:91], v[204:205], 0 op_sel_hi:[1,1,0]
	s_nop 0
	v_pk_fma_f32 v[90:91], v[92:93], v[206:207], v[90:91]
	v_cvt_pk_f32_fp8_sdwa v[92:93], v88 src0_sel:WORD_1
	v_pk_fma_f32 v[90:91], v[94:95], v[208:209], v[90:91]
	v_cvt_pk_f32_fp8_e32 v[94:95], v89
	v_pk_fma_f32 v[86:87], v[86:87], v[144:145], v[90:91]
	v_cvt_pk_f32_fp8_e32 v[90:91], v88
	v_cvt_pk_f32_fp8_sdwa v[88:89], v89 src0_sel:WORD_1
	v_pk_fma_f32 v[86:87], v[90:91], v[202:203], v[86:87]
	s_nop 0
	v_pk_fma_f32 v[86:87], v[92:93], v[138:139], v[86:87]
	v_cvt_pk_f32_fp8_e32 v[90:91], v83
	v_pk_fma_f32 v[86:87], v[94:95], v[142:143], v[86:87]
	s_nop 0
	v_pk_fma_f32 v[86:87], v[88:89], v[140:141], v[86:87]
	v_cvt_pk_f32_fp8_sdwa v[88:89], v82 src0_sel:WORD_1
	v_add_f32_e32 v92, v86, v87
	v_cvt_pk_f32_fp8_e32 v[86:87], v82
	v_cvt_pk_f32_fp8_sdwa v[82:83], v83 src0_sel:WORD_1
	v_pk_fma_f32 v[86:87], v[86:87], v[204:205], 0 op_sel_hi:[1,1,0]
	s_nop 0
	v_pk_fma_f32 v[86:87], v[88:89], v[206:207], v[86:87]
; DI void dn2_math(const u32x4 (&W)[16], u32x4 x0, u32x4 x1, float* __restrict__ parow, int lane) {
;     ...
;     pv[j] = s2.x + s2.y;
;   }
;   const bool b2 = lane & 4, b1 = lane & 2, b0 = lane & 1;
;   float q8[8];
; #pragma unroll
;   for (int i = 0; i < 8; ++i) { float snd = b2 ? pv[i] : pv[i + 8]; float kp = b2 ? pv[i + 8] : pv[i]; q8[i] = kp + __shfl_xor(snd, 4); }
;   float q4[4];
; #pragma unroll
;   for (int i = 0; i < 4; ++i) { float snd = b1 ? q8[i] : q8[i + 4]; float kp = b1 ? q8[i + 4] : q8[i]; q4[i] = kp + __shfl_xor(snd, 2); }
;   float r2[2];
; #pragma unroll
;   for (int i = 0; i < 2; ++i) { float snd = b0 ? q4[i] : q4[i + 2]; float kp = b0 ? q4[i + 2] : q4[i]; r2[i] = kp + __shfl_xor(snd, 1); }
;   const int j0 = (b0 ? 2 : 0) + (b1 ? 4 : 0) + (b2 ? 8 : 0);
;   const int grp = lane >> 3;
;   parow[8 * j0 + grp] = r2[0];
;   parow[8 * (j0 + 1) + grp] = r2[1];
	v_cvt_pk_f32_fp8_sdwa v[88:89], v84 src0_sel:WORD_1
	v_pk_fma_f32 v[86:87], v[90:91], v[208:209], v[86:87]
	v_cvt_pk_f32_fp8_e32 v[90:91], v85
	v_pk_fma_f32 v[82:83], v[82:83], v[144:145], v[86:87]
	v_cvt_pk_f32_fp8_e32 v[86:87], v84
	v_cvt_pk_f32_fp8_sdwa v[84:85], v85 src0_sel:WORD_1
	v_pk_fma_f32 v[82:83], v[86:87], v[202:203], v[82:83]
	s_nop 0
	v_pk_fma_f32 v[82:83], v[88:89], v[138:139], v[82:83]
	v_cvt_pk_f32_fp8_e32 v[86:87], v79
	v_pk_fma_f32 v[82:83], v[90:91], v[142:143], v[82:83]
	s_nop 0
	v_pk_fma_f32 v[82:83], v[84:85], v[140:141], v[82:83]
	v_cvt_pk_f32_fp8_sdwa v[84:85], v78 src0_sel:WORD_1
	v_add_f32_e32 v88, v82, v83
	v_cvt_pk_f32_fp8_e32 v[82:83], v78
	v_cvt_pk_f32_fp8_sdwa v[78:79], v79 src0_sel:WORD_1
	v_pk_fma_f32 v[82:83], v[82:83], v[204:205], 0 op_sel_hi:[1,1,0]
	s_nop 0
	v_pk_fma_f32 v[82:83], v[84:85], v[206:207], v[82:83]
	v_cvt_pk_f32_fp8_sdwa v[84:85], v80 src0_sel:WORD_1
	v_pk_fma_f32 v[82:83], v[86:87], v[208:209], v[82:83]
	v_cvt_pk_f32_fp8_e32 v[86:87], v81
	v_pk_fma_f32 v[78:79], v[78:79], v[144:145], v[82:83]
	v_cvt_pk_f32_fp8_e32 v[82:83], v80
	v_cvt_pk_f32_fp8_sdwa v[80:81], v81 src0_sel:WORD_1
	v_pk_fma_f32 v[78:79], v[82:83], v[202:203], v[78:79]
	s_nop 0
	v_pk_fma_f32 v[78:79], v[84:85], v[138:139], v[78:79]
	v_cvt_pk_f32_fp8_e32 v[82:83], v75
	v_pk_fma_f32 v[78:79], v[86:87], v[142:143], v[78:79]
	s_nop 0
	v_pk_fma_f32 v[78:79], v[80:81], v[140:141], v[78:79]
	v_cvt_pk_f32_fp8_sdwa v[80:81], v74 src0_sel:WORD_1
	v_add_f32_e32 v84, v78, v79
	v_cvt_pk_f32_fp8_e32 v[78:79], v74
	v_cvt_pk_f32_fp8_sdwa v[74:75], v75 src0_sel:WORD_1
	v_pk_fma_f32 v[78:79], v[78:79], v[204:205], 0 op_sel_hi:[1,1,0]
	s_nop 0
	v_pk_fma_f32 v[78:79], v[80:81], v[206:207], v[78:79]
	v_cvt_pk_f32_fp8_sdwa v[80:81], v76 src0_sel:WORD_1
	v_pk_fma_f32 v[78:79], v[82:83], v[208:209], v[78:79]
	v_cvt_pk_f32_fp8_e32 v[82:83], v77
	v_pk_fma_f32 v[74:75], v[74:75], v[144:145], v[78:79]
	v_cvt_pk_f32_fp8_e32 v[78:79], v76
	v_cvt_pk_f32_fp8_sdwa v[76:77], v77 src0_sel:WORD_1
	v_pk_fma_f32 v[74:75], v[78:79], v[202:203], v[74:75]
	s_nop 0
	v_pk_fma_f32 v[74:75], v[80:81], v[138:139], v[74:75]
	v_pk_fma_f32 v[74:75], v[82:83], v[142:143], v[74:75]
	v_pk_fma_f32 v[74:75], v[76:77], v[140:141], v[74:75]
	v_add_f32_e32 v74, v74, v75
	s_nop 1
	v_add_f32_dpp v75, v167, v167 row_shl:4 row_mask:0xf bank_mask:0x5
	v_add_f32_dpp v75, v108, v108 row_shr:4 row_mask:0xf bank_mask:0xa
	v_add_f32_dpp v76, v136, v136 row_shl:4 row_mask:0xf bank_mask:0x5
	v_add_f32_dpp v76, v104, v104 row_shr:4 row_mask:0xf bank_mask:0xa
	v_add_f32_dpp v77, v132, v132 row_shl:4 row_mask:0xf bank_mask:0x5
	v_add_f32_dpp v77, v100, v100 row_shr:4 row_mask:0xf bank_mask:0xa
	v_add_f32_dpp v78, v128, v128 row_shl:4 row_mask:0xf bank_mask:0x5
	v_add_f32_dpp v78, v96, v96 row_shr:4 row_mask:0xf bank_mask:0xa
	v_add_f32_dpp v79, v124, v124 row_shl:4 row_mask:0xf bank_mask:0x5
	v_add_f32_dpp v79, v92, v92 row_shr:4 row_mask:0xf bank_mask:0xa
	v_add_f32_dpp v80, v120, v120 row_shl:4 row_mask:0xf bank_mask:0x5
	v_add_f32_dpp v80, v88, v88 row_shr:4 row_mask:0xf bank_mask:0xa
	v_add_f32_dpp v81, v116, v116 row_shl:4 row_mask:0xf bank_mask:0x5
	v_add_f32_dpp v81, v84, v84 row_shr:4 row_mask:0xf bank_mask:0xa
	v_add_f32_dpp v74, v74, v74 row_shr:4 row_mask:0xf bank_mask:0xa
	v_add_f32_dpp v74, v112, v112 row_shl:4 row_mask:0xf bank_mask:0x5
	s_nop 1
	v_add_f32_dpp v75, v75, v75 quad_perm:[2,3,0,1] row_mask:0xf bank_mask:0xf
	v_add_f32_dpp v79, v79, v79 quad_perm:[2,3,0,1] row_mask:0xf bank_mask:0xf
	v_cndmask_b32_e64 v75, v79, v75, s[10:11]
	v_add_f32_dpp v77, v77, v77 quad_perm:[2,3,0,1] row_mask:0xf bank_mask:0xf
	v_add_f32_dpp v81, v81, v81 quad_perm:[2,3,0,1] row_mask:0xf bank_mask:0xf
	v_cndmask_b32_e64 v77, v81, v77, s[10:11]
	v_add_f32_dpp v76, v76, v76 quad_perm:[2,3,0,1] row_mask:0xf bank_mask:0xf
	v_add_f32_dpp v80, v80, v80 quad_perm:[2,3,0,1] row_mask:0xf bank_mask:0xf
	v_cndmask_b32_e64 v76, v80, v76, s[10:11]
	v_add_f32_dpp v78, v78, v78 quad_perm:[2,3,0,1] row_mask:0xf bank_mask:0xf
	v_add_f32_dpp v74, v74, v74 quad_perm:[2,3,0,1] row_mask:0xf bank_mask:0xf
	v_cndmask_b32_e64 v74, v74, v78, s[10:11]
	s_nop 1
	v_add_f32_dpp v75, v75, v75 quad_perm:[1,0,3,2] row_mask:0xf bank_mask:0xf
	v_add_f32_dpp v77, v77, v77 quad_perm:[1,0,3,2] row_mask:0xf bank_mask:0xf
	v_cndmask_b32_e64 v75, v77, v75, s[12:13]
	v_add_f32_dpp v76, v76, v76 quad_perm:[1,0,3,2] row_mask:0xf bank_mask:0xf
	v_add_f32_dpp v74, v74, v74 quad_perm:[1,0,3,2] row_mask:0xf bank_mask:0xf
	v_cndmask_b32_e64 v74, v74, v76, s[12:13]
	global_store_dword v[200:201], v75, off
	global_store_dword v[200:201], v74, off offset:32
	v_lshl_add_u64 v[198:199], v[198:199], 0, s[20:21]
	v_add_u32_e32 v165, 0x400, v165
	v_lshl_add_u64 v[200:201], v[200:201], 0, s[36:37]
	s_and_b64 vcc, exec, s[28:29]
	s_cbranch_vccnz .LBB0_1504

; DI void up_issue(u32x4 (&W)[16], u32 (&pj)[16], const u32* pl, const unsigned char* wbase, int grp) {
; #pragma unroll
;   for (int j = 0; j < 16; ++j) {
;     pj[j] = pl[8 * j + grp];
;     W[j] = *(const u32x4*)(wbase + (size_t)(pj[j] >> 16) * 1024);
;   }
; }
; DI void peer_up_phase(const Params& p, unsigned char* smem, int layer, u32* ctr) {
;     ...
;       const int t0 = item * 64 + 16 * w;
;       const unsigned char* wbase = wu + slice * 128 + c * 16;
;       {
;         const u32* src = hgp + (size_t)t0 * 128;
; #pragma unroll
;         for (int i = 0; i < 32; ++i) pl[i * 64 + lane] = src[i * 64 + lane];
;       }
;       float* ybase = yb + (size_t)t0 * 1024 + slice * 128;
;       u32x4 WA[16], WB[16];
;       u32 pA[16], pB[16];
;       up_issue(WA, pA, pl, wbase, grp);
.LBB0_1647:
	v_cmp_lt_i32_e32 vcc, s31, v4
	s_mov_b64 s[28:29], -1
	s_cbranch_vccnz .LBB0_1638
	s_waitcnt vmcnt(3)
	v_lshl_add_u32 v68, v4, 6, v3
	v_ashrrev_i32_e32 v69, 31, v68
	v_lshlrev_b64 v[4:5], 9, v[68:69]
	v_lshl_add_u64 v[4:5], s[16:17], 0, v[4:5]
	s_mov_b32 s100, 0x200000
	s_mov_b32 s101, 0
	v_lshl_add_u64 v[252:253], v[4:5], 0, s[100:101]
	v_mov_b32_e32 v248, v161
	v_mov_b32_e32 v249, 0
	v_lshl_add_u64 v[252:253], v[248:249], 7, v[252:253]
	v_mov_b32_e32 v139, v133
	v_lshl_add_u64 v[6:7], v[4:5], 0, v[138:139]
	global_load_dword v38, v[6:7], off
	global_load_dword v39, v[6:7], off offset:256
	v_mov_b32_e32 v141, v133
	v_mov_b32_e32 v143, v133
	v_mov_b32_e32 v145, v133
	v_mov_b32_e32 v147, v133
	v_mov_b32_e32 v149, v133
	v_mov_b32_e32 v151, v133
	v_mov_b32_e32 v153, v133
	v_mov_b32_e32 v155, v133
	v_mov_b32_e32 v157, v133
	v_mov_b32_e32 v159, v133
	v_mov_b32_e32 v163, v133
	v_mov_b32_e32 v165, v133
	v_mov_b32_e32 v167, v133
	v_mov_b32_e32 v169, v133
	v_mov_b32_e32 v171, v133
	v_mov_b32_e32 v173, v133
	v_lshl_add_u64 v[8:9], v[4:5], 0, v[140:141]
	v_lshl_add_u64 v[10:11], v[4:5], 0, v[142:143]
	v_lshl_add_u64 v[12:13], v[4:5], 0, v[144:145]
	v_lshl_add_u64 v[14:15], v[4:5], 0, v[146:147]
	v_lshl_add_u64 v[16:17], v[4:5], 0, v[148:149]
	v_lshl_add_u64 v[18:19], v[4:5], 0, v[150:151]
	v_lshl_add_u64 v[20:21], v[4:5], 0, v[152:153]
	v_lshl_add_u64 v[22:23], v[4:5], 0, v[154:155]
	v_lshl_add_u64 v[24:25], v[4:5], 0, v[156:157]
	v_lshl_add_u64 v[26:27], v[4:5], 0, v[158:159]
	v_lshl_add_u64 v[28:29], v[4:5], 0, v[162:163]
	v_lshl_add_u64 v[30:31], v[4:5], 0, v[164:165]
	v_lshl_add_u64 v[32:33], v[4:5], 0, v[166:167]
	v_lshl_add_u64 v[34:35], v[4:5], 0, v[168:169]
	v_lshl_add_u64 v[36:37], v[4:5], 0, v[170:171]
	v_lshl_add_u64 v[4:5], v[4:5], 0, v[172:173]
	global_load_dword v70, v[6:7], off offset:512
	global_load_dword v71, v[6:7], off offset:768
	global_load_dword v72, v[6:7], off offset:1024
	global_load_dword v73, v[6:7], off offset:1280
	global_load_dword v74, v[6:7], off offset:1536
	global_load_dword v75, v[6:7], off offset:1792
	global_load_dword v76, v[6:7], off offset:2048
	global_load_dword v77, v[6:7], off offset:2304
	global_load_dword v78, v[6:7], off offset:2560
	global_load_dword v79, v[6:7], off offset:2816
	global_load_dword v80, v[6:7], off offset:3072
	global_load_dword v81, v[6:7], off offset:3328
	global_load_dword v82, v[6:7], off offset:3584
	global_load_dword v83, v[6:7], off offset:3840
	global_load_dword v84, v[8:9], off
	global_load_dword v85, v[10:11], off
	global_load_dword v86, v[12:13], off
	global_load_dword v87, v[14:15], off
	global_load_dword v88, v[16:17], off
	global_load_dword v89, v[18:19], off
	global_load_dword v90, v[20:21], off
	global_load_dword v91, v[22:23], off
	global_load_dword v92, v[24:25], off
	global_load_dword v93, v[26:27], off
	global_load_dword v94, v[28:29], off
	global_load_dword v95, v[30:31], off
	global_load_dword v96, v[32:33], off
	global_load_dword v97, v[34:35], off
	global_load_dword v98, v[36:37], off
	global_load_dword v99, v[4:5], off
	v_cmp_lt_i32_e32 vcc, v223, v218
	v_lshlrev_b64 v[68:69], 12, v[68:69]
	s_mov_b32 s36, 0
	v_lshl_add_u64 v[188:189], v[176:177], 0, v[68:69]
	v_mov_b32_e32 v145, v214
	s_waitcnt vmcnt(30)
	ds_write2st64_b32 v213, v38, v39 offset0:1 offset1:2
	ds_read2_b32 v[178:179], v212 offset0:64 offset1:72
	ds_read2_b32 v[180:181], v212 offset0:80 offset1:88
	ds_read2_b32 v[182:183], v212 offset0:96 offset1:104
	ds_read2_b32 v[184:185], v212 offset0:112 offset1:120
	ds_read2_b32 v[186:187], v212 offset0:128 offset1:136
	s_waitcnt lgkmcnt(4)
	v_lshlrev_b32_sdwa v132, v215, v178 dst_sel:DWORD dst_unused:UNUSED_PAD src0_sel:DWORD src1_sel:WORD_1
	v_add_u32_e32 v12, v250, v132
	v_lshlrev_b32_sdwa v132, v215, v179 dst_sel:DWORD dst_unused:UNUSED_PAD src0_sel:DWORD src1_sel:WORD_1
	v_add_u32_e32 v14, v250, v132
	s_waitcnt lgkmcnt(3)
	v_lshlrev_b32_sdwa v132, v215, v180 dst_sel:DWORD dst_unused:UNUSED_PAD src0_sel:DWORD src1_sel:WORD_1
	v_add_u32_e32 v20, v250, v132
	v_lshlrev_b32_sdwa v132, v215, v181 dst_sel:DWORD dst_unused:UNUSED_PAD src0_sel:DWORD src1_sel:WORD_1
	v_add_u32_e32 v22, v250, v132
	s_waitcnt lgkmcnt(2)
	v_lshlrev_b32_sdwa v132, v215, v182 dst_sel:DWORD dst_unused:UNUSED_PAD src0_sel:DWORD src1_sel:WORD_1
	v_add_u32_e32 v28, v250, v132
	v_lshlrev_b32_sdwa v132, v215, v183 dst_sel:DWORD dst_unused:UNUSED_PAD src0_sel:DWORD src1_sel:WORD_1
	v_add_u32_e32 v30, v250, v132
	s_waitcnt lgkmcnt(1)
	v_lshlrev_b32_sdwa v132, v215, v184 dst_sel:DWORD dst_unused:UNUSED_PAD src0_sel:DWORD src1_sel:WORD_1
	v_add_u32_e32 v36, v250, v132
	v_lshlrev_b32_sdwa v132, v215, v185 dst_sel:DWORD dst_unused:UNUSED_PAD src0_sel:DWORD src1_sel:WORD_1
	global_load_dwordx4 v[4:7], v12, s[98:99]
	global_load_dwordx4 v[8:11], v14, s[98:99]
	s_nop 0
	global_load_dwordx4 v[12:15], v20, s[98:99]
	global_load_dwordx4 v[16:19], v22, s[98:99]
	s_nop 0
	global_load_dwordx4 v[20:23], v28, s[98:99]
	global_load_dwordx4 v[24:27], v30, s[98:99]
	v_add_u32_e32 v38, v250, v132
	global_load_dwordx4 v[28:31], v36, s[98:99]
	global_load_dwordx4 v[32:35], v38, s[98:99]
	ds_read2_b32 v[190:191], v212 offset0:144 offset1:152
	s_waitcnt lgkmcnt(1)
	v_lshlrev_b32_sdwa v132, v215, v186 dst_sel:DWORD dst_unused:UNUSED_PAD src0_sel:DWORD src1_sel:WORD_1
	v_add_u32_e32 v36, v250, v132
	v_lshlrev_b32_sdwa v132, v215, v187 dst_sel:DWORD dst_unused:UNUSED_PAD src0_sel:DWORD src1_sel:WORD_1
	v_add_u32_e32 v40, v250, v132
	s_waitcnt lgkmcnt(0)
; DI void up_issue(u32x4 (&W)[16], u32 (&pj)[16], const u32* pl, const unsigned char* wbase, int grp) {
; #pragma unroll
;   for (int j = 0; j < 16; ++j) {
;     pj[j] = pl[8 * j + grp];
;     W[j] = *(const u32x4*)(wbase + (size_t)(pj[j] >> 16) * 1024);
;   }
; }
; DI void up_math(const u32x4 (&W)[16], const u32 (&pj)[16], float* __restrict__ yrow, int lane) {
;   f2 y[8];
; #pragma unroll
;   for (int i = 0; i < 8; ++i) y[i] = f2{0.f, 0.f};
; #pragma unroll
;   for (int j = 0; j < 16; ++j) {
;     const float h = __uint_as_float(pj[j] << 16);
;     const f2 hh = {h, h};
; #pragma unroll
;     for (int d = 0; d < 4; ++d) {
;       f2 lo = __builtin_amdgcn_cvt_pk_f32_fp8((int)W[j][d], false);
;       f2 hi = __builtin_amdgcn_cvt_pk_f32_fp8((int)W[j][d], true);
;       y[2 * d] = lo * hh + y[2 * d];
;       y[2 * d + 1] = hi * hh + y[2 * d + 1];
;     }
; DI void peer_up_phase(const Params& p, unsigned char* smem, int layer, u32* ctr) {
;     ...
;       for (int tl = 0; tl < 16; tl += 2) {
;         up_issue(WB, pB, pl + (tl + 1) * 128, wbase, grp);
;         __builtin_amdgcn_sched_barrier(0);
;         up_math(WA, pA, ybase + (size_t)tl * 1024, lane);
	v_lshlrev_b32_sdwa v132, v215, v190 dst_sel:DWORD dst_unused:UNUSED_PAD src0_sel:DWORD src1_sel:WORD_1
	global_load_dwordx4 v[36:39], v36, s[98:99]
	s_nop 0
	global_load_dwordx4 v[40:43], v40, s[98:99]
	v_add_u32_e32 v44, v250, v132
	ds_read2_b32 v[192:193], v212 offset0:160 offset1:168
	v_lshlrev_b32_sdwa v132, v215, v191 dst_sel:DWORD dst_unused:UNUSED_PAD src0_sel:DWORD src1_sel:WORD_1
	v_add_u32_e32 v48, v250, v132
	global_load_dwordx4 v[44:47], v44, s[98:99]
	s_nop 0
	global_load_dwordx4 v[48:51], v48, s[98:99]
	ds_read2_b32 v[194:195], v212 offset0:176 offset1:184
	s_waitcnt lgkmcnt(1)
	v_lshlrev_b32_sdwa v132, v215, v192 dst_sel:DWORD dst_unused:UNUSED_PAD src0_sel:DWORD src1_sel:WORD_1
	v_add_u32_e32 v52, v250, v132
	v_lshlrev_b32_sdwa v132, v215, v193 dst_sel:DWORD dst_unused:UNUSED_PAD src0_sel:DWORD src1_sel:WORD_1
	v_add_u32_e32 v56, v250, v132
	s_waitcnt lgkmcnt(0)
	v_lshlrev_b32_sdwa v132, v215, v194 dst_sel:DWORD dst_unused:UNUSED_PAD src0_sel:DWORD src1_sel:WORD_1
	v_add_u32_e32 v60, v250, v132
	v_lshlrev_b32_sdwa v132, v215, v195 dst_sel:DWORD dst_unused:UNUSED_PAD src0_sel:DWORD src1_sel:WORD_1
	v_add_u32_e32 v64, v250, v132
	global_load_dwordx4 v[52:55], v52, s[98:99]
	s_nop 0
	global_load_dwordx4 v[56:59], v56, s[98:99]
	s_nop 0
	global_load_dwordx4 v[60:63], v60, s[98:99]
	s_nop 0
	global_load_dwordx4 v[64:67], v64, s[98:99]
	s_waitcnt vmcnt(44)
	ds_write2st64_b32 v213, v70, v71 offset0:3 offset1:4
	s_waitcnt vmcnt(42)
	ds_write2st64_b32 v213, v72, v73 offset0:5 offset1:6
	s_waitcnt vmcnt(40)
	ds_write2st64_b32 v213, v74, v75 offset0:7 offset1:8
	s_waitcnt vmcnt(38)
	ds_write2st64_b32 v213, v76, v77 offset0:9 offset1:10
	s_waitcnt vmcnt(36)
	ds_write2st64_b32 v213, v78, v79 offset0:11 offset1:12
	s_waitcnt vmcnt(34)
	ds_write2st64_b32 v213, v80, v81 offset0:13 offset1:14
	s_waitcnt vmcnt(32)
	ds_write2st64_b32 v213, v82, v83 offset0:15 offset1:16
	s_waitcnt vmcnt(30)
	ds_write2st64_b32 v213, v84, v85 offset0:17 offset1:18
	s_waitcnt vmcnt(28)
	ds_write2st64_b32 v213, v86, v87 offset0:19 offset1:20
	s_waitcnt vmcnt(26)
	ds_write2st64_b32 v213, v88, v89 offset0:21 offset1:22
	s_waitcnt vmcnt(24)
	ds_write2st64_b32 v213, v90, v91 offset0:23 offset1:24
	s_waitcnt vmcnt(22)
	ds_write2st64_b32 v213, v92, v93 offset0:25 offset1:26
	s_waitcnt vmcnt(20)
	ds_write2st64_b32 v213, v94, v95 offset0:27 offset1:28
	s_waitcnt vmcnt(18)
	ds_write2st64_b32 v213, v96, v97 offset0:29 offset1:30
	s_waitcnt vmcnt(16)
	ds_write2st64_b32 v213, v98, v99 offset0:31 offset1:32
	v_cndmask_b32_e32 v70, v161, v223, vcc
	v_cmp_lt_i32_e32 vcc, v224, v218
	v_lshlrev_b32_e32 v139, 2, v70
	s_nop 0
	v_cndmask_b32_e32 v70, v161, v224, vcc
	v_cmp_lt_i32_e32 vcc, v222, v218
	v_lshlrev_b32_e32 v141, 2, v70
	s_nop 0
	v_cndmask_b32_e32 v70, v161, v222, vcc
	v_lshlrev_b32_e32 v143, 2, v70
	v_lshlrev_b32_e32 v178, 16, v178
	v_lshlrev_b32_e32 v179, 16, v179
	v_lshlrev_b32_e32 v180, 16, v180
	v_lshlrev_b32_e32 v181, 16, v181
	v_lshlrev_b32_e32 v182, 16, v182
	v_lshlrev_b32_e32 v183, 16, v183
	v_lshlrev_b32_e32 v184, 16, v184
	v_lshlrev_b32_e32 v185, 16, v185
	v_lshlrev_b32_e32 v186, 16, v186
	v_lshlrev_b32_e32 v187, 16, v187
	v_lshlrev_b32_e32 v190, 16, v190
	v_lshlrev_b32_e32 v191, 16, v191
	v_lshlrev_b32_e32 v192, 16, v192
	v_lshlrev_b32_e32 v193, 16, v193
	v_lshlrev_b32_e32 v194, 16, v194
	v_lshlrev_b32_e32 v195, 16, v195
	v_mov_b32_e32 v210, 0
	v_mov_b32_e32 v211, 0
	v_mov_b32_e32 v208, 0
	v_mov_b32_e32 v209, 0
	v_mov_b32_e32 v206, 0
	v_mov_b32_e32 v207, 0
	v_mov_b32_e32 v204, 0
	v_mov_b32_e32 v205, 0
	v_mov_b32_e32 v202, 0
	v_mov_b32_e32 v203, 0
	v_mov_b32_e32 v200, 0
	v_mov_b32_e32 v201, 0
	v_mov_b32_e32 v198, 0
	v_mov_b32_e32 v199, 0
	v_mov_b32_e32 v196, 0
	v_mov_b32_e32 v197, 0
	s_branch .LBB0_1650
.LBB0_1649:
	s_add_i32 s36, s36, 2
	s_cmp_lg_u32 s36, 8
	s_cbranch_scc1 .Lmy_lpf_1649
	global_load_dword v254, v[252:253], off
.Lmy_lpf_1649:
	s_waitcnt vmcnt(16)
	v_cvt_pk_f32_fp8_e32 v[216:217], v128
	v_cvt_pk_f32_fp8_sdwa v[226:227], v128 src0_sel:WORD_1
	v_cvt_pk_f32_fp8_e32 v[228:229], v129
	v_cvt_pk_f32_fp8_sdwa v[128:129], v129 src0_sel:WORD_1
	v_cvt_pk_f32_fp8_e32 v[230:231], v130
	v_cvt_pk_f32_fp8_sdwa v[232:233], v130 src0_sel:WORD_1
	v_cvt_pk_f32_fp8_e32 v[234:235], v131
	v_cvt_pk_f32_fp8_sdwa v[130:131], v131 src0_sel:WORD_1
	v_pk_fma_f32 v[216:217], v[210:211], v[216:217], 0 op_sel_hi:[0,1,0]
	v_pk_fma_f32 v[226:227], v[210:211], v[226:227], 0 op_sel_hi:[0,1,0]
	v_pk_fma_f32 v[228:229], v[210:211], v[228:229], 0 op_sel_hi:[0,1,0]
	v_pk_fma_f32 v[128:129], v[210:211], v[128:129], 0 op_sel_hi:[0,1,0]
	v_pk_fma_f32 v[230:231], v[210:211], v[230:231], 0 op_sel_hi:[0,1,0]
	v_pk_fma_f32 v[232:233], v[210:211], v[232:233], 0 op_sel_hi:[0,1,0]
	v_pk_fma_f32 v[234:235], v[210:211], v[234:235], 0 op_sel_hi:[0,1,0]
	v_pk_fma_f32 v[130:131], v[210:211], v[130:131], 0 op_sel_hi:[0,1,0]
	v_mov_b32_e32 v132, v211
	s_waitcnt vmcnt(15)
	v_cvt_pk_f32_fp8_e32 v[210:211], v124
	v_cvt_pk_f32_fp8_sdwa v[236:237], v124 src0_sel:WORD_1
	v_cvt_pk_f32_fp8_e32 v[238:239], v125
	v_cvt_pk_f32_fp8_sdwa v[124:125], v125 src0_sel:WORD_1
	v_pk_fma_f32 v[210:211], v[132:133], v[210:211], v[216:217] op_sel_hi:[0,1,1]
	v_pk_fma_f32 v[216:217], v[132:133], v[236:237], v[226:227] op_sel_hi:[0,1,1]
	v_pk_fma_f32 v[226:227], v[132:133], v[238:239], v[228:229] op_sel_hi:[0,1,1]
	v_pk_fma_f32 v[124:125], v[132:133], v[124:125], v[128:129] op_sel_hi:[0,1,1]
	v_cvt_pk_f32_fp8_e32 v[128:129], v126
	v_cvt_pk_f32_fp8_sdwa v[228:229], v126 src0_sel:WORD_1
	v_cvt_pk_f32_fp8_e32 v[236:237], v127
	v_cvt_pk_f32_fp8_sdwa v[126:127], v127 src0_sel:WORD_1
	v_pk_fma_f32 v[128:129], v[132:133], v[128:129], v[230:231] op_sel_hi:[0,1,1]
	v_pk_fma_f32 v[228:229], v[132:133], v[228:229], v[232:233] op_sel_hi:[0,1,1]
	v_pk_fma_f32 v[230:231], v[132:133], v[236:237], v[234:235] op_sel_hi:[0,1,1]
	s_waitcnt vmcnt(14)
; DI void up_math(const u32x4 (&W)[16], const u32 (&pj)[16], float* __restrict__ yrow, int lane) {
;     ...
;   for (int j = 0; j < 16; ++j) {
;     const float h = __uint_as_float(pj[j] << 16);
;     const f2 hh = {h, h};
; #pragma unroll
;     for (int d = 0; d < 4; ++d) {
;       f2 lo = __builtin_amdgcn_cvt_pk_f32_fp8((int)W[j][d], false);
;       f2 hi = __builtin_amdgcn_cvt_pk_f32_fp8((int)W[j][d], true);
;       y[2 * d] = lo * hh + y[2 * d];
;       y[2 * d + 1] = hi * hh + y[2 * d + 1];
;     }
	v_cvt_pk_f32_fp8_e32 v[232:233], v120
	v_cvt_pk_f32_fp8_sdwa v[234:235], v120 src0_sel:WORD_1
	v_cvt_pk_f32_fp8_e32 v[236:237], v121
	v_cvt_pk_f32_fp8_sdwa v[120:121], v121 src0_sel:WORD_1
	v_pk_fma_f32 v[126:127], v[132:133], v[126:127], v[130:131] op_sel_hi:[0,1,1]
	v_pk_fma_f32 v[210:211], v[208:209], v[232:233], v[210:211] op_sel_hi:[0,1,1]
	v_pk_fma_f32 v[216:217], v[208:209], v[234:235], v[216:217] op_sel_hi:[0,1,1]
	v_pk_fma_f32 v[120:121], v[208:209], v[120:121], v[124:125] op_sel_hi:[0,1,1]
	v_cvt_pk_f32_fp8_e32 v[124:125], v122
	v_cvt_pk_f32_fp8_sdwa v[232:233], v122 src0_sel:WORD_1
	v_cvt_pk_f32_fp8_e32 v[234:235], v123
	v_cvt_pk_f32_fp8_sdwa v[122:123], v123 src0_sel:WORD_1
	v_pk_fma_f32 v[226:227], v[208:209], v[236:237], v[226:227] op_sel_hi:[0,1,1]
	v_pk_fma_f32 v[124:125], v[208:209], v[124:125], v[128:129] op_sel_hi:[0,1,1]
	v_pk_fma_f32 v[128:129], v[208:209], v[232:233], v[228:229] op_sel_hi:[0,1,1]
	v_pk_fma_f32 v[228:229], v[208:209], v[234:235], v[230:231] op_sel_hi:[0,1,1]
	v_pk_fma_f32 v[122:123], v[208:209], v[122:123], v[126:127] op_sel_hi:[0,1,1]
	v_mov_b32_e32 v126, v209
	s_waitcnt vmcnt(13)
	v_cvt_pk_f32_fp8_e32 v[130:131], v116
	v_cvt_pk_f32_fp8_sdwa v[208:209], v116 src0_sel:WORD_1
	v_cvt_pk_f32_fp8_e32 v[230:231], v117
	v_cvt_pk_f32_fp8_sdwa v[116:117], v117 src0_sel:WORD_1
	v_pk_fma_f32 v[130:131], v[126:127], v[130:131], v[210:211] op_sel_hi:[0,1,1]
	v_pk_fma_f32 v[208:209], v[126:127], v[208:209], v[216:217] op_sel_hi:[0,1,1]
	v_pk_fma_f32 v[210:211], v[126:127], v[230:231], v[226:227] op_sel_hi:[0,1,1]
	v_pk_fma_f32 v[116:117], v[126:127], v[116:117], v[120:121] op_sel_hi:[0,1,1]
	v_cvt_pk_f32_fp8_e32 v[120:121], v118
	v_cvt_pk_f32_fp8_sdwa v[216:217], v118 src0_sel:WORD_1
	v_cvt_pk_f32_fp8_e32 v[226:227], v119
	v_cvt_pk_f32_fp8_sdwa v[118:119], v119 src0_sel:WORD_1
	v_pk_fma_f32 v[120:121], v[126:127], v[120:121], v[124:125] op_sel_hi:[0,1,1]
	v_pk_fma_f32 v[124:125], v[126:127], v[216:217], v[128:129] op_sel_hi:[0,1,1]
	v_pk_fma_f32 v[128:129], v[126:127], v[226:227], v[228:229] op_sel_hi:[0,1,1]
	v_pk_fma_f32 v[118:119], v[126:127], v[118:119], v[122:123] op_sel_hi:[0,1,1]
	s_waitcnt vmcnt(12)
	v_cvt_pk_f32_fp8_e32 v[126:127], v112
	v_cvt_pk_f32_fp8_sdwa v[216:217], v112 src0_sel:WORD_1
	v_cvt_pk_f32_fp8_e32 v[226:227], v113
	v_cvt_pk_f32_fp8_sdwa v[112:113], v113 src0_sel:WORD_1
	v_pk_fma_f32 v[126:127], v[206:207], v[126:127], v[130:131] op_sel_hi:[0,1,1]
	v_pk_fma_f32 v[130:131], v[206:207], v[216:217], v[208:209] op_sel_hi:[0,1,1]
	v_pk_fma_f32 v[208:209], v[206:207], v[226:227], v[210:211] op_sel_hi:[0,1,1]
	v_pk_fma_f32 v[112:113], v[206:207], v[112:113], v[116:117] op_sel_hi:[0,1,1]
	v_cvt_pk_f32_fp8_e32 v[116:117], v114
	v_cvt_pk_f32_fp8_sdwa v[210:211], v114 src0_sel:WORD_1
	v_cvt_pk_f32_fp8_e32 v[216:217], v115
	v_cvt_pk_f32_fp8_sdwa v[114:115], v115 src0_sel:WORD_1
	v_pk_fma_f32 v[116:117], v[206:207], v[116:117], v[120:121] op_sel_hi:[0,1,1]
	v_pk_fma_f32 v[120:121], v[206:207], v[210:211], v[124:125] op_sel_hi:[0,1,1]
	v_pk_fma_f32 v[124:125], v[206:207], v[216:217], v[128:129] op_sel_hi:[0,1,1]
	v_pk_fma_f32 v[114:115], v[206:207], v[114:115], v[118:119] op_sel_hi:[0,1,1]
	v_mov_b32_e32 v118, v207
	s_waitcnt vmcnt(11)
	v_cvt_pk_f32_fp8_e32 v[122:123], v108
	v_cvt_pk_f32_fp8_sdwa v[128:129], v108 src0_sel:WORD_1
	v_cvt_pk_f32_fp8_e32 v[206:207], v109
	v_cvt_pk_f32_fp8_sdwa v[108:109], v109 src0_sel:WORD_1
	v_pk_fma_f32 v[122:123], v[118:119], v[122:123], v[126:127] op_sel_hi:[0,1,1]
	v_pk_fma_f32 v[126:127], v[118:119], v[128:129], v[130:131] op_sel_hi:[0,1,1]
	v_pk_fma_f32 v[128:129], v[118:119], v[206:207], v[208:209] op_sel_hi:[0,1,1]
	v_pk_fma_f32 v[108:109], v[118:119], v[108:109], v[112:113] op_sel_hi:[0,1,1]
	v_cvt_pk_f32_fp8_e32 v[112:113], v110
	v_cvt_pk_f32_fp8_sdwa v[130:131], v110 src0_sel:WORD_1
	v_cvt_pk_f32_fp8_e32 v[206:207], v111
	v_cvt_pk_f32_fp8_sdwa v[110:111], v111 src0_sel:WORD_1
	v_pk_fma_f32 v[112:113], v[118:119], v[112:113], v[116:117] op_sel_hi:[0,1,1]
	v_pk_fma_f32 v[116:117], v[118:119], v[130:131], v[120:121] op_sel_hi:[0,1,1]
	v_pk_fma_f32 v[120:121], v[118:119], v[206:207], v[124:125] op_sel_hi:[0,1,1]
	v_pk_fma_f32 v[110:111], v[118:119], v[110:111], v[114:115] op_sel_hi:[0,1,1]
	s_waitcnt vmcnt(10)
	v_cvt_pk_f32_fp8_e32 v[118:119], v104
	v_cvt_pk_f32_fp8_sdwa v[124:125], v104 src0_sel:WORD_1
	v_cvt_pk_f32_fp8_e32 v[130:131], v105
	v_cvt_pk_f32_fp8_sdwa v[104:105], v105 src0_sel:WORD_1
	v_pk_fma_f32 v[118:119], v[204:205], v[118:119], v[122:123] op_sel_hi:[0,1,1]
	v_pk_fma_f32 v[122:123], v[204:205], v[124:125], v[126:127] op_sel_hi:[0,1,1]
	v_pk_fma_f32 v[124:125], v[204:205], v[130:131], v[128:129] op_sel_hi:[0,1,1]
	v_pk_fma_f32 v[104:105], v[204:205], v[104:105], v[108:109] op_sel_hi:[0,1,1]
	v_cvt_pk_f32_fp8_e32 v[108:109], v106
	v_cvt_pk_f32_fp8_sdwa v[126:127], v106 src0_sel:WORD_1
	v_cvt_pk_f32_fp8_e32 v[128:129], v107
	v_cvt_pk_f32_fp8_sdwa v[106:107], v107 src0_sel:WORD_1
	v_pk_fma_f32 v[108:109], v[204:205], v[108:109], v[112:113] op_sel_hi:[0,1,1]
	v_pk_fma_f32 v[112:113], v[204:205], v[126:127], v[116:117] op_sel_hi:[0,1,1]
	v_pk_fma_f32 v[116:117], v[204:205], v[128:129], v[120:121] op_sel_hi:[0,1,1]
	v_pk_fma_f32 v[106:107], v[204:205], v[106:107], v[110:111] op_sel_hi:[0,1,1]
	s_waitcnt vmcnt(9)
; DI void up_math(const u32x4 (&W)[16], const u32 (&pj)[16], float* __restrict__ yrow, int lane) {
;     ...
;   for (int j = 0; j < 16; ++j) {
;     const float h = __uint_as_float(pj[j] << 16);
;     const f2 hh = {h, h};
; #pragma unroll
;     for (int d = 0; d < 4; ++d) {
;       f2 lo = __builtin_amdgcn_cvt_pk_f32_fp8((int)W[j][d], false);
;       f2 hi = __builtin_amdgcn_cvt_pk_f32_fp8((int)W[j][d], true);
;       y[2 * d] = lo * hh + y[2 * d];
;       y[2 * d + 1] = hi * hh + y[2 * d + 1];
;     }
	v_cvt_pk_f32_fp8_e32 v[114:115], v100
	v_cvt_pk_f32_fp8_sdwa v[120:121], v100 src0_sel:WORD_1
	v_cvt_pk_f32_fp8_e32 v[126:127], v101
	v_cvt_pk_f32_fp8_sdwa v[100:101], v101 src0_sel:WORD_1
	v_pk_fma_f32 v[114:115], v[204:205], v[114:115], v[118:119] op_sel:[1,0,0] op_sel_hi:[1,1,1]
	v_pk_fma_f32 v[118:119], v[204:205], v[120:121], v[122:123] op_sel:[1,0,0] op_sel_hi:[1,1,1]
	v_pk_fma_f32 v[120:121], v[204:205], v[126:127], v[124:125] op_sel:[1,0,0] op_sel_hi:[1,1,1]
	v_pk_fma_f32 v[100:101], v[204:205], v[100:101], v[104:105] op_sel:[1,0,0] op_sel_hi:[1,1,1]
	v_cvt_pk_f32_fp8_e32 v[104:105], v102
	v_cvt_pk_f32_fp8_sdwa v[122:123], v102 src0_sel:WORD_1
	v_cvt_pk_f32_fp8_e32 v[124:125], v103
	v_cvt_pk_f32_fp8_sdwa v[102:103], v103 src0_sel:WORD_1
	v_pk_fma_f32 v[104:105], v[204:205], v[104:105], v[108:109] op_sel:[1,0,0] op_sel_hi:[1,1,1]
	v_pk_fma_f32 v[108:109], v[204:205], v[122:123], v[112:113] op_sel:[1,0,0] op_sel_hi:[1,1,1]
	v_pk_fma_f32 v[112:113], v[204:205], v[124:125], v[116:117] op_sel:[1,0,0] op_sel_hi:[1,1,1]
	v_pk_fma_f32 v[102:103], v[204:205], v[102:103], v[106:107] op_sel:[1,0,0] op_sel_hi:[1,1,1]
	s_waitcnt vmcnt(8)
	v_cvt_pk_f32_fp8_e32 v[110:111], v96
	v_cvt_pk_f32_fp8_sdwa v[116:117], v96 src0_sel:WORD_1
	v_cvt_pk_f32_fp8_e32 v[122:123], v97
	v_cvt_pk_f32_fp8_sdwa v[96:97], v97 src0_sel:WORD_1
	v_pk_fma_f32 v[110:111], v[202:203], v[110:111], v[114:115] op_sel_hi:[0,1,1]
	v_pk_fma_f32 v[114:115], v[202:203], v[116:117], v[118:119] op_sel_hi:[0,1,1]
	v_pk_fma_f32 v[116:117], v[202:203], v[122:123], v[120:121] op_sel_hi:[0,1,1]
	v_pk_fma_f32 v[96:97], v[202:203], v[96:97], v[100:101] op_sel_hi:[0,1,1]
	v_cvt_pk_f32_fp8_e32 v[100:101], v98
	v_cvt_pk_f32_fp8_sdwa v[118:119], v98 src0_sel:WORD_1
	v_cvt_pk_f32_fp8_e32 v[120:121], v99
	v_cvt_pk_f32_fp8_sdwa v[98:99], v99 src0_sel:WORD_1
	v_pk_fma_f32 v[100:101], v[202:203], v[100:101], v[104:105] op_sel_hi:[0,1,1]
	v_pk_fma_f32 v[104:105], v[202:203], v[118:119], v[108:109] op_sel_hi:[0,1,1]
	v_pk_fma_f32 v[108:109], v[202:203], v[120:121], v[112:113] op_sel_hi:[0,1,1]
	v_pk_fma_f32 v[98:99], v[202:203], v[98:99], v[102:103] op_sel_hi:[0,1,1]
	s_waitcnt vmcnt(7)
	v_cvt_pk_f32_fp8_e32 v[106:107], v92
	v_cvt_pk_f32_fp8_sdwa v[112:113], v92 src0_sel:WORD_1
	v_cvt_pk_f32_fp8_e32 v[118:119], v93
	v_cvt_pk_f32_fp8_sdwa v[92:93], v93 src0_sel:WORD_1
	v_pk_fma_f32 v[106:107], v[202:203], v[106:107], v[110:111] op_sel:[1,0,0] op_sel_hi:[1,1,1]
	v_pk_fma_f32 v[110:111], v[202:203], v[112:113], v[114:115] op_sel:[1,0,0] op_sel_hi:[1,1,1]
	v_pk_fma_f32 v[112:113], v[202:203], v[118:119], v[116:117] op_sel:[1,0,0] op_sel_hi:[1,1,1]
	v_pk_fma_f32 v[92:93], v[202:203], v[92:93], v[96:97] op_sel:[1,0,0] op_sel_hi:[1,1,1]
	v_cvt_pk_f32_fp8_e32 v[96:97], v94
	v_cvt_pk_f32_fp8_sdwa v[114:115], v94 src0_sel:WORD_1
	v_cvt_pk_f32_fp8_e32 v[116:117], v95
	v_cvt_pk_f32_fp8_sdwa v[94:95], v95 src0_sel:WORD_1
	v_pk_fma_f32 v[96:97], v[202:203], v[96:97], v[100:101] op_sel:[1,0,0] op_sel_hi:[1,1,1]
	v_pk_fma_f32 v[100:101], v[202:203], v[114:115], v[104:105] op_sel:[1,0,0] op_sel_hi:[1,1,1]
	v_pk_fma_f32 v[104:105], v[202:203], v[116:117], v[108:109] op_sel:[1,0,0] op_sel_hi:[1,1,1]
	v_pk_fma_f32 v[94:95], v[202:203], v[94:95], v[98:99] op_sel:[1,0,0] op_sel_hi:[1,1,1]
	s_waitcnt vmcnt(6)
	v_cvt_pk_f32_fp8_e32 v[102:103], v88
	v_cvt_pk_f32_fp8_sdwa v[108:109], v88 src0_sel:WORD_1
	v_cvt_pk_f32_fp8_e32 v[114:115], v89
	v_cvt_pk_f32_fp8_sdwa v[88:89], v89 src0_sel:WORD_1
	v_pk_fma_f32 v[102:103], v[200:201], v[102:103], v[106:107] op_sel_hi:[0,1,1]
	v_pk_fma_f32 v[106:107], v[200:201], v[108:109], v[110:111] op_sel_hi:[0,1,1]
	v_pk_fma_f32 v[108:109], v[200:201], v[114:115], v[112:113] op_sel_hi:[0,1,1]
	v_pk_fma_f32 v[88:89], v[200:201], v[88:89], v[92:93] op_sel_hi:[0,1,1]
	v_cvt_pk_f32_fp8_e32 v[92:93], v90
	v_cvt_pk_f32_fp8_sdwa v[110:111], v90 src0_sel:WORD_1
	v_cvt_pk_f32_fp8_e32 v[112:113], v91
	v_cvt_pk_f32_fp8_sdwa v[90:91], v91 src0_sel:WORD_1
	v_pk_fma_f32 v[92:93], v[200:201], v[92:93], v[96:97] op_sel_hi:[0,1,1]
	v_pk_fma_f32 v[96:97], v[200:201], v[110:111], v[100:101] op_sel_hi:[0,1,1]
	v_pk_fma_f32 v[100:101], v[200:201], v[112:113], v[104:105] op_sel_hi:[0,1,1]
	v_pk_fma_f32 v[90:91], v[200:201], v[90:91], v[94:95] op_sel_hi:[0,1,1]
	s_waitcnt vmcnt(5)
	v_cvt_pk_f32_fp8_e32 v[98:99], v84
	v_cvt_pk_f32_fp8_sdwa v[104:105], v84 src0_sel:WORD_1
	v_cvt_pk_f32_fp8_e32 v[110:111], v85
	v_cvt_pk_f32_fp8_sdwa v[84:85], v85 src0_sel:WORD_1
	v_pk_fma_f32 v[98:99], v[200:201], v[98:99], v[102:103] op_sel:[1,0,0] op_sel_hi:[1,1,1]
	v_pk_fma_f32 v[102:103], v[200:201], v[104:105], v[106:107] op_sel:[1,0,0] op_sel_hi:[1,1,1]
	v_pk_fma_f32 v[104:105], v[200:201], v[110:111], v[108:109] op_sel:[1,0,0] op_sel_hi:[1,1,1]
	v_pk_fma_f32 v[84:85], v[200:201], v[84:85], v[88:89] op_sel:[1,0,0] op_sel_hi:[1,1,1]
	v_cvt_pk_f32_fp8_e32 v[88:89], v86
	v_cvt_pk_f32_fp8_sdwa v[106:107], v86 src0_sel:WORD_1
	v_cvt_pk_f32_fp8_e32 v[108:109], v87
	v_cvt_pk_f32_fp8_sdwa v[86:87], v87 src0_sel:WORD_1
	v_pk_fma_f32 v[88:89], v[200:201], v[88:89], v[92:93] op_sel:[1,0,0] op_sel_hi:[1,1,1]
	v_pk_fma_f32 v[92:93], v[200:201], v[106:107], v[96:97] op_sel:[1,0,0] op_sel_hi:[1,1,1]
	v_pk_fma_f32 v[96:97], v[200:201], v[108:109], v[100:101] op_sel:[1,0,0] op_sel_hi:[1,1,1]
	v_pk_fma_f32 v[86:87], v[200:201], v[86:87], v[90:91] op_sel:[1,0,0] op_sel_hi:[1,1,1]
	s_waitcnt vmcnt(4)
; DI void up_math(const u32x4 (&W)[16], const u32 (&pj)[16], float* __restrict__ yrow, int lane) {
;     ...
;     for (int d = 0; d < 4; ++d) {
;       f2 lo = __builtin_amdgcn_cvt_pk_f32_fp8((int)W[j][d], false);
;       f2 hi = __builtin_amdgcn_cvt_pk_f32_fp8((int)W[j][d], true);
;       y[2 * d] = lo * hh + y[2 * d];
;       y[2 * d + 1] = hi * hh + y[2 * d + 1];
;     }
;   }
;   const bool b5 = lane & 32, b4 = lane & 16, b3 = lane & 8;
;   f2 q4[4];
; #pragma unroll
;   for (int i = 0; i < 4; ++i) {
;     f2 snd = b5 ? y[i] : y[i + 4]; f2 kp = b5 ? y[i + 4] : y[i];
;     q4[i] = f2{kp.x + __shfl_xor(snd.x, 32), kp.y + __shfl_xor(snd.y, 32)};
;   }
;   f2 r2[2];
; #pragma unroll
;   for (int i = 0; i < 2; ++i) {
;     f2 snd = b4 ? q4[i] : q4[i + 2]; f2 kp = b4 ? q4[i + 2] : q4[i];
;     r2[i] = f2{kp.x + __shfl_xor(snd.x, 16), kp.y + __shfl_xor(snd.y, 16)};
;   }
;   f2 a;
;   { f2 snd = b3 ? r2[0] : r2[1]; f2 kp = b3 ? r2[1] : r2[0]; a = f2{kp.x + __shfl_xor(snd.x, 8), kp.y + __shfl_xor(snd.y, 8)}; }
;   const int ci = (b5 ? 4 : 0) + (b4 ? 2 : 0) + (b3 ? 1 : 0);
;   *(float2*)(yrow + (lane & 7) * 16 + 2 * ci) = make_float2(a.x, a.y);
	v_cvt_pk_f32_fp8_e32 v[94:95], v80
	v_cvt_pk_f32_fp8_sdwa v[100:101], v80 src0_sel:WORD_1
	v_cvt_pk_f32_fp8_e32 v[106:107], v81
	v_cvt_pk_f32_fp8_sdwa v[80:81], v81 src0_sel:WORD_1
	v_pk_fma_f32 v[94:95], v[198:199], v[94:95], v[98:99] op_sel_hi:[0,1,1]
	v_pk_fma_f32 v[98:99], v[198:199], v[100:101], v[102:103] op_sel_hi:[0,1,1]
	v_pk_fma_f32 v[100:101], v[198:199], v[106:107], v[104:105] op_sel_hi:[0,1,1]
	v_pk_fma_f32 v[80:81], v[198:199], v[80:81], v[84:85] op_sel_hi:[0,1,1]
	v_cvt_pk_f32_fp8_e32 v[84:85], v82
	v_cvt_pk_f32_fp8_sdwa v[102:103], v82 src0_sel:WORD_1
	v_cvt_pk_f32_fp8_e32 v[104:105], v83
	v_cvt_pk_f32_fp8_sdwa v[82:83], v83 src0_sel:WORD_1
	v_pk_fma_f32 v[84:85], v[198:199], v[84:85], v[88:89] op_sel_hi:[0,1,1]
	v_pk_fma_f32 v[88:89], v[198:199], v[102:103], v[92:93] op_sel_hi:[0,1,1]
	v_pk_fma_f32 v[92:93], v[198:199], v[104:105], v[96:97] op_sel_hi:[0,1,1]
	v_pk_fma_f32 v[82:83], v[198:199], v[82:83], v[86:87] op_sel_hi:[0,1,1]
	s_waitcnt vmcnt(3)
	v_cvt_pk_f32_fp8_e32 v[90:91], v76
	v_cvt_pk_f32_fp8_sdwa v[96:97], v76 src0_sel:WORD_1
	v_cvt_pk_f32_fp8_e32 v[102:103], v77
	v_cvt_pk_f32_fp8_sdwa v[76:77], v77 src0_sel:WORD_1
	v_pk_fma_f32 v[90:91], v[198:199], v[90:91], v[94:95] op_sel:[1,0,0] op_sel_hi:[1,1,1]
	v_pk_fma_f32 v[94:95], v[198:199], v[96:97], v[98:99] op_sel:[1,0,0] op_sel_hi:[1,1,1]
	v_pk_fma_f32 v[96:97], v[198:199], v[102:103], v[100:101] op_sel:[1,0,0] op_sel_hi:[1,1,1]
	v_pk_fma_f32 v[76:77], v[198:199], v[76:77], v[80:81] op_sel:[1,0,0] op_sel_hi:[1,1,1]
	v_cvt_pk_f32_fp8_e32 v[80:81], v78
	v_cvt_pk_f32_fp8_sdwa v[98:99], v78 src0_sel:WORD_1
	v_cvt_pk_f32_fp8_e32 v[100:101], v79
	v_cvt_pk_f32_fp8_sdwa v[78:79], v79 src0_sel:WORD_1
	v_pk_fma_f32 v[80:81], v[198:199], v[80:81], v[84:85] op_sel:[1,0,0] op_sel_hi:[1,1,1]
	v_pk_fma_f32 v[84:85], v[198:199], v[98:99], v[88:89] op_sel:[1,0,0] op_sel_hi:[1,1,1]
	v_pk_fma_f32 v[88:89], v[198:199], v[100:101], v[92:93] op_sel:[1,0,0] op_sel_hi:[1,1,1]
	v_pk_fma_f32 v[78:79], v[198:199], v[78:79], v[82:83] op_sel:[1,0,0] op_sel_hi:[1,1,1]
	s_waitcnt vmcnt(2)
	v_cvt_pk_f32_fp8_e32 v[86:87], v72
	v_cvt_pk_f32_fp8_sdwa v[92:93], v72 src0_sel:WORD_1
	v_cvt_pk_f32_fp8_e32 v[98:99], v73
	v_cvt_pk_f32_fp8_sdwa v[72:73], v73 src0_sel:WORD_1
	v_pk_fma_f32 v[86:87], v[196:197], v[86:87], v[90:91] op_sel_hi:[0,1,1]
	v_pk_fma_f32 v[90:91], v[196:197], v[92:93], v[94:95] op_sel_hi:[0,1,1]
	v_pk_fma_f32 v[92:93], v[196:197], v[98:99], v[96:97] op_sel_hi:[0,1,1]
	v_pk_fma_f32 v[72:73], v[196:197], v[72:73], v[76:77] op_sel_hi:[0,1,1]
	v_cvt_pk_f32_fp8_e32 v[76:77], v74
	v_cvt_pk_f32_fp8_sdwa v[94:95], v74 src0_sel:WORD_1
	v_cvt_pk_f32_fp8_e32 v[96:97], v75
	v_cvt_pk_f32_fp8_sdwa v[74:75], v75 src0_sel:WORD_1
	v_pk_fma_f32 v[76:77], v[196:197], v[76:77], v[80:81] op_sel_hi:[0,1,1]
	v_pk_fma_f32 v[80:81], v[196:197], v[94:95], v[84:85] op_sel_hi:[0,1,1]
	v_pk_fma_f32 v[84:85], v[196:197], v[96:97], v[88:89] op_sel_hi:[0,1,1]
	v_pk_fma_f32 v[74:75], v[196:197], v[74:75], v[78:79] op_sel_hi:[0,1,1]
	s_waitcnt vmcnt(1)
	v_cvt_pk_f32_fp8_e32 v[82:83], v68
	v_cvt_pk_f32_fp8_sdwa v[88:89], v68 src0_sel:WORD_1
	v_cvt_pk_f32_fp8_e32 v[94:95], v69
	v_cvt_pk_f32_fp8_sdwa v[68:69], v69 src0_sel:WORD_1
	v_pk_fma_f32 v[82:83], v[196:197], v[82:83], v[86:87] op_sel:[1,0,0] op_sel_hi:[1,1,1]
	v_pk_fma_f32 v[86:87], v[196:197], v[88:89], v[90:91] op_sel:[1,0,0] op_sel_hi:[1,1,1]
	v_pk_fma_f32 v[68:69], v[196:197], v[68:69], v[72:73] op_sel:[1,0,0] op_sel_hi:[1,1,1]
	v_cvt_pk_f32_fp8_e32 v[72:73], v70
	v_pk_fma_f32 v[88:89], v[196:197], v[94:95], v[92:93] op_sel:[1,0,0] op_sel_hi:[1,1,1]
	v_cvt_pk_f32_fp8_sdwa v[90:91], v70 src0_sel:WORD_1
	v_cvt_pk_f32_fp8_e32 v[92:93], v71
	v_cvt_pk_f32_fp8_sdwa v[70:71], v71 src0_sel:WORD_1
	v_pk_fma_f32 v[72:73], v[196:197], v[72:73], v[76:77] op_sel:[1,0,0] op_sel_hi:[1,1,1]
	v_pk_fma_f32 v[76:77], v[196:197], v[90:91], v[80:81] op_sel:[1,0,0] op_sel_hi:[1,1,1]
	v_pk_fma_f32 v[80:81], v[196:197], v[92:93], v[84:85] op_sel:[1,0,0] op_sel_hi:[1,1,1]
	v_pk_fma_f32 v[70:71], v[196:197], v[70:71], v[74:75] op_sel:[1,0,0] op_sel_hi:[1,1,1]
	s_nop 1
	v_permlane32_swap_b32_e32 v82, v72
	v_permlane32_swap_b32_e32 v83, v73
	v_permlane32_swap_b32_e32 v86, v76
	v_permlane32_swap_b32_e32 v87, v77
	v_permlane32_swap_b32_e32 v88, v80
	v_permlane32_swap_b32_e32 v89, v81
	v_permlane32_swap_b32_e32 v68, v70
	v_permlane32_swap_b32_e32 v69, v71
	v_pk_add_f32 v[72:73], v[82:83], v[72:73]
	v_pk_add_f32 v[74:75], v[86:87], v[76:77]
	v_pk_add_f32 v[76:77], v[88:89], v[80:81]
	v_pk_add_f32 v[68:69], v[68:69], v[70:71]
	s_nop 1
	v_permlane16_swap_b32_e32 v72, v76
	v_permlane16_swap_b32_e32 v73, v77
	v_permlane16_swap_b32_e32 v74, v68
	v_permlane16_swap_b32_e32 v75, v69
	v_pk_add_f32 v[70:71], v[72:73], v[76:77]
	v_pk_add_f32 v[68:69], v[74:75], v[68:69]
	s_nop 0
	v_cndmask_b32_e64 v73, v71, v69, s[10:11]
	v_cndmask_b32_e64 v72, v70, v68, s[10:11]
	ds_bpermute_b32 v72, v143, v72
	ds_bpermute_b32 v73, v143, v73
	v_cndmask_b32_e64 v69, v69, v71, s[10:11]
	v_cndmask_b32_e64 v68, v68, v70, s[10:11]
	v_add_co_u32_e32 v70, vcc, 0x1000, v188
	s_waitcnt lgkmcnt(0)
	v_pk_add_f32 v[68:69], v[68:69], v[72:73]
	v_addc_co_u32_e32 v71, vcc, 0, v189, vcc
	global_store_dwordx2 v[70:71], v[68:69], off
	v_add_u32_e32 v145, 0x400, v145
	v_lshl_add_u64 v[188:189], v[188:189], 0, s[18:19]
	s_and_b64 vcc, exec, s[28:29]
	s_cbranch_vccnz .LBB0_1637
